# within each 16-MFMA block the two MFMAs (k=0,k=1) of one accumulator are issued back to back (accumulator forwarding, less VGPR traffic); same instructions, bit-identical
# speedup vs baseline: 1.0101x; 1.0101x over previous
.LBB0_285:
	s_add_u32 s8, s26, 0x100
	s_addc_u32 s9, s27, 0
	s_add_u32 s18, s20, 0x100
	s_addc_u32 s19, s21, 0
	s_and_b64 s[16:17], s[64:65], exec
	s_cselect_b32 s31, s51, s19
	s_cselect_b32 s30, s50, s18
	s_add_i32 s46, 0, 0x10000
	s_and_b64 s[16:17], s[64:65], exec
	s_cselect_b32 s19, s15, s9
	s_cselect_b32 s18, s14, s8
	s_add_i32 s8, 0, 0x14000
	v_add_u32_e32 v2, s46, v198
	v_add_u32_e32 v132, s8, v198
	ds_read_b128 v[4:7], v2
	ds_read_b128 v[8:11], v2 offset:1024
	ds_read_b128 v[12:15], v2 offset:2048
	ds_read_b128 v[16:19], v2 offset:3072
	ds_read_b128 v[20:23], v132
	ds_read_b128 v[24:27], v132 offset:1024
	ds_read_b128 v[28:31], v132 offset:2048
	ds_read_b128 v[32:35], v132 offset:3072
	s_add_u32 s16, s26, 0x80
	s_addc_u32 s17, s27, 0
	s_add_i32 s42, s85, 0x8000
	s_add_i32 s43, s85, 0xa000
	s_mov_b64 s[28:29], s[16:17]
	s_mov_b32 m0, s42
	s_add_u32 s16, s16, s54
	ds_read_b128 v[36:39], v199 offset:8192
	ds_read_b128 v[40:43], v199 offset:9216
	ds_read_b128 v[44:47], v199 offset:10240
	ds_read_b128 v[48:51], v199 offset:11264
	ds_read_b128 v[52:55], v199 offset:12288
	ds_read_b128 v[56:59], v199 offset:13312
	ds_read_b128 v[60:63], v199 offset:14336
	ds_read_b128 v[64:67], v199 offset:15360
	s_addc_u32 s17, s17, s55
	global_load_lds_dwordx4 v194, s[28:29]
	s_mov_b32 m0, s43
	s_add_i32 s44, s85, 0xc000
	global_load_lds_dwordx4 v195, s[28:29]
	s_mov_b32 m0, s44
	s_add_i32 s45, s85, 0xe000
	s_add_u32 s28, s30, 0x80
	global_load_lds_dwordx4 v194, s[16:17]
	s_mov_b32 m0, s45
	s_addc_u32 s29, s31, 0
	global_load_lds_dwordx4 v195, s[16:17]
	s_waitcnt vmcnt(8)
	s_waitcnt lgkmcnt(0)
	s_barrier
	s_setprio 1
	s_waitcnt lgkmcnt(0)
	v_mfma_f32_16x16x32_bf16 v[68:71], v[4:7], v[36:39], 0
	v_mfma_f32_16x16x32_bf16 v[72:75], v[12:15], v[36:39], 0
	v_mfma_f32_16x16x32_bf16 v[76:79], v[4:7], v[44:47], 0
	v_mfma_f32_16x16x32_bf16 v[80:83], v[12:15], v[44:47], 0
	v_mfma_f32_16x16x32_bf16 v[84:87], v[4:7], v[52:55], 0
	v_mfma_f32_16x16x32_bf16 v[88:91], v[12:15], v[52:55], 0
	v_mfma_f32_16x16x32_bf16 v[92:95], v[4:7], v[60:63], 0
	v_mfma_f32_16x16x32_bf16 v[96:99], v[12:15], v[60:63], 0
	v_mfma_f32_16x16x32_bf16 v[68:71], v[8:11], v[40:43], v[68:71]
	v_mfma_f32_16x16x32_bf16 v[72:75], v[16:19], v[40:43], v[72:75]
	v_mfma_f32_16x16x32_bf16 v[76:79], v[8:11], v[48:51], v[76:79]
	v_mfma_f32_16x16x32_bf16 v[80:83], v[16:19], v[48:51], v[80:83]
	v_mfma_f32_16x16x32_bf16 v[84:87], v[8:11], v[56:59], v[84:87]
	v_mfma_f32_16x16x32_bf16 v[88:91], v[16:19], v[56:59], v[88:91]
	v_mfma_f32_16x16x32_bf16 v[92:95], v[8:11], v[64:67], v[92:95]
	v_mfma_f32_16x16x32_bf16 v[96:99], v[16:19], v[64:67], v[96:99]
	s_setprio 0
	s_setprio 1
	v_mfma_f32_16x16x32_bf16 v[100:103], v[20:23], v[36:39], 0
	v_mfma_f32_16x16x32_bf16 v[36:39], v[28:31], v[36:39], 0
	v_mfma_f32_16x16x32_bf16 v[100:103], v[24:27], v[40:43], v[100:103]
	v_mfma_f32_16x16x32_bf16 v[40:43], v[32:35], v[40:43], v[36:39]
	v_mfma_f32_16x16x32_bf16 v[36:39], v[20:23], v[44:47], 0
	v_mfma_f32_16x16x32_bf16 v[104:107], v[24:27], v[48:51], v[36:39]
	v_mfma_f32_16x16x32_bf16 v[36:39], v[28:31], v[44:47], 0
	v_mfma_f32_16x16x32_bf16 v[48:51], v[32:35], v[48:51], v[36:39]
	v_mfma_f32_16x16x32_bf16 v[36:39], v[20:23], v[52:55], 0
	v_mfma_f32_16x16x32_bf16 v[108:111], v[24:27], v[56:59], v[36:39]
	v_mfma_f32_16x16x32_bf16 v[36:39], v[28:31], v[52:55], 0
	v_mfma_f32_16x16x32_bf16 v[56:59], v[32:35], v[56:59], v[36:39]
	v_mfma_f32_16x16x32_bf16 v[36:39], v[20:23], v[60:63], 0
	v_mfma_f32_16x16x32_bf16 v[112:115], v[24:27], v[64:67], v[36:39]
	v_mfma_f32_16x16x32_bf16 v[36:39], v[28:31], v[60:63], 0
	v_mfma_f32_16x16x32_bf16 v[64:67], v[32:35], v[64:67], v[36:39]
	s_setprio 0
	s_barrier
	s_add_i32 s46, s46, s83
	s_mov_b64 s[16:17], s[30:31]
	s_mov_b32 m0, s46
	s_add_i32 s47, s46, 0x2000
	s_nop 0
	ds_read_b128 v[36:39], v199 offset:24576
	ds_read_b128 v[44:47], v199 offset:25600
	ds_read_b128 v[52:55], v199 offset:26624
	ds_read_b128 v[60:63], v199 offset:27648
	ds_read_b128 v[116:119], v199 offset:28672
	ds_read_b128 v[120:123], v199 offset:29696
	ds_read_b128 v[124:127], v199 offset:30720
	ds_read_b128 v[128:131], v199 offset:31744
	s_nop 0
	global_load_lds_dwordx4 v201, s[16:17]
	s_mov_b32 m0, s47
	s_nop 0
	global_load_lds_dwordx4 v200, s[16:17]
	s_add_u32 s16, s30, s54
	s_addc_u32 s17, s31, s55
	s_add_i32 s30, s8, s83
	s_mov_b32 m0, s30
	s_add_i32 s31, s30, 0x2000
	s_nop 0
	global_load_lds_dwordx4 v201, s[16:17]
	s_mov_b32 m0, s31
	s_nop 0
	global_load_lds_dwordx4 v200, s[16:17]
	s_waitcnt vmcnt(6)
	s_waitcnt lgkmcnt(0)
	s_barrier
	s_setprio 1
	s_waitcnt lgkmcnt(0)
	v_mfma_f32_16x16x32_bf16 v[134:137], v[4:7], v[36:39], 0
	v_mfma_f32_16x16x32_bf16 v[144:147], v[4:7], v[52:55], 0
	v_mfma_f32_16x16x32_bf16 v[152:155], v[4:7], v[116:119], 0
	v_mfma_f32_16x16x32_bf16 v[4:7], v[4:7], v[124:127], 0
	v_mfma_f32_16x16x32_bf16 v[140:143], v[12:15], v[36:39], 0
	v_mfma_f32_16x16x32_bf16 v[148:151], v[12:15], v[52:55], 0
	v_mfma_f32_16x16x32_bf16 v[156:159], v[12:15], v[116:119], 0
	v_mfma_f32_16x16x32_bf16 v[160:163], v[8:11], v[128:131], v[4:7]
	v_mfma_f32_16x16x32_bf16 v[4:7], v[12:15], v[124:127], 0
	v_mfma_f32_16x16x32_bf16 v[136:139], v[8:11], v[44:47], v[134:137]
	v_mfma_f32_16x16x32_bf16 v[140:143], v[16:19], v[44:47], v[140:143]
	v_mfma_f32_16x16x32_bf16 v[144:147], v[8:11], v[60:63], v[144:147]
	v_mfma_f32_16x16x32_bf16 v[148:151], v[16:19], v[60:63], v[148:151]
	v_mfma_f32_16x16x32_bf16 v[152:155], v[8:11], v[120:123], v[152:155]
	v_mfma_f32_16x16x32_bf16 v[156:159], v[16:19], v[120:123], v[156:159]
	v_mfma_f32_16x16x32_bf16 v[164:167], v[16:19], v[128:131], v[4:7]
	s_setprio 0
	s_setprio 1
	v_mfma_f32_16x16x32_bf16 v[4:7], v[20:23], v[36:39], 0
	v_mfma_f32_16x16x32_bf16 v[168:171], v[24:27], v[44:47], v[4:7]
	v_mfma_f32_16x16x32_bf16 v[4:7], v[28:31], v[36:39], 0
	v_mfma_f32_16x16x32_bf16 v[172:175], v[32:35], v[44:47], v[4:7]
	v_mfma_f32_16x16x32_bf16 v[4:7], v[20:23], v[52:55], 0
	v_mfma_f32_16x16x32_bf16 v[176:179], v[24:27], v[60:63], v[4:7]
	v_mfma_f32_16x16x32_bf16 v[4:7], v[28:31], v[52:55], 0
	v_mfma_f32_16x16x32_bf16 v[180:183], v[32:35], v[60:63], v[4:7]
	v_mfma_f32_16x16x32_bf16 v[4:7], v[20:23], v[116:119], 0
	v_mfma_f32_16x16x32_bf16 v[184:187], v[24:27], v[120:123], v[4:7]
	v_mfma_f32_16x16x32_bf16 v[4:7], v[28:31], v[116:119], 0
	v_mfma_f32_16x16x32_bf16 v[120:123], v[32:35], v[120:123], v[4:7]
	v_mfma_f32_16x16x32_bf16 v[4:7], v[20:23], v[124:127], 0
	v_mfma_f32_16x16x32_bf16 v[188:191], v[24:27], v[128:131], v[4:7]
	v_mfma_f32_16x16x32_bf16 v[4:7], v[28:31], v[124:127], 0
	v_mfma_f32_16x16x32_bf16 v[128:131], v[32:35], v[128:131], v[4:7]
	s_setprio 0
	s_barrier
	s_add_i32 s48, 0, 0x18000
	s_add_i32 s8, 0, 0x1c000
	v_add_u32_e32 v133, s48, v198
	v_add_u32_e32 v134, s8, v198
	ds_read_b128 v[116:119], v133
	ds_read_b128 v[124:127], v133 offset:1024
	ds_read_b128 v[202:205], v133 offset:2048
	ds_read_b128 v[206:209], v133 offset:3072
	ds_read_b128 v[216:219], v134
	ds_read_b128 v[220:223], v134 offset:1024
	ds_read_b128 v[224:227], v134 offset:2048
	ds_read_b128 v[228:231], v134 offset:3072
	s_mov_b32 m0, s85
	s_mov_b64 s[16:17], s[18:19]
	ds_read_b128 v[44:47], v199 offset:40960
	ds_read_b128 v[52:55], v199 offset:41984
	ds_read_b128 v[60:63], v199 offset:43008
	ds_read_b128 v[232:235], v199 offset:44032
	ds_read_b128 v[236:239], v199 offset:45056
	ds_read_b128 v[242:245], v199 offset:46080
	ds_read_b128 v[246:249], v199 offset:47104
	ds_read_b128 v[250:253], v199 offset:48128
	s_nop 0
	global_load_lds_dwordx4 v194, s[16:17]
	s_mov_b32 m0, s86
	s_nop 0
	global_load_lds_dwordx4 v195, s[16:17]
	s_add_u32 s16, s18, s54
	s_addc_u32 s17, s19, s55
	s_mov_b32 m0, s87
	s_nop 0
	global_load_lds_dwordx4 v194, s[16:17]
	s_mov_b32 m0, s88
	s_nop 0
	global_load_lds_dwordx4 v195, s[16:17]
	s_waitcnt vmcnt(8)
	s_waitcnt lgkmcnt(0)
	s_barrier
	s_setprio 1
	s_waitcnt lgkmcnt(0)
	v_mfma_f32_16x16x32_bf16 v[4:7], v[116:119], v[44:47], v[68:71]
	v_mfma_f32_16x16x32_bf16 v[4:7], v[124:127], v[52:55], v[4:7]
	v_mfma_f32_16x16x32_bf16 v[8:11], v[202:205], v[44:47], v[72:75]
	v_mfma_f32_16x16x32_bf16 v[8:11], v[206:209], v[52:55], v[8:11]
	v_mfma_f32_16x16x32_bf16 v[12:15], v[116:119], v[60:63], v[76:79]
	v_mfma_f32_16x16x32_bf16 v[12:15], v[124:127], v[232:235], v[12:15]
	v_mfma_f32_16x16x32_bf16 v[16:19], v[202:205], v[60:63], v[80:83]
	v_mfma_f32_16x16x32_bf16 v[16:19], v[206:209], v[232:235], v[16:19]
	v_mfma_f32_16x16x32_bf16 v[20:23], v[116:119], v[236:239], v[84:87]
	v_mfma_f32_16x16x32_bf16 v[20:23], v[124:127], v[242:245], v[20:23]
	v_mfma_f32_16x16x32_bf16 v[24:27], v[202:205], v[236:239], v[88:91]
	v_mfma_f32_16x16x32_bf16 v[24:27], v[206:209], v[242:245], v[24:27]
	v_mfma_f32_16x16x32_bf16 v[28:31], v[116:119], v[246:249], v[92:95]
	v_mfma_f32_16x16x32_bf16 v[28:31], v[124:127], v[250:253], v[28:31]
	v_mfma_f32_16x16x32_bf16 v[32:35], v[202:205], v[246:249], v[96:99]
	v_mfma_f32_16x16x32_bf16 v[32:35], v[206:209], v[250:253], v[32:35]
	s_setprio 0
	s_setprio 1
	v_mfma_f32_16x16x32_bf16 v[36:39], v[216:219], v[44:47], v[100:103]
	v_mfma_f32_16x16x32_bf16 v[40:43], v[224:227], v[44:47], v[40:43]
	v_mfma_f32_16x16x32_bf16 v[36:39], v[220:223], v[52:55], v[36:39]
	v_mfma_f32_16x16x32_bf16 v[40:43], v[228:231], v[52:55], v[40:43]
	v_mfma_f32_16x16x32_bf16 v[44:47], v[216:219], v[60:63], v[104:107]
	v_mfma_f32_16x16x32_bf16 v[48:51], v[224:227], v[60:63], v[48:51]
	v_mfma_f32_16x16x32_bf16 v[52:55], v[216:219], v[236:239], v[108:111]
	v_mfma_f32_16x16x32_bf16 v[56:59], v[224:227], v[236:239], v[56:59]
	v_mfma_f32_16x16x32_bf16 v[60:63], v[216:219], v[246:249], v[112:115]
	v_mfma_f32_16x16x32_bf16 v[64:67], v[224:227], v[246:249], v[64:67]
	v_mfma_f32_16x16x32_bf16 v[44:47], v[220:223], v[232:235], v[44:47]
	v_mfma_f32_16x16x32_bf16 v[48:51], v[228:231], v[232:235], v[48:51]
	v_mfma_f32_16x16x32_bf16 v[52:55], v[220:223], v[242:245], v[52:55]
	v_mfma_f32_16x16x32_bf16 v[56:59], v[228:231], v[242:245], v[56:59]
	v_mfma_f32_16x16x32_bf16 v[60:63], v[220:223], v[250:253], v[60:63]
	v_mfma_f32_16x16x32_bf16 v[64:67], v[228:231], v[250:253], v[64:67]
	s_setprio 0
	s_barrier
	s_add_i32 s48, s48, s83
	s_mov_b64 s[16:17], s[28:29]
	s_mov_b32 m0, s48
	s_add_i32 s49, s48, 0x2000
	ds_read_b128 v[104:107], v199 offset:57344
	ds_read_b128 v[108:111], v199 offset:58368
	ds_read_b128 v[112:115], v199 offset:59392
	ds_read_b128 v[232:235], v199 offset:60416
	ds_read_b128 v[236:239], v199 offset:61440
	ds_read_b128 v[242:245], v199 offset:62464
	ds_read_b128 v[246:249], v199 offset:63488
	ds_read_b128 v[250:253], v199 offset:64512
	s_nop 0
	global_load_lds_dwordx4 v201, s[16:17]
	s_mov_b32 m0, s49
	s_nop 0
	global_load_lds_dwordx4 v200, s[16:17]
	s_add_u32 s16, s28, s54
	s_addc_u32 s17, s29, s55
	s_add_i32 s28, s8, s83
	s_mov_b32 m0, s28
	s_add_i32 s29, s28, 0x2000
	s_nop 0
	global_load_lds_dwordx4 v201, s[16:17]
	s_mov_b32 m0, s29
	s_nop 0
	global_load_lds_dwordx4 v200, s[16:17]
	s_waitcnt vmcnt(6)
	s_waitcnt lgkmcnt(0)
	s_barrier
	s_setprio 1
	s_waitcnt lgkmcnt(0)
	v_mfma_f32_16x16x32_bf16 v[68:71], v[116:119], v[104:107], v[136:139]
	v_mfma_f32_16x16x32_bf16 v[68:71], v[124:127], v[108:111], v[68:71]
	v_mfma_f32_16x16x32_bf16 v[72:75], v[202:205], v[104:107], v[140:143]
	v_mfma_f32_16x16x32_bf16 v[72:75], v[206:209], v[108:111], v[72:75]
	v_mfma_f32_16x16x32_bf16 v[76:79], v[116:119], v[112:115], v[144:147]
	v_mfma_f32_16x16x32_bf16 v[76:79], v[124:127], v[232:235], v[76:79]
	v_mfma_f32_16x16x32_bf16 v[80:83], v[202:205], v[112:115], v[148:151]
	v_mfma_f32_16x16x32_bf16 v[80:83], v[206:209], v[232:235], v[80:83]
	v_mfma_f32_16x16x32_bf16 v[84:87], v[116:119], v[236:239], v[152:155]
	v_mfma_f32_16x16x32_bf16 v[84:87], v[124:127], v[242:245], v[84:87]
	v_mfma_f32_16x16x32_bf16 v[88:91], v[202:205], v[236:239], v[156:159]
	v_mfma_f32_16x16x32_bf16 v[88:91], v[206:209], v[242:245], v[88:91]
	v_mfma_f32_16x16x32_bf16 v[92:95], v[116:119], v[246:249], v[160:163]
	v_mfma_f32_16x16x32_bf16 v[92:95], v[124:127], v[250:253], v[92:95]
	v_mfma_f32_16x16x32_bf16 v[96:99], v[202:205], v[246:249], v[164:167]
	v_mfma_f32_16x16x32_bf16 v[96:99], v[206:209], v[250:253], v[96:99]
	s_setprio 0
	s_setprio 1
	v_mfma_f32_16x16x32_bf16 v[100:103], v[216:219], v[104:107], v[168:171]
	v_mfma_f32_16x16x32_bf16 v[104:107], v[224:227], v[104:107], v[172:175]
	v_mfma_f32_16x16x32_bf16 v[100:103], v[220:223], v[108:111], v[100:103]
	v_mfma_f32_16x16x32_bf16 v[104:107], v[228:231], v[108:111], v[104:107]
	v_mfma_f32_16x16x32_bf16 v[108:111], v[216:219], v[112:115], v[176:179]
	v_mfma_f32_16x16x32_bf16 v[112:115], v[224:227], v[112:115], v[180:183]
	v_mfma_f32_16x16x32_bf16 v[116:119], v[216:219], v[236:239], v[184:187]
	v_mfma_f32_16x16x32_bf16 v[120:123], v[224:227], v[236:239], v[120:123]
	v_mfma_f32_16x16x32_bf16 v[124:127], v[216:219], v[246:249], v[188:191]
	v_mfma_f32_16x16x32_bf16 v[128:131], v[224:227], v[246:249], v[128:131]
	v_mfma_f32_16x16x32_bf16 v[108:111], v[220:223], v[232:235], v[108:111]
	v_mfma_f32_16x16x32_bf16 v[112:115], v[228:231], v[232:235], v[112:115]
	v_mfma_f32_16x16x32_bf16 v[116:119], v[220:223], v[242:245], v[116:119]
	v_mfma_f32_16x16x32_bf16 v[120:123], v[228:231], v[242:245], v[120:123]
	v_mfma_f32_16x16x32_bf16 v[124:127], v[220:223], v[250:253], v[124:127]
	v_mfma_f32_16x16x32_bf16 v[128:131], v[228:231], v[250:253], v[128:131]
	s_setprio 0
	s_barrier
	s_andn2_b64 vcc, exec, s[66:67]
	s_cbranch_vccnz .LBB0_288
	s_add_u32 s52, s20, 0x200
	s_addc_u32 s53, s21, 0
	s_add_u32 s26, s26, 0x200
	s_addc_u32 s27, s27, 0
	s_mov_b32 s72, 4
.LBB0_287:
	ds_read_b128 v[136:139], v2
	ds_read_b128 v[140:143], v2 offset:1024
	ds_read_b128 v[144:147], v2 offset:2048
	ds_read_b128 v[148:151], v2 offset:3072
	ds_read_b128 v[152:155], v132
	ds_read_b128 v[156:159], v132 offset:1024
	ds_read_b128 v[160:163], v132 offset:2048
	ds_read_b128 v[164:167], v132 offset:3072
	s_cmp_eq_u32 s82, s72
	s_cselect_b32 s17, s51, s53
	s_cselect_b32 s16, s50, s52
	s_cselect_b32 s21, s15, s27
	s_cselect_b32 s20, s14, s26
	s_add_u32 s8, s26, 0xffffff80
	s_addc_u32 s9, s27, -1
	s_mov_b32 m0, s42
	s_mov_b64 s[18:19], s[8:9]
	ds_read_b128 v[168:171], v199 offset:8192
	ds_read_b128 v[172:175], v199 offset:9216
	ds_read_b128 v[176:179], v199 offset:10240
	ds_read_b128 v[180:183], v199 offset:11264
	ds_read_b128 v[184:187], v199 offset:12288
	ds_read_b128 v[188:191], v199 offset:13312
	ds_read_b128 v[202:205], v199 offset:14336
	ds_read_b128 v[206:209], v199 offset:15360
	s_add_u32 s8, s8, s54
	global_load_lds_dwordx4 v194, s[18:19]
	s_mov_b32 m0, s43
	s_addc_u32 s9, s9, s55
	global_load_lds_dwordx4 v195, s[18:19]
	s_mov_b32 m0, s44
	s_add_u32 s18, s16, 0x80
	global_load_lds_dwordx4 v194, s[8:9]
	s_mov_b32 m0, s45
	s_addc_u32 s19, s17, 0
	global_load_lds_dwordx4 v195, s[8:9]
	s_waitcnt vmcnt(8)
	s_waitcnt lgkmcnt(0)
	s_barrier
	s_setprio 1
	s_waitcnt lgkmcnt(0)
	v_mfma_f32_16x16x32_bf16 v[4:7], v[136:139], v[168:171], v[4:7]
	v_mfma_f32_16x16x32_bf16 v[4:7], v[140:143], v[172:175], v[4:7]
	v_mfma_f32_16x16x32_bf16 v[8:11], v[144:147], v[168:171], v[8:11]
	v_mfma_f32_16x16x32_bf16 v[8:11], v[148:151], v[172:175], v[8:11]
	v_mfma_f32_16x16x32_bf16 v[12:15], v[136:139], v[176:179], v[12:15]
	v_mfma_f32_16x16x32_bf16 v[12:15], v[140:143], v[180:183], v[12:15]
	v_mfma_f32_16x16x32_bf16 v[16:19], v[144:147], v[176:179], v[16:19]
	v_mfma_f32_16x16x32_bf16 v[16:19], v[148:151], v[180:183], v[16:19]
	v_mfma_f32_16x16x32_bf16 v[20:23], v[136:139], v[184:187], v[20:23]
	v_mfma_f32_16x16x32_bf16 v[20:23], v[140:143], v[188:191], v[20:23]
	v_mfma_f32_16x16x32_bf16 v[24:27], v[144:147], v[184:187], v[24:27]
	v_mfma_f32_16x16x32_bf16 v[24:27], v[148:151], v[188:191], v[24:27]
	v_mfma_f32_16x16x32_bf16 v[28:31], v[136:139], v[202:205], v[28:31]
	v_mfma_f32_16x16x32_bf16 v[28:31], v[140:143], v[206:209], v[28:31]
	v_mfma_f32_16x16x32_bf16 v[32:35], v[144:147], v[202:205], v[32:35]
	v_mfma_f32_16x16x32_bf16 v[32:35], v[148:151], v[206:209], v[32:35]
	s_setprio 0
	s_setprio 1
	v_mfma_f32_16x16x32_bf16 v[36:39], v[152:155], v[168:171], v[36:39]
	v_mfma_f32_16x16x32_bf16 v[36:39], v[156:159], v[172:175], v[36:39]
	v_mfma_f32_16x16x32_bf16 v[40:43], v[160:163], v[168:171], v[40:43]
	v_mfma_f32_16x16x32_bf16 v[40:43], v[164:167], v[172:175], v[40:43]
	v_mfma_f32_16x16x32_bf16 v[44:47], v[152:155], v[176:179], v[44:47]
	v_mfma_f32_16x16x32_bf16 v[44:47], v[156:159], v[180:183], v[44:47]
	v_mfma_f32_16x16x32_bf16 v[48:51], v[160:163], v[176:179], v[48:51]
	v_mfma_f32_16x16x32_bf16 v[48:51], v[164:167], v[180:183], v[48:51]
	v_mfma_f32_16x16x32_bf16 v[52:55], v[152:155], v[184:187], v[52:55]
	v_mfma_f32_16x16x32_bf16 v[52:55], v[156:159], v[188:191], v[52:55]
	v_mfma_f32_16x16x32_bf16 v[56:59], v[160:163], v[184:187], v[56:59]
	v_mfma_f32_16x16x32_bf16 v[56:59], v[164:167], v[188:191], v[56:59]
	v_mfma_f32_16x16x32_bf16 v[60:63], v[152:155], v[202:205], v[60:63]
	v_mfma_f32_16x16x32_bf16 v[60:63], v[156:159], v[206:209], v[60:63]
	v_mfma_f32_16x16x32_bf16 v[64:67], v[160:163], v[202:205], v[64:67]
	v_mfma_f32_16x16x32_bf16 v[64:67], v[164:167], v[206:209], v[64:67]
	s_setprio 0
	s_barrier
	s_mov_b32 m0, s46
	s_mov_b64 s[8:9], s[16:17]
	ds_read_b128 v[168:171], v199 offset:24576
	ds_read_b128 v[172:175], v199 offset:25600
	ds_read_b128 v[176:179], v199 offset:26624
	ds_read_b128 v[180:183], v199 offset:27648
	ds_read_b128 v[184:187], v199 offset:28672
	ds_read_b128 v[188:191], v199 offset:29696
	ds_read_b128 v[202:205], v199 offset:30720
	ds_read_b128 v[206:209], v199 offset:31744
	s_nop 0
	global_load_lds_dwordx4 v201, s[8:9]
	s_mov_b32 m0, s47
	s_nop 0
	global_load_lds_dwordx4 v200, s[8:9]
	s_add_u32 s8, s16, s54
	s_addc_u32 s9, s17, s55
	s_mov_b32 m0, s30
	s_nop 0
	global_load_lds_dwordx4 v201, s[8:9]
	s_mov_b32 m0, s31
	s_nop 0
	global_load_lds_dwordx4 v200, s[8:9]
	s_waitcnt vmcnt(6)
	s_waitcnt lgkmcnt(0)
	s_barrier
	s_setprio 1
	s_waitcnt lgkmcnt(0)
	v_mfma_f32_16x16x32_bf16 v[68:71], v[136:139], v[168:171], v[68:71]
	v_mfma_f32_16x16x32_bf16 v[68:71], v[140:143], v[172:175], v[68:71]
	v_mfma_f32_16x16x32_bf16 v[72:75], v[144:147], v[168:171], v[72:75]
	v_mfma_f32_16x16x32_bf16 v[72:75], v[148:151], v[172:175], v[72:75]
	v_mfma_f32_16x16x32_bf16 v[76:79], v[136:139], v[176:179], v[76:79]
	v_mfma_f32_16x16x32_bf16 v[76:79], v[140:143], v[180:183], v[76:79]
	v_mfma_f32_16x16x32_bf16 v[80:83], v[144:147], v[176:179], v[80:83]
	v_mfma_f32_16x16x32_bf16 v[80:83], v[148:151], v[180:183], v[80:83]
	v_mfma_f32_16x16x32_bf16 v[84:87], v[136:139], v[184:187], v[84:87]
	v_mfma_f32_16x16x32_bf16 v[84:87], v[140:143], v[188:191], v[84:87]
	v_mfma_f32_16x16x32_bf16 v[88:91], v[144:147], v[184:187], v[88:91]
	v_mfma_f32_16x16x32_bf16 v[88:91], v[148:151], v[188:191], v[88:91]
	v_mfma_f32_16x16x32_bf16 v[92:95], v[136:139], v[202:205], v[92:95]
	v_mfma_f32_16x16x32_bf16 v[92:95], v[140:143], v[206:209], v[92:95]
	v_mfma_f32_16x16x32_bf16 v[96:99], v[144:147], v[202:205], v[96:99]
	v_mfma_f32_16x16x32_bf16 v[96:99], v[148:151], v[206:209], v[96:99]
	s_setprio 0
	s_setprio 1
	v_mfma_f32_16x16x32_bf16 v[100:103], v[152:155], v[168:171], v[100:103]
	v_mfma_f32_16x16x32_bf16 v[100:103], v[156:159], v[172:175], v[100:103]
	v_mfma_f32_16x16x32_bf16 v[104:107], v[160:163], v[168:171], v[104:107]
	v_mfma_f32_16x16x32_bf16 v[104:107], v[164:167], v[172:175], v[104:107]
	v_mfma_f32_16x16x32_bf16 v[108:111], v[152:155], v[176:179], v[108:111]
	v_mfma_f32_16x16x32_bf16 v[108:111], v[156:159], v[180:183], v[108:111]
	v_mfma_f32_16x16x32_bf16 v[112:115], v[160:163], v[176:179], v[112:115]
	v_mfma_f32_16x16x32_bf16 v[112:115], v[164:167], v[180:183], v[112:115]
	v_mfma_f32_16x16x32_bf16 v[116:119], v[152:155], v[184:187], v[116:119]
	v_mfma_f32_16x16x32_bf16 v[116:119], v[156:159], v[188:191], v[116:119]
	v_mfma_f32_16x16x32_bf16 v[120:123], v[160:163], v[184:187], v[120:123]
	v_mfma_f32_16x16x32_bf16 v[120:123], v[164:167], v[188:191], v[120:123]
	v_mfma_f32_16x16x32_bf16 v[124:127], v[152:155], v[202:205], v[124:127]
	v_mfma_f32_16x16x32_bf16 v[124:127], v[156:159], v[206:209], v[124:127]
	v_mfma_f32_16x16x32_bf16 v[128:131], v[160:163], v[202:205], v[128:131]
	v_mfma_f32_16x16x32_bf16 v[128:131], v[164:167], v[206:209], v[128:131]
	s_setprio 0
	s_barrier
	ds_read_b128 v[136:139], v133
	ds_read_b128 v[140:143], v133 offset:1024
	ds_read_b128 v[144:147], v133 offset:2048
	ds_read_b128 v[148:151], v133 offset:3072
	ds_read_b128 v[152:155], v134
	ds_read_b128 v[156:159], v134 offset:1024
	ds_read_b128 v[160:163], v134 offset:2048
	ds_read_b128 v[164:167], v134 offset:3072
	s_mov_b32 m0, s85
	s_mov_b64 s[8:9], s[20:21]
	ds_read_b128 v[168:171], v199 offset:40960
	ds_read_b128 v[172:175], v199 offset:41984
	ds_read_b128 v[176:179], v199 offset:43008
	ds_read_b128 v[180:183], v199 offset:44032
	ds_read_b128 v[184:187], v199 offset:45056
	ds_read_b128 v[188:191], v199 offset:46080
	ds_read_b128 v[202:205], v199 offset:47104
	ds_read_b128 v[206:209], v199 offset:48128
	s_nop 0
	global_load_lds_dwordx4 v194, s[8:9]
	s_mov_b32 m0, s86
	s_nop 0
	global_load_lds_dwordx4 v195, s[8:9]
	s_add_u32 s8, s20, s54
	s_addc_u32 s9, s21, s55
	s_mov_b32 m0, s87
	s_nop 0
	global_load_lds_dwordx4 v194, s[8:9]
	s_mov_b32 m0, s88
	s_nop 0
	global_load_lds_dwordx4 v195, s[8:9]
	s_waitcnt vmcnt(8)
	s_waitcnt lgkmcnt(0)
	s_barrier
	s_setprio 1
	s_waitcnt lgkmcnt(0)
	v_mfma_f32_16x16x32_bf16 v[4:7], v[136:139], v[168:171], v[4:7]
	v_mfma_f32_16x16x32_bf16 v[4:7], v[140:143], v[172:175], v[4:7]
	v_mfma_f32_16x16x32_bf16 v[8:11], v[144:147], v[168:171], v[8:11]
	v_mfma_f32_16x16x32_bf16 v[8:11], v[148:151], v[172:175], v[8:11]
	v_mfma_f32_16x16x32_bf16 v[12:15], v[136:139], v[176:179], v[12:15]
	v_mfma_f32_16x16x32_bf16 v[12:15], v[140:143], v[180:183], v[12:15]
	v_mfma_f32_16x16x32_bf16 v[16:19], v[144:147], v[176:179], v[16:19]
	v_mfma_f32_16x16x32_bf16 v[16:19], v[148:151], v[180:183], v[16:19]
	v_mfma_f32_16x16x32_bf16 v[20:23], v[136:139], v[184:187], v[20:23]
	v_mfma_f32_16x16x32_bf16 v[20:23], v[140:143], v[188:191], v[20:23]
	v_mfma_f32_16x16x32_bf16 v[24:27], v[144:147], v[184:187], v[24:27]
	v_mfma_f32_16x16x32_bf16 v[24:27], v[148:151], v[188:191], v[24:27]
	v_mfma_f32_16x16x32_bf16 v[28:31], v[136:139], v[202:205], v[28:31]
	v_mfma_f32_16x16x32_bf16 v[28:31], v[140:143], v[206:209], v[28:31]
	v_mfma_f32_16x16x32_bf16 v[32:35], v[144:147], v[202:205], v[32:35]
	v_mfma_f32_16x16x32_bf16 v[32:35], v[148:151], v[206:209], v[32:35]
	s_setprio 0
	s_setprio 1
	v_mfma_f32_16x16x32_bf16 v[36:39], v[152:155], v[168:171], v[36:39]
	v_mfma_f32_16x16x32_bf16 v[36:39], v[156:159], v[172:175], v[36:39]
	v_mfma_f32_16x16x32_bf16 v[40:43], v[160:163], v[168:171], v[40:43]
	v_mfma_f32_16x16x32_bf16 v[40:43], v[164:167], v[172:175], v[40:43]
	v_mfma_f32_16x16x32_bf16 v[44:47], v[152:155], v[176:179], v[44:47]
	v_mfma_f32_16x16x32_bf16 v[44:47], v[156:159], v[180:183], v[44:47]
	v_mfma_f32_16x16x32_bf16 v[48:51], v[160:163], v[176:179], v[48:51]
	v_mfma_f32_16x16x32_bf16 v[48:51], v[164:167], v[180:183], v[48:51]
	v_mfma_f32_16x16x32_bf16 v[52:55], v[152:155], v[184:187], v[52:55]
	v_mfma_f32_16x16x32_bf16 v[52:55], v[156:159], v[188:191], v[52:55]
	v_mfma_f32_16x16x32_bf16 v[56:59], v[160:163], v[184:187], v[56:59]
	v_mfma_f32_16x16x32_bf16 v[56:59], v[164:167], v[188:191], v[56:59]
	v_mfma_f32_16x16x32_bf16 v[60:63], v[152:155], v[202:205], v[60:63]
	v_mfma_f32_16x16x32_bf16 v[60:63], v[156:159], v[206:209], v[60:63]
	v_mfma_f32_16x16x32_bf16 v[64:67], v[160:163], v[202:205], v[64:67]
	v_mfma_f32_16x16x32_bf16 v[64:67], v[164:167], v[206:209], v[64:67]
	s_setprio 0
	s_barrier
	s_mov_b32 m0, s48
	s_mov_b64 s[8:9], s[18:19]
	ds_read_b128 v[168:171], v199 offset:57344
	ds_read_b128 v[172:175], v199 offset:58368
	ds_read_b128 v[176:179], v199 offset:59392
	ds_read_b128 v[180:183], v199 offset:60416
	ds_read_b128 v[184:187], v199 offset:61440
	ds_read_b128 v[188:191], v199 offset:62464
	ds_read_b128 v[202:205], v199 offset:63488
	ds_read_b128 v[206:209], v199 offset:64512
	s_nop 0
	global_load_lds_dwordx4 v201, s[8:9]
	s_mov_b32 m0, s49
	s_nop 0
	global_load_lds_dwordx4 v200, s[8:9]
	s_add_u32 s8, s18, s54
	s_addc_u32 s9, s19, s55
	s_mov_b32 m0, s28
	s_nop 0
	global_load_lds_dwordx4 v201, s[8:9]
	s_mov_b32 m0, s29
	s_nop 0
	global_load_lds_dwordx4 v200, s[8:9]
	s_waitcnt vmcnt(6)
	s_waitcnt lgkmcnt(0)
	s_barrier
	s_setprio 1
	s_waitcnt lgkmcnt(0)
	v_mfma_f32_16x16x32_bf16 v[68:71], v[136:139], v[168:171], v[68:71]
	v_mfma_f32_16x16x32_bf16 v[68:71], v[140:143], v[172:175], v[68:71]
	v_mfma_f32_16x16x32_bf16 v[72:75], v[144:147], v[168:171], v[72:75]
	v_mfma_f32_16x16x32_bf16 v[72:75], v[148:151], v[172:175], v[72:75]
	v_mfma_f32_16x16x32_bf16 v[76:79], v[136:139], v[176:179], v[76:79]
	v_mfma_f32_16x16x32_bf16 v[76:79], v[140:143], v[180:183], v[76:79]
	v_mfma_f32_16x16x32_bf16 v[80:83], v[144:147], v[176:179], v[80:83]
	v_mfma_f32_16x16x32_bf16 v[80:83], v[148:151], v[180:183], v[80:83]
	v_mfma_f32_16x16x32_bf16 v[84:87], v[136:139], v[184:187], v[84:87]
	v_mfma_f32_16x16x32_bf16 v[84:87], v[140:143], v[188:191], v[84:87]
	v_mfma_f32_16x16x32_bf16 v[88:91], v[144:147], v[184:187], v[88:91]
	v_mfma_f32_16x16x32_bf16 v[88:91], v[148:151], v[188:191], v[88:91]
	v_mfma_f32_16x16x32_bf16 v[92:95], v[136:139], v[202:205], v[92:95]
	v_mfma_f32_16x16x32_bf16 v[92:95], v[140:143], v[206:209], v[92:95]
	v_mfma_f32_16x16x32_bf16 v[96:99], v[144:147], v[202:205], v[96:99]
	v_mfma_f32_16x16x32_bf16 v[96:99], v[148:151], v[206:209], v[96:99]
	s_setprio 0
	s_setprio 1
	v_mfma_f32_16x16x32_bf16 v[100:103], v[152:155], v[168:171], v[100:103]
	v_mfma_f32_16x16x32_bf16 v[100:103], v[156:159], v[172:175], v[100:103]
	v_mfma_f32_16x16x32_bf16 v[104:107], v[160:163], v[168:171], v[104:107]
	v_mfma_f32_16x16x32_bf16 v[104:107], v[164:167], v[172:175], v[104:107]
	v_mfma_f32_16x16x32_bf16 v[108:111], v[152:155], v[176:179], v[108:111]
	v_mfma_f32_16x16x32_bf16 v[108:111], v[156:159], v[180:183], v[108:111]
	v_mfma_f32_16x16x32_bf16 v[112:115], v[160:163], v[176:179], v[112:115]
	v_mfma_f32_16x16x32_bf16 v[112:115], v[164:167], v[180:183], v[112:115]
	v_mfma_f32_16x16x32_bf16 v[116:119], v[152:155], v[184:187], v[116:119]
	v_mfma_f32_16x16x32_bf16 v[116:119], v[156:159], v[188:191], v[116:119]
	v_mfma_f32_16x16x32_bf16 v[120:123], v[160:163], v[184:187], v[120:123]
	v_mfma_f32_16x16x32_bf16 v[120:123], v[164:167], v[188:191], v[120:123]
	v_mfma_f32_16x16x32_bf16 v[124:127], v[152:155], v[202:205], v[124:127]
	v_mfma_f32_16x16x32_bf16 v[124:127], v[156:159], v[206:209], v[124:127]
	v_mfma_f32_16x16x32_bf16 v[128:131], v[160:163], v[202:205], v[128:131]
	v_mfma_f32_16x16x32_bf16 v[128:131], v[164:167], v[206:209], v[128:131]
	s_setprio 0
	s_barrier
	s_add_i32 s8, s72, 2
	s_add_u32 s52, s52, 0x100
	s_addc_u32 s53, s53, 0
	s_add_u32 s26, s26, 0x100
	s_addc_u32 s27, s27, 0
	s_cmp_ge_i32 s72, s82
	s_mov_b32 s72, s8
	s_cbranch_scc0 .LBB0_287

.LBB0_427:
	s_add_u32 s8, s26, 0x100
	s_addc_u32 s9, s27, 0
	s_add_u32 s18, s20, 0x100
	s_addc_u32 s19, s21, 0
	s_and_b64 s[16:17], s[62:63], exec
	s_cselect_b32 s31, s51, s19
	s_cselect_b32 s30, s50, s18
	s_add_i32 s44, 0, 0x10000
	s_and_b64 s[16:17], s[62:63], exec
	s_cselect_b32 s19, s15, s9
	s_cselect_b32 s18, s14, s8
	s_add_i32 s8, 0, 0x14000
	v_add_u32_e32 v2, s44, v198
	v_add_u32_e32 v132, s8, v198
	ds_read_b128 v[4:7], v2
	ds_read_b128 v[8:11], v2 offset:1024
	ds_read_b128 v[12:15], v2 offset:2048
	ds_read_b128 v[16:19], v2 offset:3072
	ds_read_b128 v[20:23], v132
	ds_read_b128 v[24:27], v132 offset:1024
	ds_read_b128 v[28:31], v132 offset:2048
	ds_read_b128 v[32:35], v132 offset:3072
	s_add_u32 s16, s26, 0x80
	s_addc_u32 s17, s27, 0
	s_add_i32 s40, s84, 0x8000
	s_add_i32 s41, s84, 0xa000
	s_mov_b64 s[28:29], s[16:17]
	s_mov_b32 m0, s40
	s_add_u32 s16, s16, s52
	ds_read_b128 v[36:39], v199
	ds_read_b128 v[40:43], v199 offset:1024
	ds_read_b128 v[44:47], v199 offset:2048
	ds_read_b128 v[48:51], v199 offset:3072
	ds_read_b128 v[52:55], v199 offset:4096
	ds_read_b128 v[56:59], v199 offset:5120
	ds_read_b128 v[60:63], v199 offset:6144
	ds_read_b128 v[64:67], v199 offset:7168
	s_addc_u32 s17, s17, s53
	global_load_lds_dwordx4 v194, s[28:29]
	s_mov_b32 m0, s41
	s_add_i32 s42, s84, 0xc000
	global_load_lds_dwordx4 v195, s[28:29]
	s_mov_b32 m0, s42
	s_add_i32 s43, s84, 0xe000
	s_add_u32 s28, s30, 0x80
	global_load_lds_dwordx4 v194, s[16:17]
	s_mov_b32 m0, s43
	s_addc_u32 s29, s31, 0
	global_load_lds_dwordx4 v195, s[16:17]
	s_waitcnt vmcnt(8)
	s_waitcnt lgkmcnt(0)
	s_barrier
	s_setprio 1
	s_waitcnt lgkmcnt(0)
	v_mfma_f32_16x16x32_bf16 v[68:71], v[4:7], v[36:39], 0
	v_mfma_f32_16x16x32_bf16 v[72:75], v[12:15], v[36:39], 0
	v_mfma_f32_16x16x32_bf16 v[76:79], v[4:7], v[44:47], 0
	v_mfma_f32_16x16x32_bf16 v[80:83], v[12:15], v[44:47], 0
	v_mfma_f32_16x16x32_bf16 v[84:87], v[4:7], v[52:55], 0
	v_mfma_f32_16x16x32_bf16 v[88:91], v[12:15], v[52:55], 0
	v_mfma_f32_16x16x32_bf16 v[92:95], v[4:7], v[60:63], 0
	v_mfma_f32_16x16x32_bf16 v[96:99], v[12:15], v[60:63], 0
	v_mfma_f32_16x16x32_bf16 v[68:71], v[8:11], v[40:43], v[68:71]
	v_mfma_f32_16x16x32_bf16 v[72:75], v[16:19], v[40:43], v[72:75]
	v_mfma_f32_16x16x32_bf16 v[76:79], v[8:11], v[48:51], v[76:79]
	v_mfma_f32_16x16x32_bf16 v[80:83], v[16:19], v[48:51], v[80:83]
	v_mfma_f32_16x16x32_bf16 v[84:87], v[8:11], v[56:59], v[84:87]
	v_mfma_f32_16x16x32_bf16 v[88:91], v[16:19], v[56:59], v[88:91]
	v_mfma_f32_16x16x32_bf16 v[92:95], v[8:11], v[64:67], v[92:95]
	v_mfma_f32_16x16x32_bf16 v[96:99], v[16:19], v[64:67], v[96:99]
	s_setprio 0
	s_setprio 1
	v_mfma_f32_16x16x32_bf16 v[100:103], v[20:23], v[36:39], 0
	v_mfma_f32_16x16x32_bf16 v[36:39], v[28:31], v[36:39], 0
	v_mfma_f32_16x16x32_bf16 v[100:103], v[24:27], v[40:43], v[100:103]
	v_mfma_f32_16x16x32_bf16 v[40:43], v[32:35], v[40:43], v[36:39]
	v_mfma_f32_16x16x32_bf16 v[36:39], v[20:23], v[44:47], 0
	v_mfma_f32_16x16x32_bf16 v[104:107], v[24:27], v[48:51], v[36:39]
	v_mfma_f32_16x16x32_bf16 v[36:39], v[28:31], v[44:47], 0
	v_mfma_f32_16x16x32_bf16 v[48:51], v[32:35], v[48:51], v[36:39]
	v_mfma_f32_16x16x32_bf16 v[36:39], v[20:23], v[52:55], 0
	v_mfma_f32_16x16x32_bf16 v[108:111], v[24:27], v[56:59], v[36:39]
	v_mfma_f32_16x16x32_bf16 v[36:39], v[28:31], v[52:55], 0
	v_mfma_f32_16x16x32_bf16 v[56:59], v[32:35], v[56:59], v[36:39]
	v_mfma_f32_16x16x32_bf16 v[36:39], v[20:23], v[60:63], 0
	v_mfma_f32_16x16x32_bf16 v[112:115], v[24:27], v[64:67], v[36:39]
	v_mfma_f32_16x16x32_bf16 v[36:39], v[28:31], v[60:63], 0
	v_mfma_f32_16x16x32_bf16 v[64:67], v[32:35], v[64:67], v[36:39]
	s_setprio 0
	s_barrier
	s_add_i32 s44, s44, s82
	s_mov_b64 s[16:17], s[30:31]
	s_mov_b32 m0, s44
	s_add_i32 s45, s44, 0x2000
	s_nop 0
	ds_read_b128 v[36:39], v199 offset:16384
	ds_read_b128 v[44:47], v199 offset:17408
	ds_read_b128 v[52:55], v199 offset:18432
	ds_read_b128 v[60:63], v199 offset:19456
	ds_read_b128 v[116:119], v199 offset:20480
	ds_read_b128 v[120:123], v199 offset:21504
	ds_read_b128 v[124:127], v199 offset:22528
	ds_read_b128 v[128:131], v199 offset:23552
	s_nop 0
	global_load_lds_dwordx4 v201, s[16:17]
	s_mov_b32 m0, s45
	s_nop 0
	global_load_lds_dwordx4 v200, s[16:17]
	s_add_u32 s16, s30, s52
	s_addc_u32 s17, s31, s53
	s_add_i32 s30, s8, s82
	s_mov_b32 m0, s30
	s_add_i32 s31, s30, 0x2000
	s_nop 0
	global_load_lds_dwordx4 v201, s[16:17]
	s_mov_b32 m0, s31
	s_nop 0
	global_load_lds_dwordx4 v200, s[16:17]
	s_waitcnt vmcnt(6)
	s_waitcnt lgkmcnt(0)
	s_barrier
	s_setprio 1
	s_waitcnt lgkmcnt(0)
	v_mfma_f32_16x16x32_bf16 v[134:137], v[4:7], v[36:39], 0
	v_mfma_f32_16x16x32_bf16 v[144:147], v[4:7], v[52:55], 0
	v_mfma_f32_16x16x32_bf16 v[152:155], v[4:7], v[116:119], 0
	v_mfma_f32_16x16x32_bf16 v[4:7], v[4:7], v[124:127], 0
	v_mfma_f32_16x16x32_bf16 v[140:143], v[12:15], v[36:39], 0
	v_mfma_f32_16x16x32_bf16 v[148:151], v[12:15], v[52:55], 0
	v_mfma_f32_16x16x32_bf16 v[156:159], v[12:15], v[116:119], 0
	v_mfma_f32_16x16x32_bf16 v[160:163], v[8:11], v[128:131], v[4:7]
	v_mfma_f32_16x16x32_bf16 v[4:7], v[12:15], v[124:127], 0
	v_mfma_f32_16x16x32_bf16 v[136:139], v[8:11], v[44:47], v[134:137]
	v_mfma_f32_16x16x32_bf16 v[140:143], v[16:19], v[44:47], v[140:143]
	v_mfma_f32_16x16x32_bf16 v[144:147], v[8:11], v[60:63], v[144:147]
	v_mfma_f32_16x16x32_bf16 v[148:151], v[16:19], v[60:63], v[148:151]
	v_mfma_f32_16x16x32_bf16 v[152:155], v[8:11], v[120:123], v[152:155]
	v_mfma_f32_16x16x32_bf16 v[156:159], v[16:19], v[120:123], v[156:159]
	v_mfma_f32_16x16x32_bf16 v[164:167], v[16:19], v[128:131], v[4:7]
	s_setprio 0
	s_setprio 1
	v_mfma_f32_16x16x32_bf16 v[4:7], v[20:23], v[36:39], 0
	v_mfma_f32_16x16x32_bf16 v[168:171], v[24:27], v[44:47], v[4:7]
	v_mfma_f32_16x16x32_bf16 v[4:7], v[28:31], v[36:39], 0
	v_mfma_f32_16x16x32_bf16 v[172:175], v[32:35], v[44:47], v[4:7]
	v_mfma_f32_16x16x32_bf16 v[4:7], v[20:23], v[52:55], 0
	v_mfma_f32_16x16x32_bf16 v[176:179], v[24:27], v[60:63], v[4:7]
	v_mfma_f32_16x16x32_bf16 v[4:7], v[28:31], v[52:55], 0
	v_mfma_f32_16x16x32_bf16 v[180:183], v[32:35], v[60:63], v[4:7]
	v_mfma_f32_16x16x32_bf16 v[4:7], v[20:23], v[116:119], 0
	v_mfma_f32_16x16x32_bf16 v[184:187], v[24:27], v[120:123], v[4:7]
	v_mfma_f32_16x16x32_bf16 v[4:7], v[28:31], v[116:119], 0
	v_mfma_f32_16x16x32_bf16 v[120:123], v[32:35], v[120:123], v[4:7]
	v_mfma_f32_16x16x32_bf16 v[4:7], v[20:23], v[124:127], 0
	v_mfma_f32_16x16x32_bf16 v[188:191], v[24:27], v[128:131], v[4:7]
	v_mfma_f32_16x16x32_bf16 v[4:7], v[28:31], v[124:127], 0
	v_mfma_f32_16x16x32_bf16 v[128:131], v[32:35], v[128:131], v[4:7]
	s_setprio 0
	s_barrier
	s_add_i32 s46, 0, 0x18000
	s_add_i32 s8, 0, 0x1c000
	v_add_u32_e32 v133, s46, v198
	v_add_u32_e32 v134, s8, v198
	ds_read_b128 v[116:119], v133
	ds_read_b128 v[124:127], v133 offset:1024
	ds_read_b128 v[202:205], v133 offset:2048
	ds_read_b128 v[220:223], v133 offset:3072
	ds_read_b128 v[224:227], v134
	ds_read_b128 v[228:231], v134 offset:1024
	ds_read_b128 v[232:235], v134 offset:2048
	ds_read_b128 v[236:239], v134 offset:3072
	s_mov_b32 m0, s84
	s_mov_b64 s[16:17], s[18:19]
	ds_read_b128 v[44:47], v199 offset:32768
	ds_read_b128 v[52:55], v199 offset:33792
	ds_read_b128 v[60:63], v199 offset:34816
	ds_read_b128 v[242:245], v199 offset:35840
	ds_read_b128 v[246:249], v199 offset:36864
	ds_read_b128 v[250:253], v199 offset:37888
	ds_read_b128 v[206:209], v199 offset:38912
	ds_read_b128 v[216:219], v199 offset:39936
	s_nop 0
	global_load_lds_dwordx4 v194, s[16:17]
	s_mov_b32 m0, s85
	s_nop 0
	global_load_lds_dwordx4 v195, s[16:17]
	s_add_u32 s16, s18, s52
	s_addc_u32 s17, s19, s53
	s_mov_b32 m0, s86
	s_nop 0
	global_load_lds_dwordx4 v194, s[16:17]
	s_mov_b32 m0, s87
	s_nop 0
	global_load_lds_dwordx4 v195, s[16:17]
	s_waitcnt vmcnt(8)
	s_waitcnt lgkmcnt(0)
	s_barrier
	s_setprio 1
	s_waitcnt lgkmcnt(0)
	v_mfma_f32_16x16x32_bf16 v[4:7], v[116:119], v[44:47], v[68:71]
	v_mfma_f32_16x16x32_bf16 v[4:7], v[124:127], v[52:55], v[4:7]
	v_mfma_f32_16x16x32_bf16 v[8:11], v[202:205], v[44:47], v[72:75]
	v_mfma_f32_16x16x32_bf16 v[8:11], v[220:223], v[52:55], v[8:11]
	v_mfma_f32_16x16x32_bf16 v[12:15], v[116:119], v[60:63], v[76:79]
	v_mfma_f32_16x16x32_bf16 v[12:15], v[124:127], v[242:245], v[12:15]
	v_mfma_f32_16x16x32_bf16 v[16:19], v[202:205], v[60:63], v[80:83]
	v_mfma_f32_16x16x32_bf16 v[16:19], v[220:223], v[242:245], v[16:19]
	v_mfma_f32_16x16x32_bf16 v[20:23], v[116:119], v[246:249], v[84:87]
	v_mfma_f32_16x16x32_bf16 v[20:23], v[124:127], v[250:253], v[20:23]
	v_mfma_f32_16x16x32_bf16 v[24:27], v[202:205], v[246:249], v[88:91]
	v_mfma_f32_16x16x32_bf16 v[24:27], v[220:223], v[250:253], v[24:27]
	v_mfma_f32_16x16x32_bf16 v[28:31], v[116:119], v[206:209], v[92:95]
	v_mfma_f32_16x16x32_bf16 v[28:31], v[124:127], v[216:219], v[28:31]
	v_mfma_f32_16x16x32_bf16 v[32:35], v[202:205], v[206:209], v[96:99]
	v_mfma_f32_16x16x32_bf16 v[32:35], v[220:223], v[216:219], v[32:35]
	s_setprio 0
	s_setprio 1
	v_mfma_f32_16x16x32_bf16 v[36:39], v[224:227], v[44:47], v[100:103]
	v_mfma_f32_16x16x32_bf16 v[40:43], v[232:235], v[44:47], v[40:43]
	v_mfma_f32_16x16x32_bf16 v[36:39], v[228:231], v[52:55], v[36:39]
	v_mfma_f32_16x16x32_bf16 v[40:43], v[236:239], v[52:55], v[40:43]
	v_mfma_f32_16x16x32_bf16 v[44:47], v[224:227], v[60:63], v[104:107]
	v_mfma_f32_16x16x32_bf16 v[48:51], v[232:235], v[60:63], v[48:51]
	v_mfma_f32_16x16x32_bf16 v[52:55], v[224:227], v[246:249], v[108:111]
	v_mfma_f32_16x16x32_bf16 v[56:59], v[232:235], v[246:249], v[56:59]
	v_mfma_f32_16x16x32_bf16 v[60:63], v[224:227], v[206:209], v[112:115]
	v_mfma_f32_16x16x32_bf16 v[64:67], v[232:235], v[206:209], v[64:67]
	v_mfma_f32_16x16x32_bf16 v[44:47], v[228:231], v[242:245], v[44:47]
	v_mfma_f32_16x16x32_bf16 v[48:51], v[236:239], v[242:245], v[48:51]
	v_mfma_f32_16x16x32_bf16 v[52:55], v[228:231], v[250:253], v[52:55]
	v_mfma_f32_16x16x32_bf16 v[56:59], v[236:239], v[250:253], v[56:59]
	v_mfma_f32_16x16x32_bf16 v[60:63], v[228:231], v[216:219], v[60:63]
	v_mfma_f32_16x16x32_bf16 v[64:67], v[236:239], v[216:219], v[64:67]
	s_setprio 0
	s_barrier
	s_add_i32 s46, s46, s82
	s_mov_b64 s[16:17], s[28:29]
	s_mov_b32 m0, s46
	s_add_i32 s47, s46, 0x2000
	ds_read_b128 v[104:107], v199 offset:49152
	ds_read_b128 v[108:111], v199 offset:50176
	ds_read_b128 v[112:115], v199 offset:51200
	ds_read_b128 v[206:209], v199 offset:52224
	ds_read_b128 v[216:219], v199 offset:53248
	ds_read_b128 v[242:245], v199 offset:54272
	ds_read_b128 v[246:249], v199 offset:55296
	ds_read_b128 v[250:253], v199 offset:56320
	s_nop 0
	global_load_lds_dwordx4 v201, s[16:17]
	s_mov_b32 m0, s47
	s_nop 0
	global_load_lds_dwordx4 v200, s[16:17]
	s_add_u32 s16, s28, s52
	s_addc_u32 s17, s29, s53
	s_add_i32 s28, s8, s82
	s_mov_b32 m0, s28
	s_add_i32 s29, s28, 0x2000
	s_nop 0
	global_load_lds_dwordx4 v201, s[16:17]
	s_mov_b32 m0, s29
	s_nop 0
	global_load_lds_dwordx4 v200, s[16:17]
	s_waitcnt vmcnt(6)
	s_waitcnt lgkmcnt(0)
	s_barrier
	s_setprio 1
	s_waitcnt lgkmcnt(0)
	v_mfma_f32_16x16x32_bf16 v[68:71], v[116:119], v[104:107], v[136:139]
	v_mfma_f32_16x16x32_bf16 v[68:71], v[124:127], v[108:111], v[68:71]
	v_mfma_f32_16x16x32_bf16 v[72:75], v[202:205], v[104:107], v[140:143]
	v_mfma_f32_16x16x32_bf16 v[72:75], v[220:223], v[108:111], v[72:75]
	v_mfma_f32_16x16x32_bf16 v[76:79], v[116:119], v[112:115], v[144:147]
	v_mfma_f32_16x16x32_bf16 v[76:79], v[124:127], v[206:209], v[76:79]
	v_mfma_f32_16x16x32_bf16 v[80:83], v[202:205], v[112:115], v[148:151]
	v_mfma_f32_16x16x32_bf16 v[80:83], v[220:223], v[206:209], v[80:83]
	v_mfma_f32_16x16x32_bf16 v[84:87], v[116:119], v[216:219], v[152:155]
	v_mfma_f32_16x16x32_bf16 v[84:87], v[124:127], v[242:245], v[84:87]
	v_mfma_f32_16x16x32_bf16 v[88:91], v[202:205], v[216:219], v[156:159]
	v_mfma_f32_16x16x32_bf16 v[88:91], v[220:223], v[242:245], v[88:91]
	v_mfma_f32_16x16x32_bf16 v[92:95], v[116:119], v[246:249], v[160:163]
	v_mfma_f32_16x16x32_bf16 v[92:95], v[124:127], v[250:253], v[92:95]
	v_mfma_f32_16x16x32_bf16 v[96:99], v[202:205], v[246:249], v[164:167]
	v_mfma_f32_16x16x32_bf16 v[96:99], v[220:223], v[250:253], v[96:99]
	s_setprio 0
	s_setprio 1
	v_mfma_f32_16x16x32_bf16 v[100:103], v[224:227], v[104:107], v[168:171]
	v_mfma_f32_16x16x32_bf16 v[104:107], v[232:235], v[104:107], v[172:175]
	v_mfma_f32_16x16x32_bf16 v[100:103], v[228:231], v[108:111], v[100:103]
	v_mfma_f32_16x16x32_bf16 v[104:107], v[236:239], v[108:111], v[104:107]
	v_mfma_f32_16x16x32_bf16 v[108:111], v[224:227], v[112:115], v[176:179]
	v_mfma_f32_16x16x32_bf16 v[112:115], v[232:235], v[112:115], v[180:183]
	v_mfma_f32_16x16x32_bf16 v[116:119], v[224:227], v[216:219], v[184:187]
	v_mfma_f32_16x16x32_bf16 v[120:123], v[232:235], v[216:219], v[120:123]
	v_mfma_f32_16x16x32_bf16 v[124:127], v[224:227], v[246:249], v[188:191]
	v_mfma_f32_16x16x32_bf16 v[128:131], v[232:235], v[246:249], v[128:131]
	v_mfma_f32_16x16x32_bf16 v[108:111], v[228:231], v[206:209], v[108:111]
	v_mfma_f32_16x16x32_bf16 v[112:115], v[236:239], v[206:209], v[112:115]
	v_mfma_f32_16x16x32_bf16 v[116:119], v[228:231], v[242:245], v[116:119]
	v_mfma_f32_16x16x32_bf16 v[120:123], v[236:239], v[242:245], v[120:123]
	v_mfma_f32_16x16x32_bf16 v[124:127], v[228:231], v[250:253], v[124:127]
	v_mfma_f32_16x16x32_bf16 v[128:131], v[236:239], v[250:253], v[128:131]
	s_setprio 0
	s_barrier
	s_andn2_b64 vcc, exec, s[64:65]
	s_cbranch_vccnz .LBB0_431
	s_add_u32 s48, s20, 0x200
	s_addc_u32 s49, s21, 0
	s_add_u32 s26, s26, 0x200
	s_addc_u32 s27, s27, 0
	s_mov_b32 s66, 4
.LBB0_429:
	ds_read_b128 v[136:139], v2
	ds_read_b128 v[140:143], v2 offset:1024
	ds_read_b128 v[144:147], v2 offset:2048
	ds_read_b128 v[148:151], v2 offset:3072
	ds_read_b128 v[152:155], v132
	ds_read_b128 v[156:159], v132 offset:1024
	ds_read_b128 v[160:163], v132 offset:2048
	ds_read_b128 v[164:167], v132 offset:3072
	s_cmp_eq_u32 s73, s66
	s_cselect_b32 s17, s51, s49
	s_cselect_b32 s16, s50, s48
	s_cselect_b32 s21, s15, s27
	s_cselect_b32 s20, s14, s26
	s_add_u32 s18, s26, 0xffffff80
	s_addc_u32 s19, s27, -1
	s_mov_b32 m0, s40
	s_mov_b64 s[96:97], s[18:19]
	ds_read_b128 v[168:171], v199
	ds_read_b128 v[172:175], v199 offset:1024
	ds_read_b128 v[176:179], v199 offset:2048
	ds_read_b128 v[180:183], v199 offset:3072
	ds_read_b128 v[184:187], v199 offset:4096
	ds_read_b128 v[188:191], v199 offset:5120
	ds_read_b128 v[202:205], v199 offset:6144
	ds_read_b128 v[206:209], v199 offset:7168
	s_add_u32 s18, s18, s52
	global_load_lds_dwordx4 v194, s[96:97]
	s_mov_b32 m0, s41
	s_addc_u32 s19, s19, s53
	global_load_lds_dwordx4 v195, s[96:97]
	s_mov_b32 m0, s42
	s_nop 0
	global_load_lds_dwordx4 v194, s[18:19]
	s_mov_b32 m0, s43
	s_nop 0
	global_load_lds_dwordx4 v195, s[18:19]
	s_waitcnt vmcnt(8)
	s_waitcnt lgkmcnt(0)
	s_add_u32 s18, s16, 0x80
	s_addc_u32 s19, s17, 0
	s_barrier
	s_setprio 1
	s_waitcnt lgkmcnt(0)
	v_mfma_f32_16x16x32_bf16 v[4:7], v[136:139], v[168:171], v[4:7]
	v_mfma_f32_16x16x32_bf16 v[4:7], v[140:143], v[172:175], v[4:7]
	v_mfma_f32_16x16x32_bf16 v[8:11], v[144:147], v[168:171], v[8:11]
	v_mfma_f32_16x16x32_bf16 v[8:11], v[148:151], v[172:175], v[8:11]
	v_mfma_f32_16x16x32_bf16 v[12:15], v[136:139], v[176:179], v[12:15]
	v_mfma_f32_16x16x32_bf16 v[12:15], v[140:143], v[180:183], v[12:15]
	v_mfma_f32_16x16x32_bf16 v[16:19], v[144:147], v[176:179], v[16:19]
	v_mfma_f32_16x16x32_bf16 v[16:19], v[148:151], v[180:183], v[16:19]
	v_mfma_f32_16x16x32_bf16 v[20:23], v[136:139], v[184:187], v[20:23]
	v_mfma_f32_16x16x32_bf16 v[20:23], v[140:143], v[188:191], v[20:23]
	v_mfma_f32_16x16x32_bf16 v[24:27], v[144:147], v[184:187], v[24:27]
	v_mfma_f32_16x16x32_bf16 v[24:27], v[148:151], v[188:191], v[24:27]
	v_mfma_f32_16x16x32_bf16 v[28:31], v[136:139], v[202:205], v[28:31]
	v_mfma_f32_16x16x32_bf16 v[28:31], v[140:143], v[206:209], v[28:31]
	v_mfma_f32_16x16x32_bf16 v[32:35], v[144:147], v[202:205], v[32:35]
	v_mfma_f32_16x16x32_bf16 v[32:35], v[148:151], v[206:209], v[32:35]
	s_setprio 0
	s_setprio 1
	v_mfma_f32_16x16x32_bf16 v[36:39], v[152:155], v[168:171], v[36:39]
	v_mfma_f32_16x16x32_bf16 v[36:39], v[156:159], v[172:175], v[36:39]
	v_mfma_f32_16x16x32_bf16 v[40:43], v[160:163], v[168:171], v[40:43]
	v_mfma_f32_16x16x32_bf16 v[40:43], v[164:167], v[172:175], v[40:43]
	v_mfma_f32_16x16x32_bf16 v[44:47], v[152:155], v[176:179], v[44:47]
	v_mfma_f32_16x16x32_bf16 v[44:47], v[156:159], v[180:183], v[44:47]
	v_mfma_f32_16x16x32_bf16 v[48:51], v[160:163], v[176:179], v[48:51]
	v_mfma_f32_16x16x32_bf16 v[48:51], v[164:167], v[180:183], v[48:51]
	v_mfma_f32_16x16x32_bf16 v[52:55], v[152:155], v[184:187], v[52:55]
	v_mfma_f32_16x16x32_bf16 v[52:55], v[156:159], v[188:191], v[52:55]
	v_mfma_f32_16x16x32_bf16 v[56:59], v[160:163], v[184:187], v[56:59]
	v_mfma_f32_16x16x32_bf16 v[56:59], v[164:167], v[188:191], v[56:59]
	v_mfma_f32_16x16x32_bf16 v[60:63], v[152:155], v[202:205], v[60:63]
	v_mfma_f32_16x16x32_bf16 v[60:63], v[156:159], v[206:209], v[60:63]
	v_mfma_f32_16x16x32_bf16 v[64:67], v[160:163], v[202:205], v[64:67]
	v_mfma_f32_16x16x32_bf16 v[64:67], v[164:167], v[206:209], v[64:67]
	s_setprio 0
	s_barrier
	s_mov_b32 m0, s44
	s_mov_b64 s[96:97], s[16:17]
	ds_read_b128 v[168:171], v199 offset:16384
	ds_read_b128 v[172:175], v199 offset:17408
	ds_read_b128 v[176:179], v199 offset:18432
	ds_read_b128 v[180:183], v199 offset:19456
	ds_read_b128 v[184:187], v199 offset:20480
	ds_read_b128 v[188:191], v199 offset:21504
	ds_read_b128 v[202:205], v199 offset:22528
	ds_read_b128 v[206:209], v199 offset:23552
	s_add_u32 s16, s16, s52
	global_load_lds_dwordx4 v201, s[96:97]
	s_mov_b32 m0, s45
	s_addc_u32 s17, s17, s53
	global_load_lds_dwordx4 v200, s[96:97]
	s_mov_b32 m0, s30
	s_nop 0
	global_load_lds_dwordx4 v201, s[16:17]
	s_mov_b32 m0, s31
	s_nop 0
	global_load_lds_dwordx4 v200, s[16:17]
	s_waitcnt vmcnt(6)
	s_waitcnt lgkmcnt(0)
	s_barrier
	s_setprio 1
	s_waitcnt lgkmcnt(0)
	v_mfma_f32_16x16x32_bf16 v[68:71], v[136:139], v[168:171], v[68:71]
	v_mfma_f32_16x16x32_bf16 v[68:71], v[140:143], v[172:175], v[68:71]
	v_mfma_f32_16x16x32_bf16 v[72:75], v[144:147], v[168:171], v[72:75]
	v_mfma_f32_16x16x32_bf16 v[72:75], v[148:151], v[172:175], v[72:75]
	v_mfma_f32_16x16x32_bf16 v[76:79], v[136:139], v[176:179], v[76:79]
	v_mfma_f32_16x16x32_bf16 v[76:79], v[140:143], v[180:183], v[76:79]
	v_mfma_f32_16x16x32_bf16 v[80:83], v[144:147], v[176:179], v[80:83]
	v_mfma_f32_16x16x32_bf16 v[80:83], v[148:151], v[180:183], v[80:83]
	v_mfma_f32_16x16x32_bf16 v[84:87], v[136:139], v[184:187], v[84:87]
	v_mfma_f32_16x16x32_bf16 v[84:87], v[140:143], v[188:191], v[84:87]
	v_mfma_f32_16x16x32_bf16 v[88:91], v[144:147], v[184:187], v[88:91]
	v_mfma_f32_16x16x32_bf16 v[88:91], v[148:151], v[188:191], v[88:91]
	v_mfma_f32_16x16x32_bf16 v[92:95], v[136:139], v[202:205], v[92:95]
	v_mfma_f32_16x16x32_bf16 v[92:95], v[140:143], v[206:209], v[92:95]
	v_mfma_f32_16x16x32_bf16 v[96:99], v[144:147], v[202:205], v[96:99]
	v_mfma_f32_16x16x32_bf16 v[96:99], v[148:151], v[206:209], v[96:99]
	s_setprio 0
	s_setprio 1
	v_mfma_f32_16x16x32_bf16 v[100:103], v[152:155], v[168:171], v[100:103]
	v_mfma_f32_16x16x32_bf16 v[100:103], v[156:159], v[172:175], v[100:103]
	v_mfma_f32_16x16x32_bf16 v[104:107], v[160:163], v[168:171], v[104:107]
	v_mfma_f32_16x16x32_bf16 v[104:107], v[164:167], v[172:175], v[104:107]
	v_mfma_f32_16x16x32_bf16 v[108:111], v[152:155], v[176:179], v[108:111]
	v_mfma_f32_16x16x32_bf16 v[108:111], v[156:159], v[180:183], v[108:111]
	v_mfma_f32_16x16x32_bf16 v[112:115], v[160:163], v[176:179], v[112:115]
	v_mfma_f32_16x16x32_bf16 v[112:115], v[164:167], v[180:183], v[112:115]
	v_mfma_f32_16x16x32_bf16 v[116:119], v[152:155], v[184:187], v[116:119]
	v_mfma_f32_16x16x32_bf16 v[116:119], v[156:159], v[188:191], v[116:119]
	v_mfma_f32_16x16x32_bf16 v[120:123], v[160:163], v[184:187], v[120:123]
	v_mfma_f32_16x16x32_bf16 v[120:123], v[164:167], v[188:191], v[120:123]
	v_mfma_f32_16x16x32_bf16 v[124:127], v[152:155], v[202:205], v[124:127]
	v_mfma_f32_16x16x32_bf16 v[124:127], v[156:159], v[206:209], v[124:127]
	v_mfma_f32_16x16x32_bf16 v[128:131], v[160:163], v[202:205], v[128:131]
	v_mfma_f32_16x16x32_bf16 v[128:131], v[164:167], v[206:209], v[128:131]
	s_setprio 0
	s_barrier
	ds_read_b128 v[136:139], v133
	ds_read_b128 v[140:143], v133 offset:1024
	ds_read_b128 v[144:147], v133 offset:2048
	ds_read_b128 v[148:151], v133 offset:3072
	ds_read_b128 v[152:155], v134
	ds_read_b128 v[156:159], v134 offset:1024
	ds_read_b128 v[160:163], v134 offset:2048
	ds_read_b128 v[164:167], v134 offset:3072
	s_mov_b32 m0, s84
	s_mov_b64 s[16:17], s[20:21]
	ds_read_b128 v[168:171], v199 offset:32768
	ds_read_b128 v[172:175], v199 offset:33792
	ds_read_b128 v[176:179], v199 offset:34816
	ds_read_b128 v[180:183], v199 offset:35840
	ds_read_b128 v[184:187], v199 offset:36864
	ds_read_b128 v[188:191], v199 offset:37888
	ds_read_b128 v[202:205], v199 offset:38912
	ds_read_b128 v[206:209], v199 offset:39936
	s_nop 0
	global_load_lds_dwordx4 v194, s[16:17]
	s_mov_b32 m0, s85
	s_nop 0
	global_load_lds_dwordx4 v195, s[16:17]
	s_add_u32 s16, s20, s52
	s_addc_u32 s17, s21, s53
	s_mov_b32 m0, s86
	s_nop 0
	global_load_lds_dwordx4 v194, s[16:17]
	s_mov_b32 m0, s87
	s_nop 0
	global_load_lds_dwordx4 v195, s[16:17]
	s_waitcnt vmcnt(8)
	s_waitcnt lgkmcnt(0)
	s_barrier
	s_setprio 1
	s_waitcnt lgkmcnt(0)
	v_mfma_f32_16x16x32_bf16 v[4:7], v[136:139], v[168:171], v[4:7]
	v_mfma_f32_16x16x32_bf16 v[4:7], v[140:143], v[172:175], v[4:7]
	v_mfma_f32_16x16x32_bf16 v[8:11], v[144:147], v[168:171], v[8:11]
	v_mfma_f32_16x16x32_bf16 v[8:11], v[148:151], v[172:175], v[8:11]
	v_mfma_f32_16x16x32_bf16 v[12:15], v[136:139], v[176:179], v[12:15]
	v_mfma_f32_16x16x32_bf16 v[12:15], v[140:143], v[180:183], v[12:15]
	v_mfma_f32_16x16x32_bf16 v[16:19], v[144:147], v[176:179], v[16:19]
	v_mfma_f32_16x16x32_bf16 v[16:19], v[148:151], v[180:183], v[16:19]
	v_mfma_f32_16x16x32_bf16 v[20:23], v[136:139], v[184:187], v[20:23]
	v_mfma_f32_16x16x32_bf16 v[20:23], v[140:143], v[188:191], v[20:23]
	v_mfma_f32_16x16x32_bf16 v[24:27], v[144:147], v[184:187], v[24:27]
	v_mfma_f32_16x16x32_bf16 v[24:27], v[148:151], v[188:191], v[24:27]
	v_mfma_f32_16x16x32_bf16 v[28:31], v[136:139], v[202:205], v[28:31]
	v_mfma_f32_16x16x32_bf16 v[28:31], v[140:143], v[206:209], v[28:31]
	v_mfma_f32_16x16x32_bf16 v[32:35], v[144:147], v[202:205], v[32:35]
	v_mfma_f32_16x16x32_bf16 v[32:35], v[148:151], v[206:209], v[32:35]
	s_setprio 0
	s_setprio 1
	v_mfma_f32_16x16x32_bf16 v[36:39], v[152:155], v[168:171], v[36:39]
	v_mfma_f32_16x16x32_bf16 v[36:39], v[156:159], v[172:175], v[36:39]
	v_mfma_f32_16x16x32_bf16 v[40:43], v[160:163], v[168:171], v[40:43]
	v_mfma_f32_16x16x32_bf16 v[40:43], v[164:167], v[172:175], v[40:43]
	v_mfma_f32_16x16x32_bf16 v[44:47], v[152:155], v[176:179], v[44:47]
	v_mfma_f32_16x16x32_bf16 v[44:47], v[156:159], v[180:183], v[44:47]
	v_mfma_f32_16x16x32_bf16 v[48:51], v[160:163], v[176:179], v[48:51]
	v_mfma_f32_16x16x32_bf16 v[48:51], v[164:167], v[180:183], v[48:51]
	v_mfma_f32_16x16x32_bf16 v[52:55], v[152:155], v[184:187], v[52:55]
	v_mfma_f32_16x16x32_bf16 v[52:55], v[156:159], v[188:191], v[52:55]
	v_mfma_f32_16x16x32_bf16 v[56:59], v[160:163], v[184:187], v[56:59]
	v_mfma_f32_16x16x32_bf16 v[56:59], v[164:167], v[188:191], v[56:59]
	v_mfma_f32_16x16x32_bf16 v[60:63], v[152:155], v[202:205], v[60:63]
	v_mfma_f32_16x16x32_bf16 v[60:63], v[156:159], v[206:209], v[60:63]
	v_mfma_f32_16x16x32_bf16 v[64:67], v[160:163], v[202:205], v[64:67]
	v_mfma_f32_16x16x32_bf16 v[64:67], v[164:167], v[206:209], v[64:67]
	s_setprio 0
	s_barrier
	s_mov_b32 m0, s46
	s_mov_b64 s[16:17], s[18:19]
	ds_read_b128 v[168:171], v199 offset:49152
	ds_read_b128 v[172:175], v199 offset:50176
	ds_read_b128 v[176:179], v199 offset:51200
	ds_read_b128 v[180:183], v199 offset:52224
	ds_read_b128 v[184:187], v199 offset:53248
	ds_read_b128 v[188:191], v199 offset:54272
	ds_read_b128 v[202:205], v199 offset:55296
	ds_read_b128 v[206:209], v199 offset:56320
	s_nop 0
	global_load_lds_dwordx4 v201, s[16:17]
	s_mov_b32 m0, s47
	s_nop 0
	global_load_lds_dwordx4 v200, s[16:17]
	s_add_u32 s16, s18, s52
	s_addc_u32 s17, s19, s53
	s_mov_b32 m0, s28
	s_nop 0
	global_load_lds_dwordx4 v201, s[16:17]
	s_mov_b32 m0, s29
	s_nop 0
	global_load_lds_dwordx4 v200, s[16:17]
	s_waitcnt vmcnt(6)
	s_waitcnt lgkmcnt(0)
	s_barrier
	s_setprio 1
	s_waitcnt lgkmcnt(0)
	v_mfma_f32_16x16x32_bf16 v[68:71], v[136:139], v[168:171], v[68:71]
	v_mfma_f32_16x16x32_bf16 v[68:71], v[140:143], v[172:175], v[68:71]
	v_mfma_f32_16x16x32_bf16 v[72:75], v[144:147], v[168:171], v[72:75]
	v_mfma_f32_16x16x32_bf16 v[72:75], v[148:151], v[172:175], v[72:75]
	v_mfma_f32_16x16x32_bf16 v[76:79], v[136:139], v[176:179], v[76:79]
	v_mfma_f32_16x16x32_bf16 v[76:79], v[140:143], v[180:183], v[76:79]
	v_mfma_f32_16x16x32_bf16 v[80:83], v[144:147], v[176:179], v[80:83]
	v_mfma_f32_16x16x32_bf16 v[80:83], v[148:151], v[180:183], v[80:83]
	v_mfma_f32_16x16x32_bf16 v[84:87], v[136:139], v[184:187], v[84:87]
	v_mfma_f32_16x16x32_bf16 v[84:87], v[140:143], v[188:191], v[84:87]
	v_mfma_f32_16x16x32_bf16 v[88:91], v[144:147], v[184:187], v[88:91]
	v_mfma_f32_16x16x32_bf16 v[88:91], v[148:151], v[188:191], v[88:91]
	v_mfma_f32_16x16x32_bf16 v[92:95], v[136:139], v[202:205], v[92:95]
	v_mfma_f32_16x16x32_bf16 v[92:95], v[140:143], v[206:209], v[92:95]
	v_mfma_f32_16x16x32_bf16 v[96:99], v[144:147], v[202:205], v[96:99]
	v_mfma_f32_16x16x32_bf16 v[96:99], v[148:151], v[206:209], v[96:99]
	s_setprio 0
	s_setprio 1
	v_mfma_f32_16x16x32_bf16 v[100:103], v[152:155], v[168:171], v[100:103]
	v_mfma_f32_16x16x32_bf16 v[100:103], v[156:159], v[172:175], v[100:103]
	v_mfma_f32_16x16x32_bf16 v[104:107], v[160:163], v[168:171], v[104:107]
	v_mfma_f32_16x16x32_bf16 v[104:107], v[164:167], v[172:175], v[104:107]
	v_mfma_f32_16x16x32_bf16 v[108:111], v[152:155], v[176:179], v[108:111]
	v_mfma_f32_16x16x32_bf16 v[108:111], v[156:159], v[180:183], v[108:111]
	v_mfma_f32_16x16x32_bf16 v[112:115], v[160:163], v[176:179], v[112:115]
	v_mfma_f32_16x16x32_bf16 v[112:115], v[164:167], v[180:183], v[112:115]
	v_mfma_f32_16x16x32_bf16 v[116:119], v[152:155], v[184:187], v[116:119]
	v_mfma_f32_16x16x32_bf16 v[116:119], v[156:159], v[188:191], v[116:119]
	v_mfma_f32_16x16x32_bf16 v[120:123], v[160:163], v[184:187], v[120:123]
	v_mfma_f32_16x16x32_bf16 v[120:123], v[164:167], v[188:191], v[120:123]
	v_mfma_f32_16x16x32_bf16 v[124:127], v[152:155], v[202:205], v[124:127]
	v_mfma_f32_16x16x32_bf16 v[124:127], v[156:159], v[206:209], v[124:127]
	v_mfma_f32_16x16x32_bf16 v[128:131], v[160:163], v[202:205], v[128:131]
	v_mfma_f32_16x16x32_bf16 v[128:131], v[164:167], v[206:209], v[128:131]
	s_setprio 0
	s_barrier
	s_add_i32 s8, s66, 2
	s_add_u32 s48, s48, 0x100
	s_addc_u32 s49, s49, 0
	s_add_u32 s26, s26, 0x100
	s_addc_u32 s27, s27, 0
	s_cmp_ge_i32 s66, s73
	s_mov_b32 s66, s8
	s_cbranch_scc0 .LBB0_429
	v_readlane_b32 s96, v255, 41
	v_readlane_b32 s97, v255, 42

.LBB0_720:
	s_add_i32 s84, s84, 2
	s_and_b64 s[8:9], s[30:31], exec
	s_cselect_b32 s9, s39, s83
	s_cselect_b32 s8, s38, s82
	s_add_u32 s16, s28, 0x80
	v_mov_b32_e32 v197, v3
	v_mov_b32_e32 v201, v3
	v_mov_b32_e32 v199, v3
	s_addc_u32 s17, s29, 0
	s_setprio 0
	s_barrier
	s_add_i32 s28, 0, 0x18000
	s_add_i32 s29, 0, 0x1c000
	v_add_u32_e32 v144, s28, v204
	v_add_u32_e32 v160, s29, v204
	ds_read_b128 v[132:135], v144
	ds_read_b128 v[136:139], v144 offset:1024
	ds_read_b128 v[140:143], v144 offset:2048
	ds_read_b128 v[144:147], v144 offset:3072
	ds_read_b128 v[148:151], v160
	ds_read_b128 v[152:155], v160 offset:1024
	ds_read_b128 v[156:159], v160 offset:2048
	ds_read_b128 v[160:163], v160 offset:3072
	s_mov_b64 s[26:27], s[8:9]
	s_mov_b32 m0, s56
	s_waitcnt lgkmcnt(0)
	ds_read_b128 v[164:167], v205 offset:40960
	ds_read_b128 v[168:171], v205 offset:41984
	ds_read_b128 v[172:175], v205 offset:43008
	ds_read_b128 v[176:179], v205 offset:44032
	ds_read_b128 v[180:183], v205 offset:45056
	ds_read_b128 v[184:187], v205 offset:46080
	ds_read_b128 v[188:191], v205 offset:47104
	ds_read_b128 v[192:195], v205 offset:48128
	s_add_u32 s8, s8, s14
	v_lshl_add_u64 v[206:207], s[26:27], 0, v[2:3]
	global_load_lds_dwordx4 v[206:207], off
	v_lshl_add_u64 v[206:207], s[26:27], 0, v[196:197]
	s_mov_b32 m0, s61
	s_addc_u32 s9, s9, s15
	global_load_lds_dwordx4 v[206:207], off
	s_mov_b32 m0, s62
	v_lshl_add_u64 v[206:207], s[8:9], 0, v[2:3]
	global_load_lds_dwordx4 v[206:207], off
	v_lshl_add_u64 v[206:207], s[8:9], 0, v[196:197]
	s_mov_b32 m0, s63
	s_nop 0
	global_load_lds_dwordx4 v[206:207], off
	s_waitcnt vmcnt(8)
	s_waitcnt lgkmcnt(0)
	s_barrier
	s_setprio 1
	s_waitcnt lgkmcnt(0)
	v_mfma_f32_16x16x32_bf16 v[128:131], v[132:135], v[164:167], v[128:131]
	v_mfma_f32_16x16x32_bf16 v[128:131], v[136:139], v[168:171], v[128:131]
	v_mfma_f32_16x16x32_bf16 v[124:127], v[140:143], v[164:167], v[124:127]
	v_mfma_f32_16x16x32_bf16 v[124:127], v[144:147], v[168:171], v[124:127]
	v_mfma_f32_16x16x32_bf16 v[120:123], v[132:135], v[172:175], v[120:123]
	v_mfma_f32_16x16x32_bf16 v[120:123], v[136:139], v[176:179], v[120:123]
	v_mfma_f32_16x16x32_bf16 v[116:119], v[140:143], v[172:175], v[116:119]
	v_mfma_f32_16x16x32_bf16 v[116:119], v[144:147], v[176:179], v[116:119]
	v_mfma_f32_16x16x32_bf16 v[112:115], v[132:135], v[180:183], v[112:115]
	v_mfma_f32_16x16x32_bf16 v[112:115], v[136:139], v[184:187], v[112:115]
	v_mfma_f32_16x16x32_bf16 v[108:111], v[140:143], v[180:183], v[108:111]
	v_mfma_f32_16x16x32_bf16 v[108:111], v[144:147], v[184:187], v[108:111]
	v_mfma_f32_16x16x32_bf16 v[104:107], v[132:135], v[188:191], v[104:107]
	v_mfma_f32_16x16x32_bf16 v[104:107], v[136:139], v[192:195], v[104:107]
	v_mfma_f32_16x16x32_bf16 v[100:103], v[140:143], v[188:191], v[100:103]
	v_mfma_f32_16x16x32_bf16 v[100:103], v[144:147], v[192:195], v[100:103]
	s_setprio 0
	s_setprio 1
	v_mfma_f32_16x16x32_bf16 v[96:99], v[148:151], v[164:167], v[96:99]
	v_mfma_f32_16x16x32_bf16 v[96:99], v[152:155], v[168:171], v[96:99]
	v_mfma_f32_16x16x32_bf16 v[92:95], v[156:159], v[164:167], v[92:95]
	v_mfma_f32_16x16x32_bf16 v[92:95], v[160:163], v[168:171], v[92:95]
	v_mfma_f32_16x16x32_bf16 v[88:91], v[148:151], v[172:175], v[88:91]
	v_mfma_f32_16x16x32_bf16 v[88:91], v[152:155], v[176:179], v[88:91]
	v_mfma_f32_16x16x32_bf16 v[84:87], v[156:159], v[172:175], v[84:87]
	v_mfma_f32_16x16x32_bf16 v[84:87], v[160:163], v[176:179], v[84:87]
	v_mfma_f32_16x16x32_bf16 v[80:83], v[148:151], v[180:183], v[80:83]
	v_mfma_f32_16x16x32_bf16 v[80:83], v[152:155], v[184:187], v[80:83]
	v_mfma_f32_16x16x32_bf16 v[76:79], v[156:159], v[180:183], v[76:79]
	v_mfma_f32_16x16x32_bf16 v[76:79], v[160:163], v[184:187], v[76:79]
	v_mfma_f32_16x16x32_bf16 v[72:75], v[148:151], v[188:191], v[72:75]
	v_mfma_f32_16x16x32_bf16 v[72:75], v[152:155], v[192:195], v[72:75]
	v_mfma_f32_16x16x32_bf16 v[68:71], v[156:159], v[188:191], v[68:71]
	v_mfma_f32_16x16x32_bf16 v[68:71], v[160:163], v[192:195], v[68:71]
	s_setprio 0
	s_barrier
	s_mov_b64 s[8:9], s[16:17]
	s_add_i32 s26, s28, s55
	ds_read_b128 v[164:167], v205 offset:57344
	ds_read_b128 v[168:171], v205 offset:58368
	ds_read_b128 v[172:175], v205 offset:59392
	ds_read_b128 v[176:179], v205 offset:60416
	ds_read_b128 v[180:183], v205 offset:61440
	ds_read_b128 v[184:187], v205 offset:62464
	ds_read_b128 v[188:191], v205 offset:63488
	ds_read_b128 v[192:195], v205 offset:64512
	s_mov_b32 m0, s26
	v_lshl_add_u64 v[206:207], s[8:9], 0, v[200:201]
	global_load_lds_dwordx4 v[206:207], off
	s_add_i32 m0, s26, 0x2000
	v_lshl_add_u64 v[206:207], s[8:9], 0, v[198:199]
	s_add_u32 s8, s16, s14
	s_addc_u32 s9, s17, s15
	s_add_i32 s16, s29, s55
	global_load_lds_dwordx4 v[206:207], off
	s_mov_b32 m0, s16
	v_lshl_add_u64 v[206:207], s[8:9], 0, v[200:201]
	global_load_lds_dwordx4 v[206:207], off
	v_lshl_add_u64 v[206:207], s[8:9], 0, v[198:199]
	s_add_i32 m0, s16, 0x2000
	s_nop 0
	global_load_lds_dwordx4 v[206:207], off
	s_waitcnt vmcnt(6)
	s_waitcnt lgkmcnt(0)
	s_barrier
	s_setprio 1
	s_waitcnt lgkmcnt(0)
	v_mfma_f32_16x16x32_bf16 v[64:67], v[132:135], v[164:167], v[64:67]
	v_mfma_f32_16x16x32_bf16 v[64:67], v[136:139], v[168:171], v[64:67]
	v_mfma_f32_16x16x32_bf16 v[60:63], v[140:143], v[164:167], v[60:63]
	v_mfma_f32_16x16x32_bf16 v[60:63], v[144:147], v[168:171], v[60:63]
	v_mfma_f32_16x16x32_bf16 v[56:59], v[132:135], v[172:175], v[56:59]
	v_mfma_f32_16x16x32_bf16 v[56:59], v[136:139], v[176:179], v[56:59]
	v_mfma_f32_16x16x32_bf16 v[52:55], v[140:143], v[172:175], v[52:55]
	v_mfma_f32_16x16x32_bf16 v[52:55], v[144:147], v[176:179], v[52:55]
	v_mfma_f32_16x16x32_bf16 v[48:51], v[132:135], v[180:183], v[48:51]
	v_mfma_f32_16x16x32_bf16 v[48:51], v[136:139], v[184:187], v[48:51]
	v_mfma_f32_16x16x32_bf16 v[44:47], v[140:143], v[180:183], v[44:47]
	v_mfma_f32_16x16x32_bf16 v[44:47], v[144:147], v[184:187], v[44:47]
	v_mfma_f32_16x16x32_bf16 v[40:43], v[132:135], v[188:191], v[40:43]
	v_mfma_f32_16x16x32_bf16 v[40:43], v[136:139], v[192:195], v[40:43]
	v_mfma_f32_16x16x32_bf16 v[36:39], v[140:143], v[188:191], v[36:39]
	v_mfma_f32_16x16x32_bf16 v[36:39], v[144:147], v[192:195], v[36:39]
	s_setprio 0
	s_setprio 1
	v_mfma_f32_16x16x32_bf16 v[32:35], v[148:151], v[164:167], v[32:35]
	v_mfma_f32_16x16x32_bf16 v[32:35], v[152:155], v[168:171], v[32:35]
	v_mfma_f32_16x16x32_bf16 v[28:31], v[156:159], v[164:167], v[28:31]
	v_mfma_f32_16x16x32_bf16 v[28:31], v[160:163], v[168:171], v[28:31]
	v_mfma_f32_16x16x32_bf16 v[24:27], v[148:151], v[172:175], v[24:27]
	v_mfma_f32_16x16x32_bf16 v[24:27], v[152:155], v[176:179], v[24:27]
	v_mfma_f32_16x16x32_bf16 v[20:23], v[156:159], v[172:175], v[20:23]
	v_mfma_f32_16x16x32_bf16 v[20:23], v[160:163], v[176:179], v[20:23]
	v_mfma_f32_16x16x32_bf16 v[16:19], v[148:151], v[180:183], v[16:19]
	v_mfma_f32_16x16x32_bf16 v[16:19], v[152:155], v[184:187], v[16:19]
	v_mfma_f32_16x16x32_bf16 v[12:15], v[156:159], v[180:183], v[12:15]
	v_mfma_f32_16x16x32_bf16 v[12:15], v[160:163], v[184:187], v[12:15]
	v_mfma_f32_16x16x32_bf16 v[8:11], v[148:151], v[188:191], v[8:11]
	v_mfma_f32_16x16x32_bf16 v[8:11], v[152:155], v[192:195], v[8:11]
	v_mfma_f32_16x16x32_bf16 v[4:7], v[156:159], v[188:191], v[4:7]
	v_mfma_f32_16x16x32_bf16 v[4:7], v[160:163], v[192:195], v[4:7]
	s_setprio 0
	s_barrier
	s_add_u32 s80, s80, 0x100
	s_addc_u32 s81, s81, 0
	s_add_u32 s82, s82, 0x100
	s_addc_u32 s83, s83, 0
	s_cmp_ge_u32 s84, s47
	s_cbranch_scc1 .LBB0_737
.LBB0_721:
	v_add_u32_e32 v132, 0, v204
	v_add_u32_e32 v133, 0x10000, v132
	v_add_u32_e32 v144, 0x14000, v132
	ds_read_b128 v[148:151], v133
	ds_read_b128 v[152:155], v133 offset:1024
	ds_read_b128 v[156:159], v133 offset:2048
	ds_read_b128 v[160:163], v133 offset:3072
	ds_read_b128 v[132:135], v144
	ds_read_b128 v[136:139], v144 offset:1024
	ds_read_b128 v[140:143], v144 offset:2048
	ds_read_b128 v[144:147], v144 offset:3072
	s_or_b32 s8, s84, s76
	s_cmp_lg_u32 s8, 0
	s_cselect_b64 s[26:27], -1, 0
	s_add_u32 s8, s82, 0xffffff80
	s_addc_u32 s9, s83, -1
	s_mov_b64 s[16:17], s[8:9]
	s_add_i32 m0, s56, 0x8000
	ds_read_b128 v[188:191], v205 offset:8192
	ds_read_b128 v[192:195], v205 offset:9216
	ds_read_b128 v[180:183], v205 offset:10240
	ds_read_b128 v[184:187], v205 offset:11264
	ds_read_b128 v[172:175], v205 offset:12288
	ds_read_b128 v[176:179], v205 offset:13312
	ds_read_b128 v[164:167], v205 offset:14336
	ds_read_b128 v[168:171], v205 offset:15360
	s_nop 0
	global_load_lds_dwordx4 v2, s[16:17]
	s_add_i32 m0, s56, 0xa000
	s_add_u32 s8, s8, s14
	global_load_lds_dwordx4 v196, s[16:17]
	s_addc_u32 s9, s9, s15
	s_add_i32 m0, s56, 0xc000
	s_nop 0
	global_load_lds_dwordx4 v2, s[8:9]
	s_add_i32 m0, s56, 0xe000
	s_nop 0
	global_load_lds_dwordx4 v196, s[8:9]
	s_waitcnt vmcnt(8)
	s_waitcnt lgkmcnt(0)
	s_barrier
	s_setprio 1
	s_and_b64 vcc, exec, s[26:27]
	s_cbranch_vccz .LBB0_732
	s_waitcnt lgkmcnt(0)
	v_mfma_f32_16x16x32_bf16 v[128:131], v[148:151], v[188:191], v[128:131]
	v_mfma_f32_16x16x32_bf16 v[128:131], v[152:155], v[192:195], v[128:131]
	v_mfma_f32_16x16x32_bf16 v[124:127], v[156:159], v[188:191], v[124:127]
	v_mfma_f32_16x16x32_bf16 v[124:127], v[160:163], v[192:195], v[124:127]
	v_mfma_f32_16x16x32_bf16 v[120:123], v[148:151], v[180:183], v[120:123]
	v_mfma_f32_16x16x32_bf16 v[120:123], v[152:155], v[184:187], v[120:123]
	v_mfma_f32_16x16x32_bf16 v[116:119], v[156:159], v[180:183], v[116:119]
	v_mfma_f32_16x16x32_bf16 v[116:119], v[160:163], v[184:187], v[116:119]
	v_mfma_f32_16x16x32_bf16 v[112:115], v[148:151], v[172:175], v[112:115]
	v_mfma_f32_16x16x32_bf16 v[112:115], v[152:155], v[176:179], v[112:115]
	v_mfma_f32_16x16x32_bf16 v[108:111], v[156:159], v[172:175], v[108:111]
	v_mfma_f32_16x16x32_bf16 v[108:111], v[160:163], v[176:179], v[108:111]
	v_mfma_f32_16x16x32_bf16 v[104:107], v[148:151], v[164:167], v[104:107]
	v_mfma_f32_16x16x32_bf16 v[104:107], v[152:155], v[168:171], v[104:107]
	v_mfma_f32_16x16x32_bf16 v[100:103], v[156:159], v[164:167], v[100:103]
	v_mfma_f32_16x16x32_bf16 v[100:103], v[160:163], v[168:171], v[100:103]
	s_cbranch_execnz .LBB0_724

.LBB0_724:
	s_setprio 0
	s_setprio 1
	s_and_b64 vcc, exec, s[26:27]
	s_cbranch_vccz .LBB0_733
	s_waitcnt lgkmcnt(0)
	v_mfma_f32_16x16x32_bf16 v[96:99], v[132:135], v[188:191], v[96:99]
	v_mfma_f32_16x16x32_bf16 v[96:99], v[136:139], v[192:195], v[96:99]
	v_mfma_f32_16x16x32_bf16 v[92:95], v[140:143], v[188:191], v[92:95]
	v_mfma_f32_16x16x32_bf16 v[92:95], v[144:147], v[192:195], v[92:95]
	v_mfma_f32_16x16x32_bf16 v[88:91], v[132:135], v[180:183], v[88:91]
	v_mfma_f32_16x16x32_bf16 v[88:91], v[136:139], v[184:187], v[88:91]
	v_mfma_f32_16x16x32_bf16 v[84:87], v[140:143], v[180:183], v[84:87]
	v_mfma_f32_16x16x32_bf16 v[84:87], v[144:147], v[184:187], v[84:87]
	v_mfma_f32_16x16x32_bf16 v[80:83], v[132:135], v[172:175], v[80:83]
	v_mfma_f32_16x16x32_bf16 v[80:83], v[136:139], v[176:179], v[80:83]
	v_mfma_f32_16x16x32_bf16 v[76:79], v[140:143], v[172:175], v[76:79]
	v_mfma_f32_16x16x32_bf16 v[76:79], v[144:147], v[176:179], v[76:79]
	v_mfma_f32_16x16x32_bf16 v[72:75], v[132:135], v[164:167], v[72:75]
	v_mfma_f32_16x16x32_bf16 v[72:75], v[136:139], v[168:171], v[72:75]
	v_mfma_f32_16x16x32_bf16 v[68:71], v[140:143], v[164:167], v[68:71]
	v_mfma_f32_16x16x32_bf16 v[68:71], v[144:147], v[168:171], v[68:71]
	s_cbranch_execnz .LBB0_727

.LBB0_727:
	s_cmp_eq_u32 s79, s84
	s_cselect_b64 s[30:31], -1, 0
	s_and_b64 s[8:9], s[30:31], exec
	s_cselect_b32 s29, s41, s81
	s_cselect_b32 s28, s40, s80
	s_setprio 0
	s_barrier
	s_mov_b32 m0, s57
	s_mov_b64 s[8:9], s[28:29]
	s_waitcnt lgkmcnt(0)
	ds_read_b128 v[188:191], v205 offset:24576
	ds_read_b128 v[192:195], v205 offset:25600
	ds_read_b128 v[180:183], v205 offset:26624
	ds_read_b128 v[184:187], v205 offset:27648
	ds_read_b128 v[172:175], v205 offset:28672
	ds_read_b128 v[176:179], v205 offset:29696
	ds_read_b128 v[164:167], v205 offset:30720
	ds_read_b128 v[168:171], v205 offset:31744
	s_nop 0
	global_load_lds_dwordx4 v200, s[8:9]
	s_mov_b32 m0, s58
	s_nop 0
	global_load_lds_dwordx4 v198, s[8:9]
	s_add_u32 s8, s28, s14
	s_addc_u32 s9, s29, s15
	s_mov_b32 m0, s59
	s_nop 0
	global_load_lds_dwordx4 v200, s[8:9]
	s_mov_b32 m0, s60
	s_nop 0
	global_load_lds_dwordx4 v198, s[8:9]
	s_waitcnt vmcnt(6)
	s_waitcnt lgkmcnt(0)
	s_barrier
	s_setprio 1
	s_and_b64 vcc, exec, s[26:27]
	s_cbranch_vccz .LBB0_734
	s_waitcnt lgkmcnt(0)
	v_mfma_f32_16x16x32_bf16 v[64:67], v[148:151], v[188:191], v[64:67]
	v_mfma_f32_16x16x32_bf16 v[64:67], v[152:155], v[192:195], v[64:67]
	v_mfma_f32_16x16x32_bf16 v[60:63], v[156:159], v[188:191], v[60:63]
	v_mfma_f32_16x16x32_bf16 v[60:63], v[160:163], v[192:195], v[60:63]
	v_mfma_f32_16x16x32_bf16 v[56:59], v[148:151], v[180:183], v[56:59]
	v_mfma_f32_16x16x32_bf16 v[56:59], v[152:155], v[184:187], v[56:59]
	v_mfma_f32_16x16x32_bf16 v[52:55], v[156:159], v[180:183], v[52:55]
	v_mfma_f32_16x16x32_bf16 v[52:55], v[160:163], v[184:187], v[52:55]
	v_mfma_f32_16x16x32_bf16 v[48:51], v[148:151], v[172:175], v[48:51]
	v_mfma_f32_16x16x32_bf16 v[48:51], v[152:155], v[176:179], v[48:51]
	v_mfma_f32_16x16x32_bf16 v[44:47], v[156:159], v[172:175], v[44:47]
	v_mfma_f32_16x16x32_bf16 v[44:47], v[160:163], v[176:179], v[44:47]
	v_mfma_f32_16x16x32_bf16 v[40:43], v[148:151], v[164:167], v[40:43]
	v_mfma_f32_16x16x32_bf16 v[40:43], v[152:155], v[168:171], v[40:43]
	v_mfma_f32_16x16x32_bf16 v[36:39], v[156:159], v[164:167], v[36:39]
	v_mfma_f32_16x16x32_bf16 v[36:39], v[160:163], v[168:171], v[36:39]
	s_cbranch_execnz .LBB0_730

.LBB0_730:
	s_setprio 0
	s_setprio 1
	s_and_b64 vcc, exec, s[26:27]
	s_cbranch_vccz .LBB0_735
	s_waitcnt lgkmcnt(0)
	v_mfma_f32_16x16x32_bf16 v[32:35], v[132:135], v[188:191], v[32:35]
	v_mfma_f32_16x16x32_bf16 v[32:35], v[136:139], v[192:195], v[32:35]
	v_mfma_f32_16x16x32_bf16 v[28:31], v[140:143], v[188:191], v[28:31]
	v_mfma_f32_16x16x32_bf16 v[28:31], v[144:147], v[192:195], v[28:31]
	v_mfma_f32_16x16x32_bf16 v[24:27], v[132:135], v[180:183], v[24:27]
	v_mfma_f32_16x16x32_bf16 v[24:27], v[136:139], v[184:187], v[24:27]
	v_mfma_f32_16x16x32_bf16 v[20:23], v[140:143], v[180:183], v[20:23]
	v_mfma_f32_16x16x32_bf16 v[20:23], v[144:147], v[184:187], v[20:23]
	v_mfma_f32_16x16x32_bf16 v[16:19], v[132:135], v[172:175], v[16:19]
	v_mfma_f32_16x16x32_bf16 v[16:19], v[136:139], v[176:179], v[16:19]
	v_mfma_f32_16x16x32_bf16 v[12:15], v[140:143], v[172:175], v[12:15]
	v_mfma_f32_16x16x32_bf16 v[12:15], v[144:147], v[176:179], v[12:15]
	v_mfma_f32_16x16x32_bf16 v[8:11], v[132:135], v[164:167], v[8:11]
	v_mfma_f32_16x16x32_bf16 v[8:11], v[136:139], v[168:171], v[8:11]
	v_mfma_f32_16x16x32_bf16 v[4:7], v[140:143], v[164:167], v[4:7]
	v_mfma_f32_16x16x32_bf16 v[4:7], v[144:147], v[168:171], v[4:7]
	s_cbranch_execnz .LBB0_720
	s_branch .LBB0_736

.LBB0_760:
	s_add_i32 s80, s80, 2
	s_and_b64 s[8:9], s[30:31], exec
	s_cselect_b32 s9, s39, s79
	s_cselect_b32 s8, s38, s78
	s_add_u32 s16, s28, 0x80
	v_mov_b32_e32 v197, v3
	v_mov_b32_e32 v201, v3
	v_mov_b32_e32 v199, v3
	s_addc_u32 s17, s29, 0
	s_setprio 0
	s_barrier
	s_add_i32 s28, 0, 0x18000
	s_add_i32 s29, 0, 0x1c000
	v_add_u32_e32 v144, s28, v204
	v_add_u32_e32 v160, s29, v204
	ds_read_b128 v[132:135], v144
	ds_read_b128 v[136:139], v144 offset:1024
	ds_read_b128 v[140:143], v144 offset:2048
	ds_read_b128 v[144:147], v144 offset:3072
	ds_read_b128 v[148:151], v160
	ds_read_b128 v[152:155], v160 offset:1024
	ds_read_b128 v[156:159], v160 offset:2048
	ds_read_b128 v[160:163], v160 offset:3072
	s_mov_b64 s[26:27], s[8:9]
	s_mov_b32 m0, s56
	s_waitcnt lgkmcnt(0)
	ds_read_b128 v[164:167], v205 offset:32768
	ds_read_b128 v[168:171], v205 offset:33792
	ds_read_b128 v[172:175], v205 offset:34816
	ds_read_b128 v[176:179], v205 offset:35840
	ds_read_b128 v[180:183], v205 offset:36864
	ds_read_b128 v[184:187], v205 offset:37888
	ds_read_b128 v[188:191], v205 offset:38912
	ds_read_b128 v[192:195], v205 offset:39936
	s_add_u32 s8, s8, s14
	v_lshl_add_u64 v[206:207], s[26:27], 0, v[2:3]
	global_load_lds_dwordx4 v[206:207], off
	v_lshl_add_u64 v[206:207], s[26:27], 0, v[196:197]
	s_mov_b32 m0, s61
	s_addc_u32 s9, s9, s15
	global_load_lds_dwordx4 v[206:207], off
	s_mov_b32 m0, s62
	v_lshl_add_u64 v[206:207], s[8:9], 0, v[2:3]
	global_load_lds_dwordx4 v[206:207], off
	v_lshl_add_u64 v[206:207], s[8:9], 0, v[196:197]
	s_mov_b32 m0, s63
	s_nop 0
	global_load_lds_dwordx4 v[206:207], off
	s_waitcnt vmcnt(8)
	s_waitcnt lgkmcnt(0)
	s_barrier
	s_setprio 1
	s_waitcnt lgkmcnt(0)
	v_mfma_f32_16x16x32_bf16 v[128:131], v[132:135], v[164:167], v[128:131]
	v_mfma_f32_16x16x32_bf16 v[128:131], v[136:139], v[168:171], v[128:131]
	v_mfma_f32_16x16x32_bf16 v[124:127], v[140:143], v[164:167], v[124:127]
	v_mfma_f32_16x16x32_bf16 v[124:127], v[144:147], v[168:171], v[124:127]
	v_mfma_f32_16x16x32_bf16 v[120:123], v[132:135], v[172:175], v[120:123]
	v_mfma_f32_16x16x32_bf16 v[120:123], v[136:139], v[176:179], v[120:123]
	v_mfma_f32_16x16x32_bf16 v[116:119], v[140:143], v[172:175], v[116:119]
	v_mfma_f32_16x16x32_bf16 v[116:119], v[144:147], v[176:179], v[116:119]
	v_mfma_f32_16x16x32_bf16 v[112:115], v[132:135], v[180:183], v[112:115]
	v_mfma_f32_16x16x32_bf16 v[112:115], v[136:139], v[184:187], v[112:115]
	v_mfma_f32_16x16x32_bf16 v[108:111], v[140:143], v[180:183], v[108:111]
	v_mfma_f32_16x16x32_bf16 v[108:111], v[144:147], v[184:187], v[108:111]
	v_mfma_f32_16x16x32_bf16 v[104:107], v[132:135], v[188:191], v[104:107]
	v_mfma_f32_16x16x32_bf16 v[104:107], v[136:139], v[192:195], v[104:107]
	v_mfma_f32_16x16x32_bf16 v[100:103], v[140:143], v[188:191], v[100:103]
	v_mfma_f32_16x16x32_bf16 v[100:103], v[144:147], v[192:195], v[100:103]
	s_setprio 0
	s_setprio 1
	v_mfma_f32_16x16x32_bf16 v[96:99], v[148:151], v[164:167], v[96:99]
	v_mfma_f32_16x16x32_bf16 v[96:99], v[152:155], v[168:171], v[96:99]
	v_mfma_f32_16x16x32_bf16 v[92:95], v[156:159], v[164:167], v[92:95]
	v_mfma_f32_16x16x32_bf16 v[92:95], v[160:163], v[168:171], v[92:95]
	v_mfma_f32_16x16x32_bf16 v[88:91], v[148:151], v[172:175], v[88:91]
	v_mfma_f32_16x16x32_bf16 v[88:91], v[152:155], v[176:179], v[88:91]
	v_mfma_f32_16x16x32_bf16 v[84:87], v[156:159], v[172:175], v[84:87]
	v_mfma_f32_16x16x32_bf16 v[84:87], v[160:163], v[176:179], v[84:87]
	v_mfma_f32_16x16x32_bf16 v[80:83], v[148:151], v[180:183], v[80:83]
	v_mfma_f32_16x16x32_bf16 v[80:83], v[152:155], v[184:187], v[80:83]
	v_mfma_f32_16x16x32_bf16 v[76:79], v[156:159], v[180:183], v[76:79]
	v_mfma_f32_16x16x32_bf16 v[76:79], v[160:163], v[184:187], v[76:79]
	v_mfma_f32_16x16x32_bf16 v[72:75], v[148:151], v[188:191], v[72:75]
	v_mfma_f32_16x16x32_bf16 v[72:75], v[152:155], v[192:195], v[72:75]
	v_mfma_f32_16x16x32_bf16 v[68:71], v[156:159], v[188:191], v[68:71]
	v_mfma_f32_16x16x32_bf16 v[68:71], v[160:163], v[192:195], v[68:71]
	s_setprio 0
	s_barrier
	s_mov_b64 s[8:9], s[16:17]
	s_add_i32 s26, s28, s55
	ds_read_b128 v[164:167], v205 offset:49152
	ds_read_b128 v[168:171], v205 offset:50176
	ds_read_b128 v[172:175], v205 offset:51200
	ds_read_b128 v[176:179], v205 offset:52224
	ds_read_b128 v[180:183], v205 offset:53248
	ds_read_b128 v[184:187], v205 offset:54272
	ds_read_b128 v[188:191], v205 offset:55296
	ds_read_b128 v[192:195], v205 offset:56320
	s_mov_b32 m0, s26
	v_lshl_add_u64 v[206:207], s[8:9], 0, v[200:201]
	global_load_lds_dwordx4 v[206:207], off
	s_add_i32 m0, s26, 0x2000
	v_lshl_add_u64 v[206:207], s[8:9], 0, v[198:199]
	s_add_u32 s8, s16, s14
	s_addc_u32 s9, s17, s15
	s_add_i32 s16, s29, s55
	global_load_lds_dwordx4 v[206:207], off
	s_mov_b32 m0, s16
	v_lshl_add_u64 v[206:207], s[8:9], 0, v[200:201]
	global_load_lds_dwordx4 v[206:207], off
	v_lshl_add_u64 v[206:207], s[8:9], 0, v[198:199]
	s_add_i32 m0, s16, 0x2000
	s_nop 0
	global_load_lds_dwordx4 v[206:207], off
	s_waitcnt vmcnt(6)
	s_waitcnt lgkmcnt(0)
	s_barrier
	s_setprio 1
	s_waitcnt lgkmcnt(0)
	v_mfma_f32_16x16x32_bf16 v[64:67], v[132:135], v[164:167], v[64:67]
	v_mfma_f32_16x16x32_bf16 v[64:67], v[136:139], v[168:171], v[64:67]
	v_mfma_f32_16x16x32_bf16 v[60:63], v[140:143], v[164:167], v[60:63]
	v_mfma_f32_16x16x32_bf16 v[60:63], v[144:147], v[168:171], v[60:63]
	v_mfma_f32_16x16x32_bf16 v[56:59], v[132:135], v[172:175], v[56:59]
	v_mfma_f32_16x16x32_bf16 v[56:59], v[136:139], v[176:179], v[56:59]
	v_mfma_f32_16x16x32_bf16 v[52:55], v[140:143], v[172:175], v[52:55]
	v_mfma_f32_16x16x32_bf16 v[52:55], v[144:147], v[176:179], v[52:55]
	v_mfma_f32_16x16x32_bf16 v[48:51], v[132:135], v[180:183], v[48:51]
	v_mfma_f32_16x16x32_bf16 v[48:51], v[136:139], v[184:187], v[48:51]
	v_mfma_f32_16x16x32_bf16 v[44:47], v[140:143], v[180:183], v[44:47]
	v_mfma_f32_16x16x32_bf16 v[44:47], v[144:147], v[184:187], v[44:47]
	v_mfma_f32_16x16x32_bf16 v[40:43], v[132:135], v[188:191], v[40:43]
	v_mfma_f32_16x16x32_bf16 v[40:43], v[136:139], v[192:195], v[40:43]
	v_mfma_f32_16x16x32_bf16 v[36:39], v[140:143], v[188:191], v[36:39]
	v_mfma_f32_16x16x32_bf16 v[36:39], v[144:147], v[192:195], v[36:39]
	s_setprio 0
	s_setprio 1
	v_mfma_f32_16x16x32_bf16 v[32:35], v[148:151], v[164:167], v[32:35]
	v_mfma_f32_16x16x32_bf16 v[32:35], v[152:155], v[168:171], v[32:35]
	v_mfma_f32_16x16x32_bf16 v[28:31], v[156:159], v[164:167], v[28:31]
	v_mfma_f32_16x16x32_bf16 v[28:31], v[160:163], v[168:171], v[28:31]
	v_mfma_f32_16x16x32_bf16 v[24:27], v[148:151], v[172:175], v[24:27]
	v_mfma_f32_16x16x32_bf16 v[24:27], v[152:155], v[176:179], v[24:27]
	v_mfma_f32_16x16x32_bf16 v[20:23], v[156:159], v[172:175], v[20:23]
	v_mfma_f32_16x16x32_bf16 v[20:23], v[160:163], v[176:179], v[20:23]
	v_mfma_f32_16x16x32_bf16 v[16:19], v[148:151], v[180:183], v[16:19]
	v_mfma_f32_16x16x32_bf16 v[16:19], v[152:155], v[184:187], v[16:19]
	v_mfma_f32_16x16x32_bf16 v[12:15], v[156:159], v[180:183], v[12:15]
	v_mfma_f32_16x16x32_bf16 v[12:15], v[160:163], v[184:187], v[12:15]
	v_mfma_f32_16x16x32_bf16 v[8:11], v[148:151], v[188:191], v[8:11]
	v_mfma_f32_16x16x32_bf16 v[8:11], v[152:155], v[192:195], v[8:11]
	v_mfma_f32_16x16x32_bf16 v[4:7], v[156:159], v[188:191], v[4:7]
	v_mfma_f32_16x16x32_bf16 v[4:7], v[160:163], v[192:195], v[4:7]
	s_setprio 0
	s_barrier
	s_add_u32 s76, s76, 0x100
	s_addc_u32 s77, s77, 0
	s_add_u32 s78, s78, 0x100
	s_addc_u32 s79, s79, 0
	s_cmp_ge_u32 s80, s47
	s_cbranch_scc1 .LBB0_777
.LBB0_761:
	v_add_u32_e32 v132, 0, v204
	v_add_u32_e32 v133, 0x10000, v132
	v_add_u32_e32 v144, 0x14000, v132
	ds_read_b128 v[148:151], v133
	ds_read_b128 v[152:155], v133 offset:1024
	ds_read_b128 v[156:159], v133 offset:2048
	ds_read_b128 v[160:163], v133 offset:3072
	ds_read_b128 v[132:135], v144
	ds_read_b128 v[136:139], v144 offset:1024
	ds_read_b128 v[140:143], v144 offset:2048
	ds_read_b128 v[144:147], v144 offset:3072
	s_or_b32 s8, s80, s67
	s_cmp_lg_u32 s8, 0
	s_cselect_b64 s[26:27], -1, 0
	s_add_u32 s8, s78, 0xffffff80
	s_addc_u32 s9, s79, -1
	s_mov_b64 s[16:17], s[8:9]
	s_add_i32 m0, s56, 0x8000
	ds_read_b128 v[188:191], v205
	ds_read_b128 v[192:195], v205 offset:1024
	ds_read_b128 v[180:183], v205 offset:2048
	ds_read_b128 v[184:187], v205 offset:3072
	ds_read_b128 v[172:175], v205 offset:4096
	ds_read_b128 v[176:179], v205 offset:5120
	ds_read_b128 v[164:167], v205 offset:6144
	ds_read_b128 v[168:171], v205 offset:7168
	s_nop 0
	global_load_lds_dwordx4 v2, s[16:17]
	s_add_i32 m0, s56, 0xa000
	s_add_u32 s8, s8, s14
	global_load_lds_dwordx4 v196, s[16:17]
	s_addc_u32 s9, s9, s15
	s_add_i32 m0, s56, 0xc000
	s_nop 0
	global_load_lds_dwordx4 v2, s[8:9]
	s_add_i32 m0, s56, 0xe000
	s_nop 0
	global_load_lds_dwordx4 v196, s[8:9]
	s_waitcnt vmcnt(8)
	s_waitcnt lgkmcnt(0)
	s_barrier
	s_setprio 1
	s_and_b64 vcc, exec, s[26:27]
	s_cbranch_vccz .LBB0_772
	s_waitcnt lgkmcnt(0)
	v_mfma_f32_16x16x32_bf16 v[128:131], v[148:151], v[188:191], v[128:131]
	v_mfma_f32_16x16x32_bf16 v[128:131], v[152:155], v[192:195], v[128:131]
	v_mfma_f32_16x16x32_bf16 v[124:127], v[156:159], v[188:191], v[124:127]
	v_mfma_f32_16x16x32_bf16 v[124:127], v[160:163], v[192:195], v[124:127]
	v_mfma_f32_16x16x32_bf16 v[120:123], v[148:151], v[180:183], v[120:123]
	v_mfma_f32_16x16x32_bf16 v[120:123], v[152:155], v[184:187], v[120:123]
	v_mfma_f32_16x16x32_bf16 v[116:119], v[156:159], v[180:183], v[116:119]
	v_mfma_f32_16x16x32_bf16 v[116:119], v[160:163], v[184:187], v[116:119]
	v_mfma_f32_16x16x32_bf16 v[112:115], v[148:151], v[172:175], v[112:115]
	v_mfma_f32_16x16x32_bf16 v[112:115], v[152:155], v[176:179], v[112:115]
	v_mfma_f32_16x16x32_bf16 v[108:111], v[156:159], v[172:175], v[108:111]
	v_mfma_f32_16x16x32_bf16 v[108:111], v[160:163], v[176:179], v[108:111]
	v_mfma_f32_16x16x32_bf16 v[104:107], v[148:151], v[164:167], v[104:107]
	v_mfma_f32_16x16x32_bf16 v[104:107], v[152:155], v[168:171], v[104:107]
	v_mfma_f32_16x16x32_bf16 v[100:103], v[156:159], v[164:167], v[100:103]
	v_mfma_f32_16x16x32_bf16 v[100:103], v[160:163], v[168:171], v[100:103]
	s_cbranch_execnz .LBB0_764

.LBB0_767:
	s_cmp_eq_u32 s73, s80
	s_cselect_b64 s[30:31], -1, 0
	s_and_b64 s[8:9], s[30:31], exec
	s_cselect_b32 s29, s41, s77
	s_cselect_b32 s28, s40, s76
	s_setprio 0
	s_barrier
	s_mov_b32 m0, s57
	s_mov_b64 s[8:9], s[28:29]
	s_waitcnt lgkmcnt(0)
	ds_read_b128 v[188:191], v205 offset:16384
	ds_read_b128 v[192:195], v205 offset:17408
	ds_read_b128 v[180:183], v205 offset:18432
	ds_read_b128 v[184:187], v205 offset:19456
	ds_read_b128 v[172:175], v205 offset:20480
	ds_read_b128 v[176:179], v205 offset:21504
	ds_read_b128 v[164:167], v205 offset:22528
	ds_read_b128 v[168:171], v205 offset:23552
	s_nop 0
	global_load_lds_dwordx4 v200, s[8:9]
	s_mov_b32 m0, s58
	s_nop 0
	global_load_lds_dwordx4 v198, s[8:9]
	s_add_u32 s8, s28, s14
	s_addc_u32 s9, s29, s15
	s_mov_b32 m0, s59
	s_nop 0
	global_load_lds_dwordx4 v200, s[8:9]
	s_mov_b32 m0, s60
	s_nop 0
	global_load_lds_dwordx4 v198, s[8:9]
	s_waitcnt vmcnt(6)
	s_waitcnt lgkmcnt(0)
	s_barrier
	s_setprio 1
	s_and_b64 vcc, exec, s[26:27]
	s_cbranch_vccz .LBB0_774
	s_waitcnt lgkmcnt(0)
	v_mfma_f32_16x16x32_bf16 v[64:67], v[148:151], v[188:191], v[64:67]
	v_mfma_f32_16x16x32_bf16 v[64:67], v[152:155], v[192:195], v[64:67]
	v_mfma_f32_16x16x32_bf16 v[60:63], v[156:159], v[188:191], v[60:63]
	v_mfma_f32_16x16x32_bf16 v[60:63], v[160:163], v[192:195], v[60:63]
	v_mfma_f32_16x16x32_bf16 v[56:59], v[148:151], v[180:183], v[56:59]
	v_mfma_f32_16x16x32_bf16 v[56:59], v[152:155], v[184:187], v[56:59]
	v_mfma_f32_16x16x32_bf16 v[52:55], v[156:159], v[180:183], v[52:55]
	v_mfma_f32_16x16x32_bf16 v[52:55], v[160:163], v[184:187], v[52:55]
	v_mfma_f32_16x16x32_bf16 v[48:51], v[148:151], v[172:175], v[48:51]
	v_mfma_f32_16x16x32_bf16 v[48:51], v[152:155], v[176:179], v[48:51]
	v_mfma_f32_16x16x32_bf16 v[44:47], v[156:159], v[172:175], v[44:47]
	v_mfma_f32_16x16x32_bf16 v[44:47], v[160:163], v[176:179], v[44:47]
	v_mfma_f32_16x16x32_bf16 v[40:43], v[148:151], v[164:167], v[40:43]
	v_mfma_f32_16x16x32_bf16 v[40:43], v[152:155], v[168:171], v[40:43]
	v_mfma_f32_16x16x32_bf16 v[36:39], v[156:159], v[164:167], v[36:39]
	v_mfma_f32_16x16x32_bf16 v[36:39], v[160:163], v[168:171], v[36:39]
	s_cbranch_execnz .LBB0_770

.LBB0_853:
	s_add_u32 s16, s26, 0x100
	s_addc_u32 s17, s27, 0
	s_add_u32 s18, s20, 0x100
	s_addc_u32 s19, s21, 0
	s_and_b64 s[8:9], s[52:53], exec
	s_cselect_b32 s31, s41, s19
	s_cselect_b32 s30, s40, s18
	s_add_i32 s84, 0, 0x10000
	s_and_b64 s[8:9], s[52:53], exec
	s_cselect_b32 s19, s59, s17
	s_cselect_b32 s18, s58, s16
	s_add_i32 s86, 0, 0x14000
	v_add_u32_e32 v132, s84, v245
	v_add_u32_e32 v133, s86, v245
	ds_read_b128 v[4:7], v132
	ds_read_b128 v[8:11], v132 offset:1024
	ds_read_b128 v[12:15], v132 offset:2048
	ds_read_b128 v[16:19], v132 offset:3072
	ds_read_b128 v[20:23], v133
	ds_read_b128 v[24:27], v133 offset:1024
	ds_read_b128 v[28:31], v133 offset:2048
	ds_read_b128 v[32:35], v133 offset:3072
	s_add_u32 s8, s26, 0x80
	s_addc_u32 s9, s27, 0
	s_add_i32 s80, s7, 0x8000
	s_add_i32 s81, s7, 0xa000
	s_mov_b64 s[16:17], s[8:9]
	s_mov_b32 m0, s80
	s_add_u32 s8, s8, s42
	ds_read_b128 v[36:39], v246 offset:8192
	ds_read_b128 v[40:43], v246 offset:9216
	ds_read_b128 v[44:47], v246 offset:10240
	ds_read_b128 v[48:51], v246 offset:11264
	ds_read_b128 v[52:55], v246 offset:12288
	ds_read_b128 v[56:59], v246 offset:13312
	ds_read_b128 v[60:63], v246 offset:14336
	ds_read_b128 v[64:67], v246 offset:15360
	s_addc_u32 s9, s9, s43
	global_load_lds_dwordx4 v242, s[16:17]
	s_mov_b32 m0, s81
	s_add_i32 s82, s7, 0xc000
	global_load_lds_dwordx4 v2, s[16:17]
	s_mov_b32 m0, s82
	s_add_i32 s83, s7, 0xe000
	s_add_u32 s28, s30, 0x80
	global_load_lds_dwordx4 v242, s[8:9]
	s_mov_b32 m0, s83
	s_addc_u32 s29, s31, 0
	global_load_lds_dwordx4 v2, s[8:9]
	s_waitcnt vmcnt(8)
	s_waitcnt lgkmcnt(0)
	s_barrier
	s_setprio 1
	s_waitcnt lgkmcnt(0)
	v_mfma_f32_16x16x32_bf16 v[68:71], v[4:7], v[36:39], 0
	v_mfma_f32_16x16x32_bf16 v[72:75], v[12:15], v[36:39], 0
	v_mfma_f32_16x16x32_bf16 v[76:79], v[4:7], v[44:47], 0
	v_mfma_f32_16x16x32_bf16 v[80:83], v[12:15], v[44:47], 0
	v_mfma_f32_16x16x32_bf16 v[84:87], v[4:7], v[52:55], 0
	v_mfma_f32_16x16x32_bf16 v[88:91], v[12:15], v[52:55], 0
	v_mfma_f32_16x16x32_bf16 v[92:95], v[4:7], v[60:63], 0
	v_mfma_f32_16x16x32_bf16 v[96:99], v[12:15], v[60:63], 0
	v_mfma_f32_16x16x32_bf16 v[68:71], v[8:11], v[40:43], v[68:71]
	v_mfma_f32_16x16x32_bf16 v[72:75], v[16:19], v[40:43], v[72:75]
	v_mfma_f32_16x16x32_bf16 v[76:79], v[8:11], v[48:51], v[76:79]
	v_mfma_f32_16x16x32_bf16 v[80:83], v[16:19], v[48:51], v[80:83]
	v_mfma_f32_16x16x32_bf16 v[84:87], v[8:11], v[56:59], v[84:87]
	v_mfma_f32_16x16x32_bf16 v[88:91], v[16:19], v[56:59], v[88:91]
	v_mfma_f32_16x16x32_bf16 v[92:95], v[8:11], v[64:67], v[92:95]
	v_mfma_f32_16x16x32_bf16 v[96:99], v[16:19], v[64:67], v[96:99]
	s_setprio 0
	s_setprio 1
	v_mfma_f32_16x16x32_bf16 v[100:103], v[20:23], v[36:39], 0
	v_mfma_f32_16x16x32_bf16 v[36:39], v[28:31], v[36:39], 0
	v_mfma_f32_16x16x32_bf16 v[100:103], v[24:27], v[40:43], v[100:103]
	v_mfma_f32_16x16x32_bf16 v[40:43], v[32:35], v[40:43], v[36:39]
	v_mfma_f32_16x16x32_bf16 v[36:39], v[20:23], v[44:47], 0
	v_mfma_f32_16x16x32_bf16 v[104:107], v[24:27], v[48:51], v[36:39]
	v_mfma_f32_16x16x32_bf16 v[36:39], v[28:31], v[44:47], 0
	v_mfma_f32_16x16x32_bf16 v[48:51], v[32:35], v[48:51], v[36:39]
	v_mfma_f32_16x16x32_bf16 v[36:39], v[20:23], v[52:55], 0
	v_mfma_f32_16x16x32_bf16 v[108:111], v[24:27], v[56:59], v[36:39]
	v_mfma_f32_16x16x32_bf16 v[36:39], v[28:31], v[52:55], 0
	v_mfma_f32_16x16x32_bf16 v[56:59], v[32:35], v[56:59], v[36:39]
	v_mfma_f32_16x16x32_bf16 v[36:39], v[20:23], v[60:63], 0
	v_mfma_f32_16x16x32_bf16 v[112:115], v[24:27], v[64:67], v[36:39]
	v_mfma_f32_16x16x32_bf16 v[36:39], v[28:31], v[60:63], 0
	v_mfma_f32_16x16x32_bf16 v[64:67], v[32:35], v[64:67], v[36:39]
	s_setprio 0
	s_barrier
	s_add_i32 s84, s84, s6
	s_mov_b64 s[8:9], s[30:31]
	s_mov_b32 m0, s84
	s_add_i32 s85, s84, 0x2000
	s_nop 0
	ds_read_b128 v[36:39], v246 offset:24576
	ds_read_b128 v[44:47], v246 offset:25600
	ds_read_b128 v[52:55], v246 offset:26624
	ds_read_b128 v[60:63], v246 offset:27648
	ds_read_b128 v[116:119], v246 offset:28672
	ds_read_b128 v[120:123], v246 offset:29696
	ds_read_b128 v[124:127], v246 offset:30720
	ds_read_b128 v[128:131], v246 offset:31744
	s_nop 0
	global_load_lds_dwordx4 v248, s[8:9]
	s_mov_b32 m0, s85
	s_nop 0
	global_load_lds_dwordx4 v247, s[8:9]
	s_add_u32 s8, s30, s42
	s_addc_u32 s9, s31, s43
	s_add_i32 s30, s86, s6
	s_mov_b32 m0, s30
	s_add_i32 s31, s30, 0x2000
	s_nop 0
	global_load_lds_dwordx4 v248, s[8:9]
	s_mov_b32 m0, s31
	s_nop 0
	global_load_lds_dwordx4 v247, s[8:9]
	s_waitcnt vmcnt(6)
	s_waitcnt lgkmcnt(0)
	s_barrier
	s_setprio 1
	s_waitcnt lgkmcnt(0)
	v_mfma_f32_16x16x32_bf16 v[134:137], v[4:7], v[36:39], 0
	v_mfma_f32_16x16x32_bf16 v[144:147], v[4:7], v[52:55], 0
	v_mfma_f32_16x16x32_bf16 v[152:155], v[4:7], v[116:119], 0
	v_mfma_f32_16x16x32_bf16 v[4:7], v[4:7], v[124:127], 0
	v_mfma_f32_16x16x32_bf16 v[140:143], v[12:15], v[36:39], 0
	v_mfma_f32_16x16x32_bf16 v[148:151], v[12:15], v[52:55], 0
	v_mfma_f32_16x16x32_bf16 v[156:159], v[12:15], v[116:119], 0
	v_mfma_f32_16x16x32_bf16 v[160:163], v[8:11], v[128:131], v[4:7]
	v_mfma_f32_16x16x32_bf16 v[4:7], v[12:15], v[124:127], 0
	v_mfma_f32_16x16x32_bf16 v[136:139], v[8:11], v[44:47], v[134:137]
	v_mfma_f32_16x16x32_bf16 v[140:143], v[16:19], v[44:47], v[140:143]
	v_mfma_f32_16x16x32_bf16 v[144:147], v[8:11], v[60:63], v[144:147]
	v_mfma_f32_16x16x32_bf16 v[148:151], v[16:19], v[60:63], v[148:151]
	v_mfma_f32_16x16x32_bf16 v[152:155], v[8:11], v[120:123], v[152:155]
	v_mfma_f32_16x16x32_bf16 v[156:159], v[16:19], v[120:123], v[156:159]
	v_mfma_f32_16x16x32_bf16 v[164:167], v[16:19], v[128:131], v[4:7]
	s_setprio 0
	s_setprio 1
	v_mfma_f32_16x16x32_bf16 v[4:7], v[20:23], v[36:39], 0
	v_mfma_f32_16x16x32_bf16 v[168:171], v[24:27], v[44:47], v[4:7]
	v_mfma_f32_16x16x32_bf16 v[4:7], v[28:31], v[36:39], 0
	v_mfma_f32_16x16x32_bf16 v[172:175], v[32:35], v[44:47], v[4:7]
	v_mfma_f32_16x16x32_bf16 v[4:7], v[20:23], v[52:55], 0
	v_mfma_f32_16x16x32_bf16 v[176:179], v[24:27], v[60:63], v[4:7]
	v_mfma_f32_16x16x32_bf16 v[4:7], v[28:31], v[52:55], 0
	v_mfma_f32_16x16x32_bf16 v[180:183], v[32:35], v[60:63], v[4:7]
	v_mfma_f32_16x16x32_bf16 v[4:7], v[20:23], v[116:119], 0
	v_mfma_f32_16x16x32_bf16 v[184:187], v[24:27], v[120:123], v[4:7]
	v_mfma_f32_16x16x32_bf16 v[4:7], v[28:31], v[116:119], 0
	v_mfma_f32_16x16x32_bf16 v[120:123], v[32:35], v[120:123], v[4:7]
	v_mfma_f32_16x16x32_bf16 v[4:7], v[20:23], v[124:127], 0
	v_mfma_f32_16x16x32_bf16 v[188:191], v[24:27], v[128:131], v[4:7]
	v_mfma_f32_16x16x32_bf16 v[4:7], v[28:31], v[124:127], 0
	v_mfma_f32_16x16x32_bf16 v[128:131], v[32:35], v[128:131], v[4:7]
	s_setprio 0
	s_barrier
	s_add_i32 s86, 0, 0x18000
	s_add_i32 s16, 0, 0x1c000
	v_add_u32_e32 v134, s86, v245
	v_add_u32_e32 v135, s16, v245
	ds_read_b128 v[116:119], v134
	ds_read_b128 v[124:127], v134 offset:1024
	ds_read_b128 v[192:195], v134 offset:2048
	ds_read_b128 v[196:199], v134 offset:3072
	ds_read_b128 v[200:203], v135
	ds_read_b128 v[204:207], v135 offset:1024
	ds_read_b128 v[216:219], v135 offset:2048
	ds_read_b128 v[220:223], v135 offset:3072
	s_mov_b32 m0, s7
	s_mov_b64 s[8:9], s[18:19]
	ds_read_b128 v[44:47], v246 offset:40960
	ds_read_b128 v[52:55], v246 offset:41984
	ds_read_b128 v[60:63], v246 offset:43008
	ds_read_b128 v[224:227], v246 offset:44032
	ds_read_b128 v[228:231], v246 offset:45056
	ds_read_b128 v[232:235], v246 offset:46080
	ds_read_b128 v[236:239], v246 offset:47104
	ds_read_b128 v[250:253], v246 offset:48128
	s_nop 0
	global_load_lds_dwordx4 v242, s[8:9]
	s_mov_b32 m0, s69
	s_nop 0
	global_load_lds_dwordx4 v2, s[8:9]
	s_add_u32 s8, s18, s42
	s_addc_u32 s9, s19, s43
	s_mov_b32 m0, s72
	s_nop 0
	global_load_lds_dwordx4 v242, s[8:9]
	s_mov_b32 m0, s73
	s_nop 0
	global_load_lds_dwordx4 v2, s[8:9]
	s_waitcnt vmcnt(8)
	s_waitcnt lgkmcnt(0)
	s_barrier
	s_setprio 1
	s_waitcnt lgkmcnt(0)
	v_mfma_f32_16x16x32_bf16 v[4:7], v[116:119], v[44:47], v[68:71]
	v_mfma_f32_16x16x32_bf16 v[4:7], v[124:127], v[52:55], v[4:7]
	v_mfma_f32_16x16x32_bf16 v[8:11], v[192:195], v[44:47], v[72:75]
	v_mfma_f32_16x16x32_bf16 v[8:11], v[196:199], v[52:55], v[8:11]
	v_mfma_f32_16x16x32_bf16 v[12:15], v[116:119], v[60:63], v[76:79]
	v_mfma_f32_16x16x32_bf16 v[12:15], v[124:127], v[224:227], v[12:15]
	v_mfma_f32_16x16x32_bf16 v[16:19], v[192:195], v[60:63], v[80:83]
	v_mfma_f32_16x16x32_bf16 v[16:19], v[196:199], v[224:227], v[16:19]
	v_mfma_f32_16x16x32_bf16 v[20:23], v[116:119], v[228:231], v[84:87]
	v_mfma_f32_16x16x32_bf16 v[20:23], v[124:127], v[232:235], v[20:23]
	v_mfma_f32_16x16x32_bf16 v[24:27], v[192:195], v[228:231], v[88:91]
	v_mfma_f32_16x16x32_bf16 v[24:27], v[196:199], v[232:235], v[24:27]
	v_mfma_f32_16x16x32_bf16 v[28:31], v[116:119], v[236:239], v[92:95]
	v_mfma_f32_16x16x32_bf16 v[28:31], v[124:127], v[250:253], v[28:31]
	v_mfma_f32_16x16x32_bf16 v[32:35], v[192:195], v[236:239], v[96:99]
	v_mfma_f32_16x16x32_bf16 v[32:35], v[196:199], v[250:253], v[32:35]
	s_setprio 0
	s_setprio 1
	v_mfma_f32_16x16x32_bf16 v[36:39], v[200:203], v[44:47], v[100:103]
	v_mfma_f32_16x16x32_bf16 v[40:43], v[216:219], v[44:47], v[40:43]
	v_mfma_f32_16x16x32_bf16 v[36:39], v[204:207], v[52:55], v[36:39]
	v_mfma_f32_16x16x32_bf16 v[40:43], v[220:223], v[52:55], v[40:43]
	v_mfma_f32_16x16x32_bf16 v[44:47], v[200:203], v[60:63], v[104:107]
	v_mfma_f32_16x16x32_bf16 v[48:51], v[216:219], v[60:63], v[48:51]
	v_mfma_f32_16x16x32_bf16 v[52:55], v[200:203], v[228:231], v[108:111]
	v_mfma_f32_16x16x32_bf16 v[56:59], v[216:219], v[228:231], v[56:59]
	v_mfma_f32_16x16x32_bf16 v[60:63], v[200:203], v[236:239], v[112:115]
	v_mfma_f32_16x16x32_bf16 v[64:67], v[216:219], v[236:239], v[64:67]
	v_mfma_f32_16x16x32_bf16 v[44:47], v[204:207], v[224:227], v[44:47]
	v_mfma_f32_16x16x32_bf16 v[48:51], v[220:223], v[224:227], v[48:51]
	v_mfma_f32_16x16x32_bf16 v[52:55], v[204:207], v[232:235], v[52:55]
	v_mfma_f32_16x16x32_bf16 v[56:59], v[220:223], v[232:235], v[56:59]
	v_mfma_f32_16x16x32_bf16 v[60:63], v[204:207], v[250:253], v[60:63]
	v_mfma_f32_16x16x32_bf16 v[64:67], v[220:223], v[250:253], v[64:67]
	s_setprio 0
	s_barrier
	s_add_i32 s86, s86, s6
	s_mov_b64 s[8:9], s[28:29]
	s_mov_b32 m0, s86
	s_add_i32 s87, s86, 0x2000
	ds_read_b128 v[104:107], v246 offset:57344
	ds_read_b128 v[108:111], v246 offset:58368
	ds_read_b128 v[112:115], v246 offset:59392
	ds_read_b128 v[224:227], v246 offset:60416
	ds_read_b128 v[228:231], v246 offset:61440
	ds_read_b128 v[232:235], v246 offset:62464
	ds_read_b128 v[236:239], v246 offset:63488
	ds_read_b128 v[250:253], v246 offset:64512
	s_nop 0
	global_load_lds_dwordx4 v248, s[8:9]
	s_mov_b32 m0, s87
	s_nop 0
	global_load_lds_dwordx4 v247, s[8:9]
	s_add_u32 s8, s28, s42
	s_addc_u32 s9, s29, s43
	s_add_i32 s28, s16, s6
	s_mov_b32 m0, s28
	s_add_i32 s29, s28, 0x2000
	s_nop 0
	global_load_lds_dwordx4 v248, s[8:9]
	s_mov_b32 m0, s29
	s_nop 0
	global_load_lds_dwordx4 v247, s[8:9]
	s_waitcnt vmcnt(6)
	s_waitcnt lgkmcnt(0)
	s_barrier
	s_setprio 1
	s_waitcnt lgkmcnt(0)
	v_mfma_f32_16x16x32_bf16 v[68:71], v[116:119], v[104:107], v[136:139]
	v_mfma_f32_16x16x32_bf16 v[68:71], v[124:127], v[108:111], v[68:71]
	v_mfma_f32_16x16x32_bf16 v[72:75], v[192:195], v[104:107], v[140:143]
	v_mfma_f32_16x16x32_bf16 v[72:75], v[196:199], v[108:111], v[72:75]
	v_mfma_f32_16x16x32_bf16 v[76:79], v[116:119], v[112:115], v[144:147]
	v_mfma_f32_16x16x32_bf16 v[76:79], v[124:127], v[224:227], v[76:79]
	v_mfma_f32_16x16x32_bf16 v[80:83], v[192:195], v[112:115], v[148:151]
	v_mfma_f32_16x16x32_bf16 v[80:83], v[196:199], v[224:227], v[80:83]
	v_mfma_f32_16x16x32_bf16 v[84:87], v[116:119], v[228:231], v[152:155]
	v_mfma_f32_16x16x32_bf16 v[84:87], v[124:127], v[232:235], v[84:87]
	v_mfma_f32_16x16x32_bf16 v[88:91], v[192:195], v[228:231], v[156:159]
	v_mfma_f32_16x16x32_bf16 v[88:91], v[196:199], v[232:235], v[88:91]
	v_mfma_f32_16x16x32_bf16 v[92:95], v[116:119], v[236:239], v[160:163]
	v_mfma_f32_16x16x32_bf16 v[92:95], v[124:127], v[250:253], v[92:95]
	v_mfma_f32_16x16x32_bf16 v[96:99], v[192:195], v[236:239], v[164:167]
	v_mfma_f32_16x16x32_bf16 v[96:99], v[196:199], v[250:253], v[96:99]
	s_setprio 0
	s_setprio 1
	v_mfma_f32_16x16x32_bf16 v[100:103], v[200:203], v[104:107], v[168:171]
	v_mfma_f32_16x16x32_bf16 v[104:107], v[216:219], v[104:107], v[172:175]
	v_mfma_f32_16x16x32_bf16 v[100:103], v[204:207], v[108:111], v[100:103]
	v_mfma_f32_16x16x32_bf16 v[104:107], v[220:223], v[108:111], v[104:107]
	v_mfma_f32_16x16x32_bf16 v[108:111], v[200:203], v[112:115], v[176:179]
	v_mfma_f32_16x16x32_bf16 v[112:115], v[216:219], v[112:115], v[180:183]
	v_mfma_f32_16x16x32_bf16 v[116:119], v[200:203], v[228:231], v[184:187]
	v_mfma_f32_16x16x32_bf16 v[120:123], v[216:219], v[228:231], v[120:123]
	v_mfma_f32_16x16x32_bf16 v[124:127], v[200:203], v[236:239], v[188:191]
	v_mfma_f32_16x16x32_bf16 v[128:131], v[216:219], v[236:239], v[128:131]
	v_mfma_f32_16x16x32_bf16 v[108:111], v[204:207], v[224:227], v[108:111]
	v_mfma_f32_16x16x32_bf16 v[112:115], v[220:223], v[224:227], v[112:115]
	v_mfma_f32_16x16x32_bf16 v[116:119], v[204:207], v[232:235], v[116:119]
	v_mfma_f32_16x16x32_bf16 v[120:123], v[220:223], v[232:235], v[120:123]
	v_mfma_f32_16x16x32_bf16 v[124:127], v[204:207], v[250:253], v[124:127]
	v_mfma_f32_16x16x32_bf16 v[128:131], v[220:223], v[250:253], v[128:131]
	s_setprio 0
	s_barrier
	s_andn2_b64 vcc, exec, s[54:55]
	s_cbranch_vccnz .LBB0_857
	s_add_u32 s88, s20, 0x200
	s_addc_u32 s89, s21, 0
	s_add_u32 s26, s26, 0x200
	s_addc_u32 s27, s27, 0
	s_mov_b32 s90, 4
.LBB0_855:
	ds_read_b128 v[136:139], v132
	ds_read_b128 v[140:143], v132 offset:1024
	ds_read_b128 v[144:147], v132 offset:2048
	ds_read_b128 v[148:151], v132 offset:3072
	ds_read_b128 v[152:155], v133
	ds_read_b128 v[156:159], v133 offset:1024
	ds_read_b128 v[160:163], v133 offset:2048
	ds_read_b128 v[164:167], v133 offset:3072
	s_cmp_eq_u32 s4, s90
	s_cselect_b32 s17, s41, s89
	s_cselect_b32 s16, s40, s88
	s_cselect_b32 s21, s59, s27
	s_cselect_b32 s20, s58, s26
	s_add_u32 s8, s26, 0xffffff80
	s_addc_u32 s9, s27, -1
	s_mov_b32 m0, s80
	s_mov_b64 s[18:19], s[8:9]
	ds_read_b128 v[168:171], v246 offset:8192
	ds_read_b128 v[172:175], v246 offset:9216
	ds_read_b128 v[176:179], v246 offset:10240
	ds_read_b128 v[180:183], v246 offset:11264
	ds_read_b128 v[184:187], v246 offset:12288
	ds_read_b128 v[188:191], v246 offset:13312
	ds_read_b128 v[192:195], v246 offset:14336
	ds_read_b128 v[196:199], v246 offset:15360
	s_add_u32 s8, s8, s42
	global_load_lds_dwordx4 v242, s[18:19]
	s_mov_b32 m0, s81
	s_addc_u32 s9, s9, s43
	global_load_lds_dwordx4 v2, s[18:19]
	s_mov_b32 m0, s82
	s_add_u32 s18, s16, 0x80
	global_load_lds_dwordx4 v242, s[8:9]
	s_mov_b32 m0, s83
	s_addc_u32 s19, s17, 0
	global_load_lds_dwordx4 v2, s[8:9]
	s_waitcnt vmcnt(8)
	s_waitcnt lgkmcnt(0)
	s_barrier
	s_setprio 1
	s_waitcnt lgkmcnt(0)
	v_mfma_f32_16x16x32_bf16 v[4:7], v[136:139], v[168:171], v[4:7]
	v_mfma_f32_16x16x32_bf16 v[4:7], v[140:143], v[172:175], v[4:7]
	v_mfma_f32_16x16x32_bf16 v[8:11], v[144:147], v[168:171], v[8:11]
	v_mfma_f32_16x16x32_bf16 v[8:11], v[148:151], v[172:175], v[8:11]
	v_mfma_f32_16x16x32_bf16 v[12:15], v[136:139], v[176:179], v[12:15]
	v_mfma_f32_16x16x32_bf16 v[12:15], v[140:143], v[180:183], v[12:15]
	v_mfma_f32_16x16x32_bf16 v[16:19], v[144:147], v[176:179], v[16:19]
	v_mfma_f32_16x16x32_bf16 v[16:19], v[148:151], v[180:183], v[16:19]
	v_mfma_f32_16x16x32_bf16 v[20:23], v[136:139], v[184:187], v[20:23]
	v_mfma_f32_16x16x32_bf16 v[20:23], v[140:143], v[188:191], v[20:23]
	v_mfma_f32_16x16x32_bf16 v[24:27], v[144:147], v[184:187], v[24:27]
	v_mfma_f32_16x16x32_bf16 v[24:27], v[148:151], v[188:191], v[24:27]
	v_mfma_f32_16x16x32_bf16 v[28:31], v[136:139], v[192:195], v[28:31]
	v_mfma_f32_16x16x32_bf16 v[28:31], v[140:143], v[196:199], v[28:31]
	v_mfma_f32_16x16x32_bf16 v[32:35], v[144:147], v[192:195], v[32:35]
	v_mfma_f32_16x16x32_bf16 v[32:35], v[148:151], v[196:199], v[32:35]
	s_setprio 0
	s_setprio 1
	v_mfma_f32_16x16x32_bf16 v[36:39], v[152:155], v[168:171], v[36:39]
	v_mfma_f32_16x16x32_bf16 v[36:39], v[156:159], v[172:175], v[36:39]
	v_mfma_f32_16x16x32_bf16 v[40:43], v[160:163], v[168:171], v[40:43]
	v_mfma_f32_16x16x32_bf16 v[40:43], v[164:167], v[172:175], v[40:43]
	v_mfma_f32_16x16x32_bf16 v[44:47], v[152:155], v[176:179], v[44:47]
	v_mfma_f32_16x16x32_bf16 v[44:47], v[156:159], v[180:183], v[44:47]
	v_mfma_f32_16x16x32_bf16 v[48:51], v[160:163], v[176:179], v[48:51]
	v_mfma_f32_16x16x32_bf16 v[48:51], v[164:167], v[180:183], v[48:51]
	v_mfma_f32_16x16x32_bf16 v[52:55], v[152:155], v[184:187], v[52:55]
	v_mfma_f32_16x16x32_bf16 v[52:55], v[156:159], v[188:191], v[52:55]
	v_mfma_f32_16x16x32_bf16 v[56:59], v[160:163], v[184:187], v[56:59]
	v_mfma_f32_16x16x32_bf16 v[56:59], v[164:167], v[188:191], v[56:59]
	v_mfma_f32_16x16x32_bf16 v[60:63], v[152:155], v[192:195], v[60:63]
	v_mfma_f32_16x16x32_bf16 v[60:63], v[156:159], v[196:199], v[60:63]
	v_mfma_f32_16x16x32_bf16 v[64:67], v[160:163], v[192:195], v[64:67]
	v_mfma_f32_16x16x32_bf16 v[64:67], v[164:167], v[196:199], v[64:67]
	s_setprio 0
	s_barrier
	s_mov_b32 m0, s84
	s_mov_b64 s[8:9], s[16:17]
	ds_read_b128 v[168:171], v246 offset:24576
	ds_read_b128 v[172:175], v246 offset:25600
	ds_read_b128 v[176:179], v246 offset:26624
	ds_read_b128 v[180:183], v246 offset:27648
	ds_read_b128 v[184:187], v246 offset:28672
	ds_read_b128 v[188:191], v246 offset:29696
	ds_read_b128 v[192:195], v246 offset:30720
	ds_read_b128 v[196:199], v246 offset:31744
	s_nop 0
	global_load_lds_dwordx4 v248, s[8:9]
	s_mov_b32 m0, s85
	s_nop 0
	global_load_lds_dwordx4 v247, s[8:9]
	s_add_u32 s8, s16, s42
	s_addc_u32 s9, s17, s43
	s_mov_b32 m0, s30
	s_nop 0
	global_load_lds_dwordx4 v248, s[8:9]
	s_mov_b32 m0, s31
	s_nop 0
	global_load_lds_dwordx4 v247, s[8:9]
	s_waitcnt vmcnt(6)
	s_waitcnt lgkmcnt(0)
	s_barrier
	s_setprio 1
	s_waitcnt lgkmcnt(0)
	v_mfma_f32_16x16x32_bf16 v[68:71], v[136:139], v[168:171], v[68:71]
	v_mfma_f32_16x16x32_bf16 v[68:71], v[140:143], v[172:175], v[68:71]
	v_mfma_f32_16x16x32_bf16 v[72:75], v[144:147], v[168:171], v[72:75]
	v_mfma_f32_16x16x32_bf16 v[72:75], v[148:151], v[172:175], v[72:75]
	v_mfma_f32_16x16x32_bf16 v[76:79], v[136:139], v[176:179], v[76:79]
	v_mfma_f32_16x16x32_bf16 v[76:79], v[140:143], v[180:183], v[76:79]
	v_mfma_f32_16x16x32_bf16 v[80:83], v[144:147], v[176:179], v[80:83]
	v_mfma_f32_16x16x32_bf16 v[80:83], v[148:151], v[180:183], v[80:83]
	v_mfma_f32_16x16x32_bf16 v[84:87], v[136:139], v[184:187], v[84:87]
	v_mfma_f32_16x16x32_bf16 v[84:87], v[140:143], v[188:191], v[84:87]
	v_mfma_f32_16x16x32_bf16 v[88:91], v[144:147], v[184:187], v[88:91]
	v_mfma_f32_16x16x32_bf16 v[88:91], v[148:151], v[188:191], v[88:91]
	v_mfma_f32_16x16x32_bf16 v[92:95], v[136:139], v[192:195], v[92:95]
	v_mfma_f32_16x16x32_bf16 v[92:95], v[140:143], v[196:199], v[92:95]
	v_mfma_f32_16x16x32_bf16 v[96:99], v[144:147], v[192:195], v[96:99]
	v_mfma_f32_16x16x32_bf16 v[96:99], v[148:151], v[196:199], v[96:99]
	s_setprio 0
	s_setprio 1
	v_mfma_f32_16x16x32_bf16 v[100:103], v[152:155], v[168:171], v[100:103]
	v_mfma_f32_16x16x32_bf16 v[100:103], v[156:159], v[172:175], v[100:103]
	v_mfma_f32_16x16x32_bf16 v[104:107], v[160:163], v[168:171], v[104:107]
	v_mfma_f32_16x16x32_bf16 v[104:107], v[164:167], v[172:175], v[104:107]
	v_mfma_f32_16x16x32_bf16 v[108:111], v[152:155], v[176:179], v[108:111]
	v_mfma_f32_16x16x32_bf16 v[108:111], v[156:159], v[180:183], v[108:111]
	v_mfma_f32_16x16x32_bf16 v[112:115], v[160:163], v[176:179], v[112:115]
	v_mfma_f32_16x16x32_bf16 v[112:115], v[164:167], v[180:183], v[112:115]
	v_mfma_f32_16x16x32_bf16 v[116:119], v[152:155], v[184:187], v[116:119]
	v_mfma_f32_16x16x32_bf16 v[116:119], v[156:159], v[188:191], v[116:119]
	v_mfma_f32_16x16x32_bf16 v[120:123], v[160:163], v[184:187], v[120:123]
	v_mfma_f32_16x16x32_bf16 v[120:123], v[164:167], v[188:191], v[120:123]
	v_mfma_f32_16x16x32_bf16 v[124:127], v[152:155], v[192:195], v[124:127]
	v_mfma_f32_16x16x32_bf16 v[124:127], v[156:159], v[196:199], v[124:127]
	v_mfma_f32_16x16x32_bf16 v[128:131], v[160:163], v[192:195], v[128:131]
	v_mfma_f32_16x16x32_bf16 v[128:131], v[164:167], v[196:199], v[128:131]
	s_setprio 0
	s_barrier
	ds_read_b128 v[136:139], v134
	ds_read_b128 v[140:143], v134 offset:1024
	ds_read_b128 v[144:147], v134 offset:2048
	ds_read_b128 v[148:151], v134 offset:3072
	ds_read_b128 v[152:155], v135
	ds_read_b128 v[156:159], v135 offset:1024
	ds_read_b128 v[160:163], v135 offset:2048
	ds_read_b128 v[164:167], v135 offset:3072
	s_mov_b32 m0, s7
	s_mov_b64 s[8:9], s[20:21]
	ds_read_b128 v[168:171], v246 offset:40960
	ds_read_b128 v[172:175], v246 offset:41984
	ds_read_b128 v[176:179], v246 offset:43008
	ds_read_b128 v[180:183], v246 offset:44032
	ds_read_b128 v[184:187], v246 offset:45056
	ds_read_b128 v[188:191], v246 offset:46080
	ds_read_b128 v[192:195], v246 offset:47104
	ds_read_b128 v[196:199], v246 offset:48128
	s_nop 0
	global_load_lds_dwordx4 v242, s[8:9]
	s_mov_b32 m0, s69
	s_nop 0
	global_load_lds_dwordx4 v2, s[8:9]
	s_add_u32 s8, s20, s42
	s_addc_u32 s9, s21, s43
	s_mov_b32 m0, s72
	s_nop 0
	global_load_lds_dwordx4 v242, s[8:9]
	s_mov_b32 m0, s73
	s_nop 0
	global_load_lds_dwordx4 v2, s[8:9]
	s_waitcnt vmcnt(8)
	s_waitcnt lgkmcnt(0)
	s_barrier
	s_setprio 1
	s_waitcnt lgkmcnt(0)
	v_mfma_f32_16x16x32_bf16 v[4:7], v[136:139], v[168:171], v[4:7]
	v_mfma_f32_16x16x32_bf16 v[4:7], v[140:143], v[172:175], v[4:7]
	v_mfma_f32_16x16x32_bf16 v[8:11], v[144:147], v[168:171], v[8:11]
	v_mfma_f32_16x16x32_bf16 v[8:11], v[148:151], v[172:175], v[8:11]
	v_mfma_f32_16x16x32_bf16 v[12:15], v[136:139], v[176:179], v[12:15]
	v_mfma_f32_16x16x32_bf16 v[12:15], v[140:143], v[180:183], v[12:15]
	v_mfma_f32_16x16x32_bf16 v[16:19], v[144:147], v[176:179], v[16:19]
	v_mfma_f32_16x16x32_bf16 v[16:19], v[148:151], v[180:183], v[16:19]
	v_mfma_f32_16x16x32_bf16 v[20:23], v[136:139], v[184:187], v[20:23]
	v_mfma_f32_16x16x32_bf16 v[20:23], v[140:143], v[188:191], v[20:23]
	v_mfma_f32_16x16x32_bf16 v[24:27], v[144:147], v[184:187], v[24:27]
	v_mfma_f32_16x16x32_bf16 v[24:27], v[148:151], v[188:191], v[24:27]
	v_mfma_f32_16x16x32_bf16 v[28:31], v[136:139], v[192:195], v[28:31]
	v_mfma_f32_16x16x32_bf16 v[28:31], v[140:143], v[196:199], v[28:31]
	v_mfma_f32_16x16x32_bf16 v[32:35], v[144:147], v[192:195], v[32:35]
	v_mfma_f32_16x16x32_bf16 v[32:35], v[148:151], v[196:199], v[32:35]
	s_setprio 0
	s_setprio 1
	v_mfma_f32_16x16x32_bf16 v[36:39], v[152:155], v[168:171], v[36:39]
	v_mfma_f32_16x16x32_bf16 v[36:39], v[156:159], v[172:175], v[36:39]
	v_mfma_f32_16x16x32_bf16 v[40:43], v[160:163], v[168:171], v[40:43]
	v_mfma_f32_16x16x32_bf16 v[40:43], v[164:167], v[172:175], v[40:43]
	v_mfma_f32_16x16x32_bf16 v[44:47], v[152:155], v[176:179], v[44:47]
	v_mfma_f32_16x16x32_bf16 v[44:47], v[156:159], v[180:183], v[44:47]
	v_mfma_f32_16x16x32_bf16 v[48:51], v[160:163], v[176:179], v[48:51]
	v_mfma_f32_16x16x32_bf16 v[48:51], v[164:167], v[180:183], v[48:51]
	v_mfma_f32_16x16x32_bf16 v[52:55], v[152:155], v[184:187], v[52:55]
	v_mfma_f32_16x16x32_bf16 v[52:55], v[156:159], v[188:191], v[52:55]
	v_mfma_f32_16x16x32_bf16 v[56:59], v[160:163], v[184:187], v[56:59]
	v_mfma_f32_16x16x32_bf16 v[56:59], v[164:167], v[188:191], v[56:59]
	v_mfma_f32_16x16x32_bf16 v[60:63], v[152:155], v[192:195], v[60:63]
	v_mfma_f32_16x16x32_bf16 v[60:63], v[156:159], v[196:199], v[60:63]
	v_mfma_f32_16x16x32_bf16 v[64:67], v[160:163], v[192:195], v[64:67]
	v_mfma_f32_16x16x32_bf16 v[64:67], v[164:167], v[196:199], v[64:67]
	s_setprio 0
	s_barrier
	s_mov_b32 m0, s86
	s_mov_b64 s[8:9], s[18:19]
	ds_read_b128 v[168:171], v246 offset:57344
	ds_read_b128 v[172:175], v246 offset:58368
	ds_read_b128 v[176:179], v246 offset:59392
	ds_read_b128 v[180:183], v246 offset:60416
	ds_read_b128 v[184:187], v246 offset:61440
	ds_read_b128 v[188:191], v246 offset:62464
	ds_read_b128 v[192:195], v246 offset:63488
	ds_read_b128 v[196:199], v246 offset:64512
	s_nop 0
	global_load_lds_dwordx4 v248, s[8:9]
	s_mov_b32 m0, s87
	s_nop 0
	global_load_lds_dwordx4 v247, s[8:9]
	s_add_u32 s8, s18, s42
	s_addc_u32 s9, s19, s43
	s_mov_b32 m0, s28
	s_nop 0
	global_load_lds_dwordx4 v248, s[8:9]
	s_mov_b32 m0, s29
	s_nop 0
	global_load_lds_dwordx4 v247, s[8:9]
	s_waitcnt vmcnt(6)
	s_waitcnt lgkmcnt(0)
	s_barrier
	s_setprio 1
	s_waitcnt lgkmcnt(0)
	v_mfma_f32_16x16x32_bf16 v[68:71], v[136:139], v[168:171], v[68:71]
	v_mfma_f32_16x16x32_bf16 v[68:71], v[140:143], v[172:175], v[68:71]
	v_mfma_f32_16x16x32_bf16 v[72:75], v[144:147], v[168:171], v[72:75]
	v_mfma_f32_16x16x32_bf16 v[72:75], v[148:151], v[172:175], v[72:75]
	v_mfma_f32_16x16x32_bf16 v[76:79], v[136:139], v[176:179], v[76:79]
	v_mfma_f32_16x16x32_bf16 v[76:79], v[140:143], v[180:183], v[76:79]
	v_mfma_f32_16x16x32_bf16 v[80:83], v[144:147], v[176:179], v[80:83]
	v_mfma_f32_16x16x32_bf16 v[80:83], v[148:151], v[180:183], v[80:83]
	v_mfma_f32_16x16x32_bf16 v[84:87], v[136:139], v[184:187], v[84:87]
	v_mfma_f32_16x16x32_bf16 v[84:87], v[140:143], v[188:191], v[84:87]
	v_mfma_f32_16x16x32_bf16 v[88:91], v[144:147], v[184:187], v[88:91]
	v_mfma_f32_16x16x32_bf16 v[88:91], v[148:151], v[188:191], v[88:91]
	v_mfma_f32_16x16x32_bf16 v[92:95], v[136:139], v[192:195], v[92:95]
	v_mfma_f32_16x16x32_bf16 v[92:95], v[140:143], v[196:199], v[92:95]
	v_mfma_f32_16x16x32_bf16 v[96:99], v[144:147], v[192:195], v[96:99]
	v_mfma_f32_16x16x32_bf16 v[96:99], v[148:151], v[196:199], v[96:99]
	s_setprio 0
	s_setprio 1
	v_mfma_f32_16x16x32_bf16 v[100:103], v[152:155], v[168:171], v[100:103]
	v_mfma_f32_16x16x32_bf16 v[100:103], v[156:159], v[172:175], v[100:103]
	v_mfma_f32_16x16x32_bf16 v[104:107], v[160:163], v[168:171], v[104:107]
	v_mfma_f32_16x16x32_bf16 v[104:107], v[164:167], v[172:175], v[104:107]
	v_mfma_f32_16x16x32_bf16 v[108:111], v[152:155], v[176:179], v[108:111]
	v_mfma_f32_16x16x32_bf16 v[108:111], v[156:159], v[180:183], v[108:111]
	v_mfma_f32_16x16x32_bf16 v[112:115], v[160:163], v[176:179], v[112:115]
	v_mfma_f32_16x16x32_bf16 v[112:115], v[164:167], v[180:183], v[112:115]
	v_mfma_f32_16x16x32_bf16 v[116:119], v[152:155], v[184:187], v[116:119]
	v_mfma_f32_16x16x32_bf16 v[116:119], v[156:159], v[188:191], v[116:119]
	v_mfma_f32_16x16x32_bf16 v[120:123], v[160:163], v[184:187], v[120:123]
	v_mfma_f32_16x16x32_bf16 v[120:123], v[164:167], v[188:191], v[120:123]
	v_mfma_f32_16x16x32_bf16 v[124:127], v[152:155], v[192:195], v[124:127]
	v_mfma_f32_16x16x32_bf16 v[124:127], v[156:159], v[196:199], v[124:127]
	v_mfma_f32_16x16x32_bf16 v[128:131], v[160:163], v[192:195], v[128:131]
	v_mfma_f32_16x16x32_bf16 v[128:131], v[164:167], v[196:199], v[128:131]
	s_setprio 0
	s_barrier
	s_add_i32 s8, s90, 2
	s_add_u32 s88, s88, 0x100
	s_addc_u32 s89, s89, 0
	s_add_u32 s26, s26, 0x100
	s_addc_u32 s27, s27, 0
	s_cmp_ge_i32 s90, s4
	s_mov_b32 s90, s8
	s_cbranch_scc0 .LBB0_855
	v_readlane_b32 s90, v255, 45
	v_readlane_b32 s91, v255, 46
	s_movk_i32 s89, 0x61

.LBB0_878:
	s_add_u32 s16, s26, 0x100
	s_addc_u32 s17, s27, 0
	s_add_u32 s18, s20, 0x100
	s_addc_u32 s19, s21, 0
	s_and_b64 s[8:9], s[54:55], exec
	s_cselect_b32 s31, s43, s19
	s_cselect_b32 s30, s42, s18
	s_add_i32 s82, 0, 0x10000
	s_and_b64 s[8:9], s[54:55], exec
	s_cselect_b32 s19, s41, s17
	s_cselect_b32 s18, s40, s16
	s_add_i32 s84, 0, 0x14000
	v_add_u32_e32 v132, s82, v245
	v_add_u32_e32 v133, s84, v245
	ds_read_b128 v[4:7], v132
	ds_read_b128 v[8:11], v132 offset:1024
	ds_read_b128 v[12:15], v132 offset:2048
	ds_read_b128 v[16:19], v132 offset:3072
	ds_read_b128 v[20:23], v133
	ds_read_b128 v[24:27], v133 offset:1024
	ds_read_b128 v[28:31], v133 offset:2048
	ds_read_b128 v[32:35], v133 offset:3072
	s_add_u32 s8, s26, 0x80
	s_addc_u32 s9, s27, 0
	s_add_i32 s78, s7, 0x8000
	s_add_i32 s79, s7, 0xa000
	s_mov_b64 s[16:17], s[8:9]
	s_mov_b32 m0, s78
	s_add_u32 s8, s8, s46
	ds_read_b128 v[36:39], v246
	ds_read_b128 v[40:43], v246 offset:1024
	ds_read_b128 v[44:47], v246 offset:2048
	ds_read_b128 v[48:51], v246 offset:3072
	ds_read_b128 v[52:55], v246 offset:4096
	ds_read_b128 v[56:59], v246 offset:5120
	ds_read_b128 v[60:63], v246 offset:6144
	ds_read_b128 v[64:67], v246 offset:7168
	s_addc_u32 s9, s9, s47
	global_load_lds_dwordx4 v242, s[16:17]
	s_mov_b32 m0, s79
	s_add_i32 s80, s7, 0xc000
	global_load_lds_dwordx4 v2, s[16:17]
	s_mov_b32 m0, s80
	s_add_i32 s81, s7, 0xe000
	s_add_u32 s28, s30, 0x80
	global_load_lds_dwordx4 v242, s[8:9]
	s_mov_b32 m0, s81
	s_addc_u32 s29, s31, 0
	global_load_lds_dwordx4 v2, s[8:9]
	s_waitcnt vmcnt(8)
	s_waitcnt lgkmcnt(0)
	s_barrier
	s_setprio 1
	s_waitcnt lgkmcnt(0)
	v_mfma_f32_16x16x32_bf16 v[68:71], v[4:7], v[36:39], 0
	v_mfma_f32_16x16x32_bf16 v[72:75], v[12:15], v[36:39], 0
	v_mfma_f32_16x16x32_bf16 v[76:79], v[4:7], v[44:47], 0
	v_mfma_f32_16x16x32_bf16 v[80:83], v[12:15], v[44:47], 0
	v_mfma_f32_16x16x32_bf16 v[84:87], v[4:7], v[52:55], 0
	v_mfma_f32_16x16x32_bf16 v[88:91], v[12:15], v[52:55], 0
	v_mfma_f32_16x16x32_bf16 v[92:95], v[4:7], v[60:63], 0
	v_mfma_f32_16x16x32_bf16 v[96:99], v[12:15], v[60:63], 0
	v_mfma_f32_16x16x32_bf16 v[68:71], v[8:11], v[40:43], v[68:71]
	v_mfma_f32_16x16x32_bf16 v[72:75], v[16:19], v[40:43], v[72:75]
	v_mfma_f32_16x16x32_bf16 v[76:79], v[8:11], v[48:51], v[76:79]
	v_mfma_f32_16x16x32_bf16 v[80:83], v[16:19], v[48:51], v[80:83]
	v_mfma_f32_16x16x32_bf16 v[84:87], v[8:11], v[56:59], v[84:87]
	v_mfma_f32_16x16x32_bf16 v[88:91], v[16:19], v[56:59], v[88:91]
	v_mfma_f32_16x16x32_bf16 v[92:95], v[8:11], v[64:67], v[92:95]
	v_mfma_f32_16x16x32_bf16 v[96:99], v[16:19], v[64:67], v[96:99]
	s_setprio 0
	s_setprio 1
	v_mfma_f32_16x16x32_bf16 v[100:103], v[20:23], v[36:39], 0
	v_mfma_f32_16x16x32_bf16 v[36:39], v[28:31], v[36:39], 0
	v_mfma_f32_16x16x32_bf16 v[100:103], v[24:27], v[40:43], v[100:103]
	v_mfma_f32_16x16x32_bf16 v[40:43], v[32:35], v[40:43], v[36:39]
	v_mfma_f32_16x16x32_bf16 v[36:39], v[20:23], v[44:47], 0
	v_mfma_f32_16x16x32_bf16 v[104:107], v[24:27], v[48:51], v[36:39]
	v_mfma_f32_16x16x32_bf16 v[36:39], v[28:31], v[44:47], 0
	v_mfma_f32_16x16x32_bf16 v[48:51], v[32:35], v[48:51], v[36:39]
	v_mfma_f32_16x16x32_bf16 v[36:39], v[20:23], v[52:55], 0
	v_mfma_f32_16x16x32_bf16 v[108:111], v[24:27], v[56:59], v[36:39]
	v_mfma_f32_16x16x32_bf16 v[36:39], v[28:31], v[52:55], 0
	v_mfma_f32_16x16x32_bf16 v[56:59], v[32:35], v[56:59], v[36:39]
	v_mfma_f32_16x16x32_bf16 v[36:39], v[20:23], v[60:63], 0
	v_mfma_f32_16x16x32_bf16 v[112:115], v[24:27], v[64:67], v[36:39]
	v_mfma_f32_16x16x32_bf16 v[36:39], v[28:31], v[60:63], 0
	v_mfma_f32_16x16x32_bf16 v[64:67], v[32:35], v[64:67], v[36:39]
	s_setprio 0
	s_barrier
	s_add_i32 s82, s82, s6
	s_mov_b64 s[8:9], s[30:31]
	s_mov_b32 m0, s82
	s_add_i32 s83, s82, 0x2000
	s_nop 0
	ds_read_b128 v[36:39], v246 offset:16384
	ds_read_b128 v[44:47], v246 offset:17408
	ds_read_b128 v[52:55], v246 offset:18432
	ds_read_b128 v[60:63], v246 offset:19456
	ds_read_b128 v[116:119], v246 offset:20480
	ds_read_b128 v[120:123], v246 offset:21504
	ds_read_b128 v[124:127], v246 offset:22528
	ds_read_b128 v[128:131], v246 offset:23552
	s_nop 0
	global_load_lds_dwordx4 v248, s[8:9]
	s_mov_b32 m0, s83
	s_nop 0
	global_load_lds_dwordx4 v247, s[8:9]
	s_add_u32 s8, s30, s46
	s_addc_u32 s9, s31, s47
	s_add_i32 s30, s84, s6
	s_mov_b32 m0, s30
	s_add_i32 s31, s30, 0x2000
	s_nop 0
	global_load_lds_dwordx4 v248, s[8:9]
	s_mov_b32 m0, s31
	s_nop 0
	global_load_lds_dwordx4 v247, s[8:9]
	s_waitcnt vmcnt(6)
	s_waitcnt lgkmcnt(0)
	s_barrier
	s_setprio 1
	s_waitcnt lgkmcnt(0)
	v_mfma_f32_16x16x32_bf16 v[134:137], v[4:7], v[36:39], 0
	v_mfma_f32_16x16x32_bf16 v[144:147], v[4:7], v[52:55], 0
	v_mfma_f32_16x16x32_bf16 v[152:155], v[4:7], v[116:119], 0
	v_mfma_f32_16x16x32_bf16 v[4:7], v[4:7], v[124:127], 0
	v_mfma_f32_16x16x32_bf16 v[140:143], v[12:15], v[36:39], 0
	v_mfma_f32_16x16x32_bf16 v[148:151], v[12:15], v[52:55], 0
	v_mfma_f32_16x16x32_bf16 v[156:159], v[12:15], v[116:119], 0
	v_mfma_f32_16x16x32_bf16 v[160:163], v[8:11], v[128:131], v[4:7]
	v_mfma_f32_16x16x32_bf16 v[4:7], v[12:15], v[124:127], 0
	v_mfma_f32_16x16x32_bf16 v[136:139], v[8:11], v[44:47], v[134:137]
	v_mfma_f32_16x16x32_bf16 v[140:143], v[16:19], v[44:47], v[140:143]
	v_mfma_f32_16x16x32_bf16 v[144:147], v[8:11], v[60:63], v[144:147]
	v_mfma_f32_16x16x32_bf16 v[148:151], v[16:19], v[60:63], v[148:151]
	v_mfma_f32_16x16x32_bf16 v[152:155], v[8:11], v[120:123], v[152:155]
	v_mfma_f32_16x16x32_bf16 v[156:159], v[16:19], v[120:123], v[156:159]
	v_mfma_f32_16x16x32_bf16 v[164:167], v[16:19], v[128:131], v[4:7]
	s_setprio 0
	s_setprio 1
	v_mfma_f32_16x16x32_bf16 v[4:7], v[20:23], v[36:39], 0
	v_mfma_f32_16x16x32_bf16 v[168:171], v[24:27], v[44:47], v[4:7]
	v_mfma_f32_16x16x32_bf16 v[4:7], v[28:31], v[36:39], 0
	v_mfma_f32_16x16x32_bf16 v[172:175], v[32:35], v[44:47], v[4:7]
	v_mfma_f32_16x16x32_bf16 v[4:7], v[20:23], v[52:55], 0
	v_mfma_f32_16x16x32_bf16 v[176:179], v[24:27], v[60:63], v[4:7]
	v_mfma_f32_16x16x32_bf16 v[4:7], v[28:31], v[52:55], 0
	v_mfma_f32_16x16x32_bf16 v[180:183], v[32:35], v[60:63], v[4:7]
	v_mfma_f32_16x16x32_bf16 v[4:7], v[20:23], v[116:119], 0
	v_mfma_f32_16x16x32_bf16 v[184:187], v[24:27], v[120:123], v[4:7]
	v_mfma_f32_16x16x32_bf16 v[4:7], v[28:31], v[116:119], 0
	v_mfma_f32_16x16x32_bf16 v[120:123], v[32:35], v[120:123], v[4:7]
	v_mfma_f32_16x16x32_bf16 v[4:7], v[20:23], v[124:127], 0
	v_mfma_f32_16x16x32_bf16 v[188:191], v[24:27], v[128:131], v[4:7]
	v_mfma_f32_16x16x32_bf16 v[4:7], v[28:31], v[124:127], 0
	v_mfma_f32_16x16x32_bf16 v[128:131], v[32:35], v[128:131], v[4:7]
	s_setprio 0
	s_barrier
	s_add_i32 s84, 0, 0x18000
	s_add_i32 s16, 0, 0x1c000
	v_add_u32_e32 v134, s84, v245
	v_add_u32_e32 v135, s16, v245
	ds_read_b128 v[116:119], v134
	ds_read_b128 v[124:127], v134 offset:1024
	ds_read_b128 v[192:195], v134 offset:2048
	ds_read_b128 v[196:199], v134 offset:3072
	ds_read_b128 v[200:203], v135
	ds_read_b128 v[204:207], v135 offset:1024
	ds_read_b128 v[216:219], v135 offset:2048
	ds_read_b128 v[220:223], v135 offset:3072
	s_mov_b32 m0, s7
	s_mov_b64 s[8:9], s[18:19]
	ds_read_b128 v[44:47], v246 offset:32768
	ds_read_b128 v[52:55], v246 offset:33792
	ds_read_b128 v[60:63], v246 offset:34816
	ds_read_b128 v[224:227], v246 offset:35840
	ds_read_b128 v[228:231], v246 offset:36864
	ds_read_b128 v[232:235], v246 offset:37888
	ds_read_b128 v[236:239], v246 offset:38912
	ds_read_b128 v[250:253], v246 offset:39936
	s_nop 0
	global_load_lds_dwordx4 v242, s[8:9]
	s_mov_b32 m0, s58
	s_nop 0
	global_load_lds_dwordx4 v2, s[8:9]
	s_add_u32 s8, s18, s46
	s_addc_u32 s9, s19, s47
	s_mov_b32 m0, s59
	s_nop 0
	global_load_lds_dwordx4 v242, s[8:9]
	s_mov_b32 m0, s69
	s_nop 0
	global_load_lds_dwordx4 v2, s[8:9]
	s_waitcnt vmcnt(8)
	s_waitcnt lgkmcnt(0)
	s_barrier
	s_setprio 1
	s_waitcnt lgkmcnt(0)
	v_mfma_f32_16x16x32_bf16 v[4:7], v[116:119], v[44:47], v[68:71]
	v_mfma_f32_16x16x32_bf16 v[4:7], v[124:127], v[52:55], v[4:7]
	v_mfma_f32_16x16x32_bf16 v[8:11], v[192:195], v[44:47], v[72:75]
	v_mfma_f32_16x16x32_bf16 v[8:11], v[196:199], v[52:55], v[8:11]
	v_mfma_f32_16x16x32_bf16 v[12:15], v[116:119], v[60:63], v[76:79]
	v_mfma_f32_16x16x32_bf16 v[12:15], v[124:127], v[224:227], v[12:15]
	v_mfma_f32_16x16x32_bf16 v[16:19], v[192:195], v[60:63], v[80:83]
	v_mfma_f32_16x16x32_bf16 v[16:19], v[196:199], v[224:227], v[16:19]
	v_mfma_f32_16x16x32_bf16 v[20:23], v[116:119], v[228:231], v[84:87]
	v_mfma_f32_16x16x32_bf16 v[20:23], v[124:127], v[232:235], v[20:23]
	v_mfma_f32_16x16x32_bf16 v[24:27], v[192:195], v[228:231], v[88:91]
	v_mfma_f32_16x16x32_bf16 v[24:27], v[196:199], v[232:235], v[24:27]
	v_mfma_f32_16x16x32_bf16 v[28:31], v[116:119], v[236:239], v[92:95]
	v_mfma_f32_16x16x32_bf16 v[28:31], v[124:127], v[250:253], v[28:31]
	v_mfma_f32_16x16x32_bf16 v[32:35], v[192:195], v[236:239], v[96:99]
	v_mfma_f32_16x16x32_bf16 v[32:35], v[196:199], v[250:253], v[32:35]
	s_setprio 0
	s_setprio 1
	v_mfma_f32_16x16x32_bf16 v[36:39], v[200:203], v[44:47], v[100:103]
	v_mfma_f32_16x16x32_bf16 v[40:43], v[216:219], v[44:47], v[40:43]
	v_mfma_f32_16x16x32_bf16 v[36:39], v[204:207], v[52:55], v[36:39]
	v_mfma_f32_16x16x32_bf16 v[40:43], v[220:223], v[52:55], v[40:43]
	v_mfma_f32_16x16x32_bf16 v[44:47], v[200:203], v[60:63], v[104:107]
	v_mfma_f32_16x16x32_bf16 v[48:51], v[216:219], v[60:63], v[48:51]
	v_mfma_f32_16x16x32_bf16 v[52:55], v[200:203], v[228:231], v[108:111]
	v_mfma_f32_16x16x32_bf16 v[56:59], v[216:219], v[228:231], v[56:59]
	v_mfma_f32_16x16x32_bf16 v[60:63], v[200:203], v[236:239], v[112:115]
	v_mfma_f32_16x16x32_bf16 v[64:67], v[216:219], v[236:239], v[64:67]
	v_mfma_f32_16x16x32_bf16 v[44:47], v[204:207], v[224:227], v[44:47]
	v_mfma_f32_16x16x32_bf16 v[48:51], v[220:223], v[224:227], v[48:51]
	v_mfma_f32_16x16x32_bf16 v[52:55], v[204:207], v[232:235], v[52:55]
	v_mfma_f32_16x16x32_bf16 v[56:59], v[220:223], v[232:235], v[56:59]
	v_mfma_f32_16x16x32_bf16 v[60:63], v[204:207], v[250:253], v[60:63]
	v_mfma_f32_16x16x32_bf16 v[64:67], v[220:223], v[250:253], v[64:67]
	s_setprio 0
	s_barrier
	s_add_i32 s84, s84, s6
	s_mov_b64 s[8:9], s[28:29]
	s_mov_b32 m0, s84
	s_add_i32 s85, s84, 0x2000
	ds_read_b128 v[104:107], v246 offset:49152
	ds_read_b128 v[108:111], v246 offset:50176
	ds_read_b128 v[112:115], v246 offset:51200
	ds_read_b128 v[224:227], v246 offset:52224
	ds_read_b128 v[228:231], v246 offset:53248
	ds_read_b128 v[232:235], v246 offset:54272
	ds_read_b128 v[236:239], v246 offset:55296
	ds_read_b128 v[250:253], v246 offset:56320
	s_nop 0
	global_load_lds_dwordx4 v248, s[8:9]
	s_mov_b32 m0, s85
	s_nop 0
	global_load_lds_dwordx4 v247, s[8:9]
	s_add_u32 s8, s28, s46
	s_addc_u32 s9, s29, s47
	s_add_i32 s28, s16, s6
	s_mov_b32 m0, s28
	s_add_i32 s29, s28, 0x2000
	s_nop 0
	global_load_lds_dwordx4 v248, s[8:9]
	s_mov_b32 m0, s29
	s_nop 0
	global_load_lds_dwordx4 v247, s[8:9]
	s_waitcnt vmcnt(6)
	s_waitcnt lgkmcnt(0)
	s_barrier
	s_setprio 1
	s_waitcnt lgkmcnt(0)
	v_mfma_f32_16x16x32_bf16 v[68:71], v[116:119], v[104:107], v[136:139]
	v_mfma_f32_16x16x32_bf16 v[68:71], v[124:127], v[108:111], v[68:71]
	v_mfma_f32_16x16x32_bf16 v[72:75], v[192:195], v[104:107], v[140:143]
	v_mfma_f32_16x16x32_bf16 v[72:75], v[196:199], v[108:111], v[72:75]
	v_mfma_f32_16x16x32_bf16 v[76:79], v[116:119], v[112:115], v[144:147]
	v_mfma_f32_16x16x32_bf16 v[76:79], v[124:127], v[224:227], v[76:79]
	v_mfma_f32_16x16x32_bf16 v[80:83], v[192:195], v[112:115], v[148:151]
	v_mfma_f32_16x16x32_bf16 v[80:83], v[196:199], v[224:227], v[80:83]
	v_mfma_f32_16x16x32_bf16 v[84:87], v[116:119], v[228:231], v[152:155]
	v_mfma_f32_16x16x32_bf16 v[84:87], v[124:127], v[232:235], v[84:87]
	v_mfma_f32_16x16x32_bf16 v[88:91], v[192:195], v[228:231], v[156:159]
	v_mfma_f32_16x16x32_bf16 v[88:91], v[196:199], v[232:235], v[88:91]
	v_mfma_f32_16x16x32_bf16 v[92:95], v[116:119], v[236:239], v[160:163]
	v_mfma_f32_16x16x32_bf16 v[92:95], v[124:127], v[250:253], v[92:95]
	v_mfma_f32_16x16x32_bf16 v[96:99], v[192:195], v[236:239], v[164:167]
	v_mfma_f32_16x16x32_bf16 v[96:99], v[196:199], v[250:253], v[96:99]
	s_setprio 0
	s_setprio 1
	v_mfma_f32_16x16x32_bf16 v[100:103], v[200:203], v[104:107], v[168:171]
	v_mfma_f32_16x16x32_bf16 v[104:107], v[216:219], v[104:107], v[172:175]
	v_mfma_f32_16x16x32_bf16 v[100:103], v[204:207], v[108:111], v[100:103]
	v_mfma_f32_16x16x32_bf16 v[104:107], v[220:223], v[108:111], v[104:107]
	v_mfma_f32_16x16x32_bf16 v[108:111], v[200:203], v[112:115], v[176:179]
	v_mfma_f32_16x16x32_bf16 v[112:115], v[216:219], v[112:115], v[180:183]
	v_mfma_f32_16x16x32_bf16 v[116:119], v[200:203], v[228:231], v[184:187]
	v_mfma_f32_16x16x32_bf16 v[120:123], v[216:219], v[228:231], v[120:123]
	v_mfma_f32_16x16x32_bf16 v[124:127], v[200:203], v[236:239], v[188:191]
	v_mfma_f32_16x16x32_bf16 v[128:131], v[216:219], v[236:239], v[128:131]
	v_mfma_f32_16x16x32_bf16 v[108:111], v[204:207], v[224:227], v[108:111]
	v_mfma_f32_16x16x32_bf16 v[112:115], v[220:223], v[224:227], v[112:115]
	v_mfma_f32_16x16x32_bf16 v[116:119], v[204:207], v[232:235], v[116:119]
	v_mfma_f32_16x16x32_bf16 v[120:123], v[220:223], v[232:235], v[120:123]
	v_mfma_f32_16x16x32_bf16 v[124:127], v[204:207], v[250:253], v[124:127]
	v_mfma_f32_16x16x32_bf16 v[128:131], v[220:223], v[250:253], v[128:131]
	s_setprio 0
	s_barrier
	s_andn2_b64 vcc, exec, s[56:57]
	s_cbranch_vccnz .LBB0_881
	s_add_u32 s86, s20, 0x200
	s_addc_u32 s87, s21, 0
	s_add_u32 s26, s26, 0x200
	s_addc_u32 s27, s27, 0
	s_mov_b32 s88, 4
.LBB0_880:
	ds_read_b128 v[136:139], v132
	ds_read_b128 v[140:143], v132 offset:1024
	ds_read_b128 v[144:147], v132 offset:2048
	ds_read_b128 v[148:151], v132 offset:3072
	ds_read_b128 v[152:155], v133
	ds_read_b128 v[156:159], v133 offset:1024
	ds_read_b128 v[160:163], v133 offset:2048
	ds_read_b128 v[164:167], v133 offset:3072
	s_cmp_eq_u32 s4, s88
	s_cselect_b32 s17, s43, s87
	s_cselect_b32 s16, s42, s86
	s_cselect_b32 s21, s41, s27
	s_cselect_b32 s20, s40, s26
	s_add_u32 s8, s26, 0xffffff80
	s_addc_u32 s9, s27, -1
	s_mov_b32 m0, s78
	s_mov_b64 s[18:19], s[8:9]
	ds_read_b128 v[168:171], v246
	ds_read_b128 v[172:175], v246 offset:1024
	ds_read_b128 v[176:179], v246 offset:2048
	ds_read_b128 v[180:183], v246 offset:3072
	ds_read_b128 v[184:187], v246 offset:4096
	ds_read_b128 v[188:191], v246 offset:5120
	ds_read_b128 v[192:195], v246 offset:6144
	ds_read_b128 v[196:199], v246 offset:7168
	s_add_u32 s8, s8, s46
	global_load_lds_dwordx4 v242, s[18:19]
	s_mov_b32 m0, s79
	s_addc_u32 s9, s9, s47
	global_load_lds_dwordx4 v2, s[18:19]
	s_mov_b32 m0, s80
	s_add_u32 s18, s16, 0x80
	global_load_lds_dwordx4 v242, s[8:9]
	s_mov_b32 m0, s81
	s_addc_u32 s19, s17, 0
	global_load_lds_dwordx4 v2, s[8:9]
	s_waitcnt vmcnt(8)
	s_waitcnt lgkmcnt(0)
	s_barrier
	s_setprio 1
	s_waitcnt lgkmcnt(0)
	v_mfma_f32_16x16x32_bf16 v[4:7], v[136:139], v[168:171], v[4:7]
	v_mfma_f32_16x16x32_bf16 v[4:7], v[140:143], v[172:175], v[4:7]
	v_mfma_f32_16x16x32_bf16 v[8:11], v[144:147], v[168:171], v[8:11]
	v_mfma_f32_16x16x32_bf16 v[8:11], v[148:151], v[172:175], v[8:11]
	v_mfma_f32_16x16x32_bf16 v[12:15], v[136:139], v[176:179], v[12:15]
	v_mfma_f32_16x16x32_bf16 v[12:15], v[140:143], v[180:183], v[12:15]
	v_mfma_f32_16x16x32_bf16 v[16:19], v[144:147], v[176:179], v[16:19]
	v_mfma_f32_16x16x32_bf16 v[16:19], v[148:151], v[180:183], v[16:19]
	v_mfma_f32_16x16x32_bf16 v[20:23], v[136:139], v[184:187], v[20:23]
	v_mfma_f32_16x16x32_bf16 v[20:23], v[140:143], v[188:191], v[20:23]
	v_mfma_f32_16x16x32_bf16 v[24:27], v[144:147], v[184:187], v[24:27]
	v_mfma_f32_16x16x32_bf16 v[24:27], v[148:151], v[188:191], v[24:27]
	v_mfma_f32_16x16x32_bf16 v[28:31], v[136:139], v[192:195], v[28:31]
	v_mfma_f32_16x16x32_bf16 v[28:31], v[140:143], v[196:199], v[28:31]
	v_mfma_f32_16x16x32_bf16 v[32:35], v[144:147], v[192:195], v[32:35]
	v_mfma_f32_16x16x32_bf16 v[32:35], v[148:151], v[196:199], v[32:35]
	s_setprio 0
	s_setprio 1
	v_mfma_f32_16x16x32_bf16 v[36:39], v[152:155], v[168:171], v[36:39]
	v_mfma_f32_16x16x32_bf16 v[36:39], v[156:159], v[172:175], v[36:39]
	v_mfma_f32_16x16x32_bf16 v[40:43], v[160:163], v[168:171], v[40:43]
	v_mfma_f32_16x16x32_bf16 v[40:43], v[164:167], v[172:175], v[40:43]
	v_mfma_f32_16x16x32_bf16 v[44:47], v[152:155], v[176:179], v[44:47]
	v_mfma_f32_16x16x32_bf16 v[44:47], v[156:159], v[180:183], v[44:47]
	v_mfma_f32_16x16x32_bf16 v[48:51], v[160:163], v[176:179], v[48:51]
	v_mfma_f32_16x16x32_bf16 v[48:51], v[164:167], v[180:183], v[48:51]
	v_mfma_f32_16x16x32_bf16 v[52:55], v[152:155], v[184:187], v[52:55]
	v_mfma_f32_16x16x32_bf16 v[52:55], v[156:159], v[188:191], v[52:55]
	v_mfma_f32_16x16x32_bf16 v[56:59], v[160:163], v[184:187], v[56:59]
	v_mfma_f32_16x16x32_bf16 v[56:59], v[164:167], v[188:191], v[56:59]
	v_mfma_f32_16x16x32_bf16 v[60:63], v[152:155], v[192:195], v[60:63]
	v_mfma_f32_16x16x32_bf16 v[60:63], v[156:159], v[196:199], v[60:63]
	v_mfma_f32_16x16x32_bf16 v[64:67], v[160:163], v[192:195], v[64:67]
	v_mfma_f32_16x16x32_bf16 v[64:67], v[164:167], v[196:199], v[64:67]
	s_setprio 0
	s_barrier
	s_mov_b32 m0, s82
	s_mov_b64 s[8:9], s[16:17]
	ds_read_b128 v[168:171], v246 offset:16384
	ds_read_b128 v[172:175], v246 offset:17408
	ds_read_b128 v[176:179], v246 offset:18432
	ds_read_b128 v[180:183], v246 offset:19456
	ds_read_b128 v[184:187], v246 offset:20480
	ds_read_b128 v[188:191], v246 offset:21504
	ds_read_b128 v[192:195], v246 offset:22528
	ds_read_b128 v[196:199], v246 offset:23552
	s_nop 0
	global_load_lds_dwordx4 v248, s[8:9]
	s_mov_b32 m0, s83
	s_nop 0
	global_load_lds_dwordx4 v247, s[8:9]
	s_add_u32 s8, s16, s46
	s_addc_u32 s9, s17, s47
	s_mov_b32 m0, s30
	s_nop 0
	global_load_lds_dwordx4 v248, s[8:9]
	s_mov_b32 m0, s31
	s_nop 0
	global_load_lds_dwordx4 v247, s[8:9]
	s_waitcnt vmcnt(6)
	s_waitcnt lgkmcnt(0)
	s_barrier
	s_setprio 1
	s_waitcnt lgkmcnt(0)
	v_mfma_f32_16x16x32_bf16 v[68:71], v[136:139], v[168:171], v[68:71]
	v_mfma_f32_16x16x32_bf16 v[68:71], v[140:143], v[172:175], v[68:71]
	v_mfma_f32_16x16x32_bf16 v[72:75], v[144:147], v[168:171], v[72:75]
	v_mfma_f32_16x16x32_bf16 v[72:75], v[148:151], v[172:175], v[72:75]
	v_mfma_f32_16x16x32_bf16 v[76:79], v[136:139], v[176:179], v[76:79]
	v_mfma_f32_16x16x32_bf16 v[76:79], v[140:143], v[180:183], v[76:79]
	v_mfma_f32_16x16x32_bf16 v[80:83], v[144:147], v[176:179], v[80:83]
	v_mfma_f32_16x16x32_bf16 v[80:83], v[148:151], v[180:183], v[80:83]
	v_mfma_f32_16x16x32_bf16 v[84:87], v[136:139], v[184:187], v[84:87]
	v_mfma_f32_16x16x32_bf16 v[84:87], v[140:143], v[188:191], v[84:87]
	v_mfma_f32_16x16x32_bf16 v[88:91], v[144:147], v[184:187], v[88:91]
	v_mfma_f32_16x16x32_bf16 v[88:91], v[148:151], v[188:191], v[88:91]
	v_mfma_f32_16x16x32_bf16 v[92:95], v[136:139], v[192:195], v[92:95]
	v_mfma_f32_16x16x32_bf16 v[92:95], v[140:143], v[196:199], v[92:95]
	v_mfma_f32_16x16x32_bf16 v[96:99], v[144:147], v[192:195], v[96:99]
	v_mfma_f32_16x16x32_bf16 v[96:99], v[148:151], v[196:199], v[96:99]
	s_setprio 0
	s_setprio 1
	v_mfma_f32_16x16x32_bf16 v[100:103], v[152:155], v[168:171], v[100:103]
	v_mfma_f32_16x16x32_bf16 v[100:103], v[156:159], v[172:175], v[100:103]
	v_mfma_f32_16x16x32_bf16 v[104:107], v[160:163], v[168:171], v[104:107]
	v_mfma_f32_16x16x32_bf16 v[104:107], v[164:167], v[172:175], v[104:107]
	v_mfma_f32_16x16x32_bf16 v[108:111], v[152:155], v[176:179], v[108:111]
	v_mfma_f32_16x16x32_bf16 v[108:111], v[156:159], v[180:183], v[108:111]
	v_mfma_f32_16x16x32_bf16 v[112:115], v[160:163], v[176:179], v[112:115]
	v_mfma_f32_16x16x32_bf16 v[112:115], v[164:167], v[180:183], v[112:115]
	v_mfma_f32_16x16x32_bf16 v[116:119], v[152:155], v[184:187], v[116:119]
	v_mfma_f32_16x16x32_bf16 v[116:119], v[156:159], v[188:191], v[116:119]
	v_mfma_f32_16x16x32_bf16 v[120:123], v[160:163], v[184:187], v[120:123]
	v_mfma_f32_16x16x32_bf16 v[120:123], v[164:167], v[188:191], v[120:123]
	v_mfma_f32_16x16x32_bf16 v[124:127], v[152:155], v[192:195], v[124:127]
	v_mfma_f32_16x16x32_bf16 v[124:127], v[156:159], v[196:199], v[124:127]
	v_mfma_f32_16x16x32_bf16 v[128:131], v[160:163], v[192:195], v[128:131]
	v_mfma_f32_16x16x32_bf16 v[128:131], v[164:167], v[196:199], v[128:131]
	s_setprio 0
	s_barrier
	ds_read_b128 v[136:139], v134
	ds_read_b128 v[140:143], v134 offset:1024
	ds_read_b128 v[144:147], v134 offset:2048
	ds_read_b128 v[148:151], v134 offset:3072
	ds_read_b128 v[152:155], v135
	ds_read_b128 v[156:159], v135 offset:1024
	ds_read_b128 v[160:163], v135 offset:2048
	ds_read_b128 v[164:167], v135 offset:3072
	s_mov_b32 m0, s7
	s_mov_b64 s[8:9], s[20:21]
	ds_read_b128 v[168:171], v246 offset:32768
	ds_read_b128 v[172:175], v246 offset:33792
	ds_read_b128 v[176:179], v246 offset:34816
	ds_read_b128 v[180:183], v246 offset:35840
	ds_read_b128 v[184:187], v246 offset:36864
	ds_read_b128 v[188:191], v246 offset:37888
	ds_read_b128 v[192:195], v246 offset:38912
	ds_read_b128 v[196:199], v246 offset:39936
	s_nop 0
	global_load_lds_dwordx4 v242, s[8:9]
	s_mov_b32 m0, s58
	s_nop 0
	global_load_lds_dwordx4 v2, s[8:9]
	s_add_u32 s8, s20, s46
	s_addc_u32 s9, s21, s47
	s_mov_b32 m0, s59
	s_nop 0
	global_load_lds_dwordx4 v242, s[8:9]
	s_mov_b32 m0, s69
	s_nop 0
	global_load_lds_dwordx4 v2, s[8:9]
	s_waitcnt vmcnt(8)
	s_waitcnt lgkmcnt(0)
	s_barrier
	s_setprio 1
	s_waitcnt lgkmcnt(0)
	v_mfma_f32_16x16x32_bf16 v[4:7], v[136:139], v[168:171], v[4:7]
	v_mfma_f32_16x16x32_bf16 v[4:7], v[140:143], v[172:175], v[4:7]
	v_mfma_f32_16x16x32_bf16 v[8:11], v[144:147], v[168:171], v[8:11]
	v_mfma_f32_16x16x32_bf16 v[8:11], v[148:151], v[172:175], v[8:11]
	v_mfma_f32_16x16x32_bf16 v[12:15], v[136:139], v[176:179], v[12:15]
	v_mfma_f32_16x16x32_bf16 v[12:15], v[140:143], v[180:183], v[12:15]
	v_mfma_f32_16x16x32_bf16 v[16:19], v[144:147], v[176:179], v[16:19]
	v_mfma_f32_16x16x32_bf16 v[16:19], v[148:151], v[180:183], v[16:19]
	v_mfma_f32_16x16x32_bf16 v[20:23], v[136:139], v[184:187], v[20:23]
	v_mfma_f32_16x16x32_bf16 v[20:23], v[140:143], v[188:191], v[20:23]
	v_mfma_f32_16x16x32_bf16 v[24:27], v[144:147], v[184:187], v[24:27]
	v_mfma_f32_16x16x32_bf16 v[24:27], v[148:151], v[188:191], v[24:27]
	v_mfma_f32_16x16x32_bf16 v[28:31], v[136:139], v[192:195], v[28:31]
	v_mfma_f32_16x16x32_bf16 v[28:31], v[140:143], v[196:199], v[28:31]
	v_mfma_f32_16x16x32_bf16 v[32:35], v[144:147], v[192:195], v[32:35]
	v_mfma_f32_16x16x32_bf16 v[32:35], v[148:151], v[196:199], v[32:35]
	s_setprio 0
	s_setprio 1
	v_mfma_f32_16x16x32_bf16 v[36:39], v[152:155], v[168:171], v[36:39]
	v_mfma_f32_16x16x32_bf16 v[36:39], v[156:159], v[172:175], v[36:39]
	v_mfma_f32_16x16x32_bf16 v[40:43], v[160:163], v[168:171], v[40:43]
	v_mfma_f32_16x16x32_bf16 v[40:43], v[164:167], v[172:175], v[40:43]
	v_mfma_f32_16x16x32_bf16 v[44:47], v[152:155], v[176:179], v[44:47]
	v_mfma_f32_16x16x32_bf16 v[44:47], v[156:159], v[180:183], v[44:47]
	v_mfma_f32_16x16x32_bf16 v[48:51], v[160:163], v[176:179], v[48:51]
	v_mfma_f32_16x16x32_bf16 v[48:51], v[164:167], v[180:183], v[48:51]
	v_mfma_f32_16x16x32_bf16 v[52:55], v[152:155], v[184:187], v[52:55]
	v_mfma_f32_16x16x32_bf16 v[52:55], v[156:159], v[188:191], v[52:55]
	v_mfma_f32_16x16x32_bf16 v[56:59], v[160:163], v[184:187], v[56:59]
	v_mfma_f32_16x16x32_bf16 v[56:59], v[164:167], v[188:191], v[56:59]
	v_mfma_f32_16x16x32_bf16 v[60:63], v[152:155], v[192:195], v[60:63]
	v_mfma_f32_16x16x32_bf16 v[60:63], v[156:159], v[196:199], v[60:63]
	v_mfma_f32_16x16x32_bf16 v[64:67], v[160:163], v[192:195], v[64:67]
	v_mfma_f32_16x16x32_bf16 v[64:67], v[164:167], v[196:199], v[64:67]
	s_setprio 0
	s_barrier
	s_mov_b32 m0, s84
	s_mov_b64 s[8:9], s[18:19]
	ds_read_b128 v[168:171], v246 offset:49152
	ds_read_b128 v[172:175], v246 offset:50176
	ds_read_b128 v[176:179], v246 offset:51200
	ds_read_b128 v[180:183], v246 offset:52224
	ds_read_b128 v[184:187], v246 offset:53248
	ds_read_b128 v[188:191], v246 offset:54272
	ds_read_b128 v[192:195], v246 offset:55296
	ds_read_b128 v[196:199], v246 offset:56320
	s_nop 0
	global_load_lds_dwordx4 v248, s[8:9]
	s_mov_b32 m0, s85
	s_nop 0
	global_load_lds_dwordx4 v247, s[8:9]
	s_add_u32 s8, s18, s46
	s_addc_u32 s9, s19, s47
	s_mov_b32 m0, s28
	s_nop 0
	global_load_lds_dwordx4 v248, s[8:9]
	s_mov_b32 m0, s29
	s_nop 0
	global_load_lds_dwordx4 v247, s[8:9]
	s_waitcnt vmcnt(6)
	s_waitcnt lgkmcnt(0)
	s_barrier
	s_setprio 1
	s_waitcnt lgkmcnt(0)
	v_mfma_f32_16x16x32_bf16 v[68:71], v[136:139], v[168:171], v[68:71]
	v_mfma_f32_16x16x32_bf16 v[68:71], v[140:143], v[172:175], v[68:71]
	v_mfma_f32_16x16x32_bf16 v[72:75], v[144:147], v[168:171], v[72:75]
	v_mfma_f32_16x16x32_bf16 v[72:75], v[148:151], v[172:175], v[72:75]
	v_mfma_f32_16x16x32_bf16 v[76:79], v[136:139], v[176:179], v[76:79]
	v_mfma_f32_16x16x32_bf16 v[76:79], v[140:143], v[180:183], v[76:79]
	v_mfma_f32_16x16x32_bf16 v[80:83], v[144:147], v[176:179], v[80:83]
	v_mfma_f32_16x16x32_bf16 v[80:83], v[148:151], v[180:183], v[80:83]
	v_mfma_f32_16x16x32_bf16 v[84:87], v[136:139], v[184:187], v[84:87]
	v_mfma_f32_16x16x32_bf16 v[84:87], v[140:143], v[188:191], v[84:87]
	v_mfma_f32_16x16x32_bf16 v[88:91], v[144:147], v[184:187], v[88:91]
	v_mfma_f32_16x16x32_bf16 v[88:91], v[148:151], v[188:191], v[88:91]
	v_mfma_f32_16x16x32_bf16 v[92:95], v[136:139], v[192:195], v[92:95]
	v_mfma_f32_16x16x32_bf16 v[92:95], v[140:143], v[196:199], v[92:95]
	v_mfma_f32_16x16x32_bf16 v[96:99], v[144:147], v[192:195], v[96:99]
	v_mfma_f32_16x16x32_bf16 v[96:99], v[148:151], v[196:199], v[96:99]
	s_setprio 0
	s_setprio 1
	v_mfma_f32_16x16x32_bf16 v[100:103], v[152:155], v[168:171], v[100:103]
	v_mfma_f32_16x16x32_bf16 v[100:103], v[156:159], v[172:175], v[100:103]
	v_mfma_f32_16x16x32_bf16 v[104:107], v[160:163], v[168:171], v[104:107]
	v_mfma_f32_16x16x32_bf16 v[104:107], v[164:167], v[172:175], v[104:107]
	v_mfma_f32_16x16x32_bf16 v[108:111], v[152:155], v[176:179], v[108:111]
	v_mfma_f32_16x16x32_bf16 v[108:111], v[156:159], v[180:183], v[108:111]
	v_mfma_f32_16x16x32_bf16 v[112:115], v[160:163], v[176:179], v[112:115]
	v_mfma_f32_16x16x32_bf16 v[112:115], v[164:167], v[180:183], v[112:115]
	v_mfma_f32_16x16x32_bf16 v[116:119], v[152:155], v[184:187], v[116:119]
	v_mfma_f32_16x16x32_bf16 v[116:119], v[156:159], v[188:191], v[116:119]
	v_mfma_f32_16x16x32_bf16 v[120:123], v[160:163], v[184:187], v[120:123]
	v_mfma_f32_16x16x32_bf16 v[120:123], v[164:167], v[188:191], v[120:123]
	v_mfma_f32_16x16x32_bf16 v[124:127], v[152:155], v[192:195], v[124:127]
	v_mfma_f32_16x16x32_bf16 v[124:127], v[156:159], v[196:199], v[124:127]
	v_mfma_f32_16x16x32_bf16 v[128:131], v[160:163], v[192:195], v[128:131]
	v_mfma_f32_16x16x32_bf16 v[128:131], v[164:167], v[196:199], v[128:131]
	s_setprio 0
	s_barrier
	s_add_i32 s8, s88, 2
	s_add_u32 s86, s86, 0x100
	s_addc_u32 s87, s87, 0
	s_add_u32 s26, s26, 0x100
	s_addc_u32 s27, s27, 0
	s_cmp_ge_i32 s88, s4
	s_mov_b32 s88, s8
	s_cbranch_scc0 .LBB0_880

.LBB0_1019:
	s_add_u32 s18, s72, 0x100
	s_addc_u32 s19, s73, 0
	s_add_u32 s16, s66, 0x100
	s_addc_u32 s17, s67, 0
	s_and_b64 s[8:9], s[30:31], exec
	s_cselect_b32 s17, s43, s17
	s_cselect_b32 s16, s42, s16
	s_add_i32 s89, 0, 0x10000
	s_and_b64 s[8:9], s[30:31], exec
	s_cselect_b32 s69, s65, s19
	s_cselect_b32 s68, s64, s18
	s_add_i32 s91, 0, 0x14000
	v_add_u32_e32 v132, s89, v140
	v_add_u32_e32 v133, s91, v140
	ds_read_b128 v[4:7], v132
	ds_read_b128 v[8:11], v132 offset:1024
	ds_read_b128 v[12:15], v132 offset:2048
	ds_read_b128 v[16:19], v132 offset:3072
	ds_read_b128 v[20:23], v133
	ds_read_b128 v[24:27], v133 offset:1024
	ds_read_b128 v[28:31], v133 offset:2048
	ds_read_b128 v[32:35], v133 offset:3072
	s_add_u32 s8, s72, 0x80
	s_addc_u32 s9, s73, 0
	s_add_i32 s85, s78, 0x8000
	s_add_i32 s86, s78, 0xa000
	s_mov_b64 s[18:19], s[8:9]
	s_mov_b32 m0, s85
	s_add_u32 s8, s8, s20
	ds_read_b128 v[36:39], v141 offset:8192
	ds_read_b128 v[40:43], v141 offset:9216
	ds_read_b128 v[44:47], v141 offset:10240
	ds_read_b128 v[48:51], v141 offset:11264
	ds_read_b128 v[52:55], v141 offset:12288
	ds_read_b128 v[56:59], v141 offset:13312
	ds_read_b128 v[60:63], v141 offset:14336
	ds_read_b128 v[64:67], v141 offset:15360
	s_addc_u32 s9, s9, s21
	global_load_lds_dwordx4 v137, s[18:19]
	s_mov_b32 m0, s86
	s_add_i32 s87, s78, 0xc000
	global_load_lds_dwordx4 v136, s[18:19]
	s_mov_b32 m0, s87
	s_add_i32 s88, s78, 0xe000
	s_add_u32 s18, s16, 0x80
	global_load_lds_dwordx4 v137, s[8:9]
	s_mov_b32 m0, s88
	s_addc_u32 s19, s17, 0
	global_load_lds_dwordx4 v136, s[8:9]
	s_waitcnt vmcnt(8)
	s_waitcnt lgkmcnt(0)
	s_barrier
	s_setprio 1
	s_waitcnt lgkmcnt(0)
	v_mfma_f32_16x16x32_bf16 v[68:71], v[4:7], v[36:39], 0
	v_mfma_f32_16x16x32_bf16 v[72:75], v[12:15], v[36:39], 0
	v_mfma_f32_16x16x32_bf16 v[76:79], v[4:7], v[44:47], 0
	v_mfma_f32_16x16x32_bf16 v[80:83], v[12:15], v[44:47], 0
	v_mfma_f32_16x16x32_bf16 v[84:87], v[4:7], v[52:55], 0
	v_mfma_f32_16x16x32_bf16 v[88:91], v[12:15], v[52:55], 0
	v_mfma_f32_16x16x32_bf16 v[92:95], v[4:7], v[60:63], 0
	v_mfma_f32_16x16x32_bf16 v[96:99], v[12:15], v[60:63], 0
	v_mfma_f32_16x16x32_bf16 v[68:71], v[8:11], v[40:43], v[68:71]
	v_mfma_f32_16x16x32_bf16 v[72:75], v[16:19], v[40:43], v[72:75]
	v_mfma_f32_16x16x32_bf16 v[76:79], v[8:11], v[48:51], v[76:79]
	v_mfma_f32_16x16x32_bf16 v[80:83], v[16:19], v[48:51], v[80:83]
	v_mfma_f32_16x16x32_bf16 v[84:87], v[8:11], v[56:59], v[84:87]
	v_mfma_f32_16x16x32_bf16 v[88:91], v[16:19], v[56:59], v[88:91]
	v_mfma_f32_16x16x32_bf16 v[92:95], v[8:11], v[64:67], v[92:95]
	v_mfma_f32_16x16x32_bf16 v[96:99], v[16:19], v[64:67], v[96:99]
	s_setprio 0
	s_setprio 1
	v_mfma_f32_16x16x32_bf16 v[100:103], v[20:23], v[36:39], 0
	v_mfma_f32_16x16x32_bf16 v[36:39], v[28:31], v[36:39], 0
	v_mfma_f32_16x16x32_bf16 v[100:103], v[24:27], v[40:43], v[100:103]
	v_mfma_f32_16x16x32_bf16 v[40:43], v[32:35], v[40:43], v[36:39]
	v_mfma_f32_16x16x32_bf16 v[36:39], v[20:23], v[44:47], 0
	v_mfma_f32_16x16x32_bf16 v[104:107], v[24:27], v[48:51], v[36:39]
	v_mfma_f32_16x16x32_bf16 v[36:39], v[28:31], v[44:47], 0
	v_mfma_f32_16x16x32_bf16 v[48:51], v[32:35], v[48:51], v[36:39]
	v_mfma_f32_16x16x32_bf16 v[36:39], v[20:23], v[52:55], 0
	v_mfma_f32_16x16x32_bf16 v[108:111], v[24:27], v[56:59], v[36:39]
	v_mfma_f32_16x16x32_bf16 v[36:39], v[28:31], v[52:55], 0
	v_mfma_f32_16x16x32_bf16 v[56:59], v[32:35], v[56:59], v[36:39]
	v_mfma_f32_16x16x32_bf16 v[36:39], v[20:23], v[60:63], 0
	v_mfma_f32_16x16x32_bf16 v[112:115], v[24:27], v[64:67], v[36:39]
	v_mfma_f32_16x16x32_bf16 v[36:39], v[28:31], v[60:63], 0
	v_mfma_f32_16x16x32_bf16 v[64:67], v[32:35], v[64:67], v[36:39]
	s_setprio 0
	s_barrier
	s_add_i32 s89, s89, s77
	s_mov_b64 s[8:9], s[16:17]
	s_mov_b32 m0, s89
	s_add_i32 s90, s89, 0x2000
	s_nop 0
	ds_read_b128 v[36:39], v141 offset:24576
	ds_read_b128 v[44:47], v141 offset:25600
	ds_read_b128 v[52:55], v141 offset:26624
	ds_read_b128 v[60:63], v141 offset:27648
	ds_read_b128 v[116:119], v141 offset:28672
	ds_read_b128 v[120:123], v141 offset:29696
	ds_read_b128 v[124:127], v141 offset:30720
	ds_read_b128 v[128:131], v141 offset:31744
	s_nop 0
	global_load_lds_dwordx4 v143, s[8:9]
	s_mov_b32 m0, s90
	s_nop 0
	global_load_lds_dwordx4 v142, s[8:9]
	s_add_u32 s8, s16, s20
	s_addc_u32 s9, s17, s21
	s_add_i32 s91, s91, s77
	s_mov_b32 m0, s91
	s_add_i32 s92, s91, 0x2000
	s_nop 0
	global_load_lds_dwordx4 v143, s[8:9]
	s_mov_b32 m0, s92
	s_nop 0
	global_load_lds_dwordx4 v142, s[8:9]
	s_waitcnt vmcnt(6)
	s_waitcnt lgkmcnt(0)
	s_barrier
	s_setprio 1
	s_waitcnt lgkmcnt(0)
	v_mfma_f32_16x16x32_bf16 v[144:147], v[4:7], v[36:39], 0
	v_mfma_f32_16x16x32_bf16 v[152:155], v[4:7], v[52:55], 0
	v_mfma_f32_16x16x32_bf16 v[160:163], v[4:7], v[116:119], 0
	v_mfma_f32_16x16x32_bf16 v[4:7], v[4:7], v[124:127], 0
	v_mfma_f32_16x16x32_bf16 v[148:151], v[12:15], v[36:39], 0
	v_mfma_f32_16x16x32_bf16 v[156:159], v[12:15], v[52:55], 0
	v_mfma_f32_16x16x32_bf16 v[164:167], v[12:15], v[116:119], 0
	v_mfma_f32_16x16x32_bf16 v[168:171], v[8:11], v[128:131], v[4:7]
	v_mfma_f32_16x16x32_bf16 v[4:7], v[12:15], v[124:127], 0
	v_mfma_f32_16x16x32_bf16 v[144:147], v[8:11], v[44:47], v[144:147]
	v_mfma_f32_16x16x32_bf16 v[148:151], v[16:19], v[44:47], v[148:151]
	v_mfma_f32_16x16x32_bf16 v[152:155], v[8:11], v[60:63], v[152:155]
	v_mfma_f32_16x16x32_bf16 v[156:159], v[16:19], v[60:63], v[156:159]
	v_mfma_f32_16x16x32_bf16 v[160:163], v[8:11], v[120:123], v[160:163]
	v_mfma_f32_16x16x32_bf16 v[164:167], v[16:19], v[120:123], v[164:167]
	v_mfma_f32_16x16x32_bf16 v[172:175], v[16:19], v[128:131], v[4:7]
	s_setprio 0
	s_setprio 1
	v_mfma_f32_16x16x32_bf16 v[4:7], v[20:23], v[36:39], 0
	v_mfma_f32_16x16x32_bf16 v[176:179], v[24:27], v[44:47], v[4:7]
	v_mfma_f32_16x16x32_bf16 v[4:7], v[28:31], v[36:39], 0
	v_mfma_f32_16x16x32_bf16 v[180:183], v[32:35], v[44:47], v[4:7]
	v_mfma_f32_16x16x32_bf16 v[4:7], v[20:23], v[52:55], 0
	v_mfma_f32_16x16x32_bf16 v[184:187], v[24:27], v[60:63], v[4:7]
	v_mfma_f32_16x16x32_bf16 v[4:7], v[28:31], v[52:55], 0
	v_mfma_f32_16x16x32_bf16 v[188:191], v[32:35], v[60:63], v[4:7]
	v_mfma_f32_16x16x32_bf16 v[4:7], v[20:23], v[116:119], 0
	v_mfma_f32_16x16x32_bf16 v[192:195], v[24:27], v[120:123], v[4:7]
	v_mfma_f32_16x16x32_bf16 v[4:7], v[28:31], v[116:119], 0
	v_mfma_f32_16x16x32_bf16 v[120:123], v[32:35], v[120:123], v[4:7]
	v_mfma_f32_16x16x32_bf16 v[4:7], v[20:23], v[124:127], 0
	v_mfma_f32_16x16x32_bf16 v[196:199], v[24:27], v[128:131], v[4:7]
	v_mfma_f32_16x16x32_bf16 v[4:7], v[28:31], v[124:127], 0
	v_mfma_f32_16x16x32_bf16 v[128:131], v[32:35], v[128:131], v[4:7]
	s_setprio 0
	s_barrier
	s_add_i32 s16, 0, 0x18000
	s_add_i32 s93, 0, 0x1c000
	v_add_u32_e32 v134, s16, v140
	v_add_u32_e32 v135, s93, v140
	ds_read_b128 v[116:119], v134
	ds_read_b128 v[124:127], v134 offset:1024
	ds_read_b128 v[200:203], v134 offset:2048
	ds_read_b128 v[204:207], v134 offset:3072
	ds_read_b128 v[216:219], v135
	ds_read_b128 v[220:223], v135 offset:1024
	ds_read_b128 v[224:227], v135 offset:2048
	ds_read_b128 v[228:231], v135 offset:3072
	s_mov_b32 m0, s78
	s_mov_b64 s[8:9], s[68:69]
	ds_read_b128 v[44:47], v141 offset:40960
	ds_read_b128 v[52:55], v141 offset:41984
	ds_read_b128 v[60:63], v141 offset:43008
	ds_read_b128 v[232:235], v141 offset:44032
	ds_read_b128 v[236:239], v141 offset:45056
	ds_read_b128 v[242:245], v141 offset:46080
	ds_read_b128 v[246:249], v141 offset:47104
	ds_read_b128 v[250:253], v141 offset:48128
	s_nop 0
	global_load_lds_dwordx4 v137, s[8:9]
	s_mov_b32 m0, s79
	s_nop 0
	global_load_lds_dwordx4 v136, s[8:9]
	s_add_u32 s8, s68, s20
	s_addc_u32 s9, s69, s21
	s_mov_b32 m0, s80
	s_nop 0
	global_load_lds_dwordx4 v137, s[8:9]
	s_mov_b32 m0, s81
	s_nop 0
	global_load_lds_dwordx4 v136, s[8:9]
	s_waitcnt vmcnt(8)
	s_waitcnt lgkmcnt(0)
	s_barrier
	s_setprio 1
	s_waitcnt lgkmcnt(0)
	v_mfma_f32_16x16x32_bf16 v[4:7], v[116:119], v[44:47], v[68:71]
	v_mfma_f32_16x16x32_bf16 v[4:7], v[124:127], v[52:55], v[4:7]
	v_mfma_f32_16x16x32_bf16 v[8:11], v[200:203], v[44:47], v[72:75]
	v_mfma_f32_16x16x32_bf16 v[8:11], v[204:207], v[52:55], v[8:11]
	v_mfma_f32_16x16x32_bf16 v[12:15], v[116:119], v[60:63], v[76:79]
	v_mfma_f32_16x16x32_bf16 v[12:15], v[124:127], v[232:235], v[12:15]
	v_mfma_f32_16x16x32_bf16 v[16:19], v[200:203], v[60:63], v[80:83]
	v_mfma_f32_16x16x32_bf16 v[16:19], v[204:207], v[232:235], v[16:19]
	v_mfma_f32_16x16x32_bf16 v[20:23], v[116:119], v[236:239], v[84:87]
	v_mfma_f32_16x16x32_bf16 v[20:23], v[124:127], v[242:245], v[20:23]
	v_mfma_f32_16x16x32_bf16 v[24:27], v[200:203], v[236:239], v[88:91]
	v_mfma_f32_16x16x32_bf16 v[24:27], v[204:207], v[242:245], v[24:27]
	v_mfma_f32_16x16x32_bf16 v[28:31], v[116:119], v[246:249], v[92:95]
	v_mfma_f32_16x16x32_bf16 v[28:31], v[124:127], v[250:253], v[28:31]
	v_mfma_f32_16x16x32_bf16 v[32:35], v[200:203], v[246:249], v[96:99]
	v_mfma_f32_16x16x32_bf16 v[32:35], v[204:207], v[250:253], v[32:35]
	s_setprio 0
	s_setprio 1
	v_mfma_f32_16x16x32_bf16 v[36:39], v[216:219], v[44:47], v[100:103]
	v_mfma_f32_16x16x32_bf16 v[40:43], v[224:227], v[44:47], v[40:43]
	v_mfma_f32_16x16x32_bf16 v[36:39], v[220:223], v[52:55], v[36:39]
	v_mfma_f32_16x16x32_bf16 v[40:43], v[228:231], v[52:55], v[40:43]
	v_mfma_f32_16x16x32_bf16 v[44:47], v[216:219], v[60:63], v[104:107]
	v_mfma_f32_16x16x32_bf16 v[48:51], v[224:227], v[60:63], v[48:51]
	v_mfma_f32_16x16x32_bf16 v[52:55], v[216:219], v[236:239], v[108:111]
	v_mfma_f32_16x16x32_bf16 v[56:59], v[224:227], v[236:239], v[56:59]
	v_mfma_f32_16x16x32_bf16 v[60:63], v[216:219], v[246:249], v[112:115]
	v_mfma_f32_16x16x32_bf16 v[64:67], v[224:227], v[246:249], v[64:67]
	v_mfma_f32_16x16x32_bf16 v[44:47], v[220:223], v[232:235], v[44:47]
	v_mfma_f32_16x16x32_bf16 v[48:51], v[228:231], v[232:235], v[48:51]
	v_mfma_f32_16x16x32_bf16 v[52:55], v[220:223], v[242:245], v[52:55]
	v_mfma_f32_16x16x32_bf16 v[56:59], v[228:231], v[242:245], v[56:59]
	v_mfma_f32_16x16x32_bf16 v[60:63], v[220:223], v[250:253], v[60:63]
	v_mfma_f32_16x16x32_bf16 v[64:67], v[228:231], v[250:253], v[64:67]
	s_setprio 0
	s_barrier
	s_add_i32 s68, s16, s77
	s_mov_b64 s[8:9], s[18:19]
	s_mov_b32 m0, s68
	s_add_i32 s69, s68, 0x2000
	ds_read_b128 v[104:107], v141 offset:57344
	ds_read_b128 v[108:111], v141 offset:58368
	ds_read_b128 v[112:115], v141 offset:59392
	ds_read_b128 v[232:235], v141 offset:60416
	ds_read_b128 v[236:239], v141 offset:61440
	ds_read_b128 v[242:245], v141 offset:62464
	ds_read_b128 v[246:249], v141 offset:63488
	ds_read_b128 v[250:253], v141 offset:64512
	s_nop 0
	global_load_lds_dwordx4 v143, s[8:9]
	s_mov_b32 m0, s69
	s_nop 0
	global_load_lds_dwordx4 v142, s[8:9]
	s_add_u32 s8, s18, s20
	s_addc_u32 s9, s19, s21
	s_add_i32 s93, s93, s77
	s_mov_b32 m0, s93
	s_add_i32 s94, s93, 0x2000
	s_nop 0
	global_load_lds_dwordx4 v143, s[8:9]
	s_mov_b32 m0, s94
	s_nop 0
	global_load_lds_dwordx4 v142, s[8:9]
	s_waitcnt vmcnt(6)
	s_waitcnt lgkmcnt(0)
	s_barrier
	s_setprio 1
	s_waitcnt lgkmcnt(0)
	v_mfma_f32_16x16x32_bf16 v[68:71], v[116:119], v[104:107], v[144:147]
	v_mfma_f32_16x16x32_bf16 v[68:71], v[124:127], v[108:111], v[68:71]
	v_mfma_f32_16x16x32_bf16 v[72:75], v[200:203], v[104:107], v[148:151]
	v_mfma_f32_16x16x32_bf16 v[72:75], v[204:207], v[108:111], v[72:75]
	v_mfma_f32_16x16x32_bf16 v[76:79], v[116:119], v[112:115], v[152:155]
	v_mfma_f32_16x16x32_bf16 v[76:79], v[124:127], v[232:235], v[76:79]
	v_mfma_f32_16x16x32_bf16 v[80:83], v[200:203], v[112:115], v[156:159]
	v_mfma_f32_16x16x32_bf16 v[80:83], v[204:207], v[232:235], v[80:83]
	v_mfma_f32_16x16x32_bf16 v[84:87], v[116:119], v[236:239], v[160:163]
	v_mfma_f32_16x16x32_bf16 v[84:87], v[124:127], v[242:245], v[84:87]
	v_mfma_f32_16x16x32_bf16 v[88:91], v[200:203], v[236:239], v[164:167]
	v_mfma_f32_16x16x32_bf16 v[88:91], v[204:207], v[242:245], v[88:91]
	v_mfma_f32_16x16x32_bf16 v[92:95], v[116:119], v[246:249], v[168:171]
	v_mfma_f32_16x16x32_bf16 v[92:95], v[124:127], v[250:253], v[92:95]
	v_mfma_f32_16x16x32_bf16 v[96:99], v[200:203], v[246:249], v[172:175]
	v_mfma_f32_16x16x32_bf16 v[96:99], v[204:207], v[250:253], v[96:99]
	s_setprio 0
	s_setprio 1
	v_mfma_f32_16x16x32_bf16 v[100:103], v[216:219], v[104:107], v[176:179]
	v_mfma_f32_16x16x32_bf16 v[104:107], v[224:227], v[104:107], v[180:183]
	v_mfma_f32_16x16x32_bf16 v[100:103], v[220:223], v[108:111], v[100:103]
	v_mfma_f32_16x16x32_bf16 v[104:107], v[228:231], v[108:111], v[104:107]
	v_mfma_f32_16x16x32_bf16 v[108:111], v[216:219], v[112:115], v[184:187]
	v_mfma_f32_16x16x32_bf16 v[112:115], v[224:227], v[112:115], v[188:191]
	v_mfma_f32_16x16x32_bf16 v[116:119], v[216:219], v[236:239], v[192:195]
	v_mfma_f32_16x16x32_bf16 v[120:123], v[224:227], v[236:239], v[120:123]
	v_mfma_f32_16x16x32_bf16 v[124:127], v[216:219], v[246:249], v[196:199]
	v_mfma_f32_16x16x32_bf16 v[128:131], v[224:227], v[246:249], v[128:131]
	v_mfma_f32_16x16x32_bf16 v[108:111], v[220:223], v[232:235], v[108:111]
	v_mfma_f32_16x16x32_bf16 v[112:115], v[228:231], v[232:235], v[112:115]
	v_mfma_f32_16x16x32_bf16 v[116:119], v[220:223], v[242:245], v[116:119]
	v_mfma_f32_16x16x32_bf16 v[120:123], v[228:231], v[242:245], v[120:123]
	v_mfma_f32_16x16x32_bf16 v[124:127], v[220:223], v[250:253], v[124:127]
	v_mfma_f32_16x16x32_bf16 v[128:131], v[228:231], v[250:253], v[128:131]
	s_setprio 0
	s_barrier
	s_andn2_b64 vcc, exec, s[60:61]
	s_cbranch_vccnz .LBB0_1023
	s_add_u32 s95, s66, 0x200
	s_addc_u32 s96, s67, 0
	s_add_u32 s72, s72, 0x200
	s_addc_u32 s73, s73, 0
	s_mov_b32 s97, 4
.LBB0_1021:
	ds_read_b128 v[144:147], v132
	ds_read_b128 v[148:151], v132 offset:1024
	ds_read_b128 v[152:155], v132 offset:2048
	ds_read_b128 v[156:159], v132 offset:3072
	ds_read_b128 v[160:163], v133
	ds_read_b128 v[164:167], v133 offset:1024
	ds_read_b128 v[168:171], v133 offset:2048
	ds_read_b128 v[172:175], v133 offset:3072
	s_cmp_eq_u32 s76, s97
	s_cselect_b32 s17, s43, s96
	s_cselect_b32 s16, s42, s95
	s_cselect_b32 s67, s65, s73
	s_cselect_b32 s66, s64, s72
	s_add_u32 s8, s72, 0xffffff80
	s_addc_u32 s9, s73, -1
	s_mov_b32 m0, s85
	s_mov_b64 s[18:19], s[8:9]
	ds_read_b128 v[176:179], v141 offset:8192
	ds_read_b128 v[180:183], v141 offset:9216
	ds_read_b128 v[184:187], v141 offset:10240
	ds_read_b128 v[188:191], v141 offset:11264
	ds_read_b128 v[192:195], v141 offset:12288
	ds_read_b128 v[196:199], v141 offset:13312
	ds_read_b128 v[200:203], v141 offset:14336
	ds_read_b128 v[204:207], v141 offset:15360
	s_add_u32 s8, s8, s20
	global_load_lds_dwordx4 v137, s[18:19]
	s_mov_b32 m0, s86
	s_addc_u32 s9, s9, s21
	global_load_lds_dwordx4 v136, s[18:19]
	s_mov_b32 m0, s87
	s_add_u32 s18, s16, 0x80
	global_load_lds_dwordx4 v137, s[8:9]
	s_mov_b32 m0, s88
	s_addc_u32 s19, s17, 0
	global_load_lds_dwordx4 v136, s[8:9]
	s_waitcnt vmcnt(8)
	s_waitcnt lgkmcnt(0)
	s_barrier
	s_setprio 1
	s_waitcnt lgkmcnt(0)
	v_mfma_f32_16x16x32_bf16 v[4:7], v[144:147], v[176:179], v[4:7]
	v_mfma_f32_16x16x32_bf16 v[4:7], v[148:151], v[180:183], v[4:7]
	v_mfma_f32_16x16x32_bf16 v[8:11], v[152:155], v[176:179], v[8:11]
	v_mfma_f32_16x16x32_bf16 v[8:11], v[156:159], v[180:183], v[8:11]
	v_mfma_f32_16x16x32_bf16 v[12:15], v[144:147], v[184:187], v[12:15]
	v_mfma_f32_16x16x32_bf16 v[12:15], v[148:151], v[188:191], v[12:15]
	v_mfma_f32_16x16x32_bf16 v[16:19], v[152:155], v[184:187], v[16:19]
	v_mfma_f32_16x16x32_bf16 v[16:19], v[156:159], v[188:191], v[16:19]
	v_mfma_f32_16x16x32_bf16 v[20:23], v[144:147], v[192:195], v[20:23]
	v_mfma_f32_16x16x32_bf16 v[20:23], v[148:151], v[196:199], v[20:23]
	v_mfma_f32_16x16x32_bf16 v[24:27], v[152:155], v[192:195], v[24:27]
	v_mfma_f32_16x16x32_bf16 v[24:27], v[156:159], v[196:199], v[24:27]
	v_mfma_f32_16x16x32_bf16 v[28:31], v[144:147], v[200:203], v[28:31]
	v_mfma_f32_16x16x32_bf16 v[28:31], v[148:151], v[204:207], v[28:31]
	v_mfma_f32_16x16x32_bf16 v[32:35], v[152:155], v[200:203], v[32:35]
	v_mfma_f32_16x16x32_bf16 v[32:35], v[156:159], v[204:207], v[32:35]
	s_setprio 0
	s_setprio 1
	v_mfma_f32_16x16x32_bf16 v[36:39], v[160:163], v[176:179], v[36:39]
	v_mfma_f32_16x16x32_bf16 v[36:39], v[164:167], v[180:183], v[36:39]
	v_mfma_f32_16x16x32_bf16 v[40:43], v[168:171], v[176:179], v[40:43]
	v_mfma_f32_16x16x32_bf16 v[40:43], v[172:175], v[180:183], v[40:43]
	v_mfma_f32_16x16x32_bf16 v[44:47], v[160:163], v[184:187], v[44:47]
	v_mfma_f32_16x16x32_bf16 v[44:47], v[164:167], v[188:191], v[44:47]
	v_mfma_f32_16x16x32_bf16 v[48:51], v[168:171], v[184:187], v[48:51]
	v_mfma_f32_16x16x32_bf16 v[48:51], v[172:175], v[188:191], v[48:51]
	v_mfma_f32_16x16x32_bf16 v[52:55], v[160:163], v[192:195], v[52:55]
	v_mfma_f32_16x16x32_bf16 v[52:55], v[164:167], v[196:199], v[52:55]
	v_mfma_f32_16x16x32_bf16 v[56:59], v[168:171], v[192:195], v[56:59]
	v_mfma_f32_16x16x32_bf16 v[56:59], v[172:175], v[196:199], v[56:59]
	v_mfma_f32_16x16x32_bf16 v[60:63], v[160:163], v[200:203], v[60:63]
	v_mfma_f32_16x16x32_bf16 v[60:63], v[164:167], v[204:207], v[60:63]
	v_mfma_f32_16x16x32_bf16 v[64:67], v[168:171], v[200:203], v[64:67]
	v_mfma_f32_16x16x32_bf16 v[64:67], v[172:175], v[204:207], v[64:67]
	s_setprio 0
	s_barrier
	s_mov_b32 m0, s89
	s_mov_b64 s[8:9], s[16:17]
	ds_read_b128 v[176:179], v141 offset:24576
	ds_read_b128 v[180:183], v141 offset:25600
	ds_read_b128 v[184:187], v141 offset:26624
	ds_read_b128 v[188:191], v141 offset:27648
	ds_read_b128 v[192:195], v141 offset:28672
	ds_read_b128 v[196:199], v141 offset:29696
	ds_read_b128 v[200:203], v141 offset:30720
	ds_read_b128 v[204:207], v141 offset:31744
	s_nop 0
	global_load_lds_dwordx4 v143, s[8:9]
	s_mov_b32 m0, s90
	s_nop 0
	global_load_lds_dwordx4 v142, s[8:9]
	s_add_u32 s8, s16, s20
	s_addc_u32 s9, s17, s21
	s_mov_b32 m0, s91
	s_nop 0
	global_load_lds_dwordx4 v143, s[8:9]
	s_mov_b32 m0, s92
	s_nop 0
	global_load_lds_dwordx4 v142, s[8:9]
	s_waitcnt vmcnt(6)
	s_waitcnt lgkmcnt(0)
	s_barrier
	s_setprio 1
	s_waitcnt lgkmcnt(0)
	v_mfma_f32_16x16x32_bf16 v[68:71], v[144:147], v[176:179], v[68:71]
	v_mfma_f32_16x16x32_bf16 v[68:71], v[148:151], v[180:183], v[68:71]
	v_mfma_f32_16x16x32_bf16 v[72:75], v[152:155], v[176:179], v[72:75]
	v_mfma_f32_16x16x32_bf16 v[72:75], v[156:159], v[180:183], v[72:75]
	v_mfma_f32_16x16x32_bf16 v[76:79], v[144:147], v[184:187], v[76:79]
	v_mfma_f32_16x16x32_bf16 v[76:79], v[148:151], v[188:191], v[76:79]
	v_mfma_f32_16x16x32_bf16 v[80:83], v[152:155], v[184:187], v[80:83]
	v_mfma_f32_16x16x32_bf16 v[80:83], v[156:159], v[188:191], v[80:83]
	v_mfma_f32_16x16x32_bf16 v[84:87], v[144:147], v[192:195], v[84:87]
	v_mfma_f32_16x16x32_bf16 v[84:87], v[148:151], v[196:199], v[84:87]
	v_mfma_f32_16x16x32_bf16 v[88:91], v[152:155], v[192:195], v[88:91]
	v_mfma_f32_16x16x32_bf16 v[88:91], v[156:159], v[196:199], v[88:91]
	v_mfma_f32_16x16x32_bf16 v[92:95], v[144:147], v[200:203], v[92:95]
	v_mfma_f32_16x16x32_bf16 v[92:95], v[148:151], v[204:207], v[92:95]
	v_mfma_f32_16x16x32_bf16 v[96:99], v[152:155], v[200:203], v[96:99]
	v_mfma_f32_16x16x32_bf16 v[96:99], v[156:159], v[204:207], v[96:99]
	s_setprio 0
	s_setprio 1
	v_mfma_f32_16x16x32_bf16 v[100:103], v[160:163], v[176:179], v[100:103]
	v_mfma_f32_16x16x32_bf16 v[100:103], v[164:167], v[180:183], v[100:103]
	v_mfma_f32_16x16x32_bf16 v[104:107], v[168:171], v[176:179], v[104:107]
	v_mfma_f32_16x16x32_bf16 v[104:107], v[172:175], v[180:183], v[104:107]
	v_mfma_f32_16x16x32_bf16 v[108:111], v[160:163], v[184:187], v[108:111]
	v_mfma_f32_16x16x32_bf16 v[108:111], v[164:167], v[188:191], v[108:111]
	v_mfma_f32_16x16x32_bf16 v[112:115], v[168:171], v[184:187], v[112:115]
	v_mfma_f32_16x16x32_bf16 v[112:115], v[172:175], v[188:191], v[112:115]
	v_mfma_f32_16x16x32_bf16 v[116:119], v[160:163], v[192:195], v[116:119]
	v_mfma_f32_16x16x32_bf16 v[116:119], v[164:167], v[196:199], v[116:119]
	v_mfma_f32_16x16x32_bf16 v[120:123], v[168:171], v[192:195], v[120:123]
	v_mfma_f32_16x16x32_bf16 v[120:123], v[172:175], v[196:199], v[120:123]
	v_mfma_f32_16x16x32_bf16 v[124:127], v[160:163], v[200:203], v[124:127]
	v_mfma_f32_16x16x32_bf16 v[124:127], v[164:167], v[204:207], v[124:127]
	v_mfma_f32_16x16x32_bf16 v[128:131], v[168:171], v[200:203], v[128:131]
	v_mfma_f32_16x16x32_bf16 v[128:131], v[172:175], v[204:207], v[128:131]
	s_setprio 0
	s_barrier
	ds_read_b128 v[144:147], v134
	ds_read_b128 v[148:151], v134 offset:1024
	ds_read_b128 v[152:155], v134 offset:2048
	ds_read_b128 v[156:159], v134 offset:3072
	ds_read_b128 v[160:163], v135
	ds_read_b128 v[164:167], v135 offset:1024
	ds_read_b128 v[168:171], v135 offset:2048
	ds_read_b128 v[172:175], v135 offset:3072
	s_mov_b32 m0, s78
	s_mov_b64 s[8:9], s[66:67]
	ds_read_b128 v[176:179], v141 offset:40960
	ds_read_b128 v[180:183], v141 offset:41984
	ds_read_b128 v[184:187], v141 offset:43008
	ds_read_b128 v[188:191], v141 offset:44032
	ds_read_b128 v[192:195], v141 offset:45056
	ds_read_b128 v[196:199], v141 offset:46080
	ds_read_b128 v[200:203], v141 offset:47104
	ds_read_b128 v[204:207], v141 offset:48128
	s_nop 0
	global_load_lds_dwordx4 v137, s[8:9]
	s_mov_b32 m0, s79
	s_nop 0
	global_load_lds_dwordx4 v136, s[8:9]
	s_add_u32 s8, s66, s20
	s_addc_u32 s9, s67, s21
	s_mov_b32 m0, s80
	s_nop 0
	global_load_lds_dwordx4 v137, s[8:9]
	s_mov_b32 m0, s81
	s_nop 0
	global_load_lds_dwordx4 v136, s[8:9]
	s_waitcnt vmcnt(8)
	s_waitcnt lgkmcnt(0)
	s_barrier
	s_setprio 1
	s_waitcnt lgkmcnt(0)
	v_mfma_f32_16x16x32_bf16 v[4:7], v[144:147], v[176:179], v[4:7]
	v_mfma_f32_16x16x32_bf16 v[4:7], v[148:151], v[180:183], v[4:7]
	v_mfma_f32_16x16x32_bf16 v[8:11], v[152:155], v[176:179], v[8:11]
	v_mfma_f32_16x16x32_bf16 v[8:11], v[156:159], v[180:183], v[8:11]
	v_mfma_f32_16x16x32_bf16 v[12:15], v[144:147], v[184:187], v[12:15]
	v_mfma_f32_16x16x32_bf16 v[12:15], v[148:151], v[188:191], v[12:15]
	v_mfma_f32_16x16x32_bf16 v[16:19], v[152:155], v[184:187], v[16:19]
	v_mfma_f32_16x16x32_bf16 v[16:19], v[156:159], v[188:191], v[16:19]
	v_mfma_f32_16x16x32_bf16 v[20:23], v[144:147], v[192:195], v[20:23]
	v_mfma_f32_16x16x32_bf16 v[20:23], v[148:151], v[196:199], v[20:23]
	v_mfma_f32_16x16x32_bf16 v[24:27], v[152:155], v[192:195], v[24:27]
	v_mfma_f32_16x16x32_bf16 v[24:27], v[156:159], v[196:199], v[24:27]
	v_mfma_f32_16x16x32_bf16 v[28:31], v[144:147], v[200:203], v[28:31]
	v_mfma_f32_16x16x32_bf16 v[28:31], v[148:151], v[204:207], v[28:31]
	v_mfma_f32_16x16x32_bf16 v[32:35], v[152:155], v[200:203], v[32:35]
	v_mfma_f32_16x16x32_bf16 v[32:35], v[156:159], v[204:207], v[32:35]
	s_setprio 0
	s_setprio 1
	v_mfma_f32_16x16x32_bf16 v[36:39], v[160:163], v[176:179], v[36:39]
	v_mfma_f32_16x16x32_bf16 v[36:39], v[164:167], v[180:183], v[36:39]
	v_mfma_f32_16x16x32_bf16 v[40:43], v[168:171], v[176:179], v[40:43]
	v_mfma_f32_16x16x32_bf16 v[40:43], v[172:175], v[180:183], v[40:43]
	v_mfma_f32_16x16x32_bf16 v[44:47], v[160:163], v[184:187], v[44:47]
	v_mfma_f32_16x16x32_bf16 v[44:47], v[164:167], v[188:191], v[44:47]
	v_mfma_f32_16x16x32_bf16 v[48:51], v[168:171], v[184:187], v[48:51]
	v_mfma_f32_16x16x32_bf16 v[48:51], v[172:175], v[188:191], v[48:51]
	v_mfma_f32_16x16x32_bf16 v[52:55], v[160:163], v[192:195], v[52:55]
	v_mfma_f32_16x16x32_bf16 v[52:55], v[164:167], v[196:199], v[52:55]
	v_mfma_f32_16x16x32_bf16 v[56:59], v[168:171], v[192:195], v[56:59]
	v_mfma_f32_16x16x32_bf16 v[56:59], v[172:175], v[196:199], v[56:59]
	v_mfma_f32_16x16x32_bf16 v[60:63], v[160:163], v[200:203], v[60:63]
	v_mfma_f32_16x16x32_bf16 v[60:63], v[164:167], v[204:207], v[60:63]
	v_mfma_f32_16x16x32_bf16 v[64:67], v[168:171], v[200:203], v[64:67]
	v_mfma_f32_16x16x32_bf16 v[64:67], v[172:175], v[204:207], v[64:67]
	s_setprio 0
	s_barrier
	s_mov_b32 m0, s68
	s_mov_b64 s[8:9], s[18:19]
	ds_read_b128 v[176:179], v141 offset:57344
	ds_read_b128 v[180:183], v141 offset:58368
	ds_read_b128 v[184:187], v141 offset:59392
	ds_read_b128 v[188:191], v141 offset:60416
	ds_read_b128 v[192:195], v141 offset:61440
	ds_read_b128 v[196:199], v141 offset:62464
	ds_read_b128 v[200:203], v141 offset:63488
	ds_read_b128 v[204:207], v141 offset:64512
	s_nop 0
	global_load_lds_dwordx4 v143, s[8:9]
	s_mov_b32 m0, s69
	s_nop 0
	global_load_lds_dwordx4 v142, s[8:9]
	s_add_u32 s8, s18, s20
	s_addc_u32 s9, s19, s21
	s_mov_b32 m0, s93
	s_nop 0
	global_load_lds_dwordx4 v143, s[8:9]
	s_mov_b32 m0, s94
	s_nop 0
	global_load_lds_dwordx4 v142, s[8:9]
	s_waitcnt vmcnt(6)
	s_waitcnt lgkmcnt(0)
	s_barrier
	s_setprio 1
	s_waitcnt lgkmcnt(0)
	v_mfma_f32_16x16x32_bf16 v[68:71], v[144:147], v[176:179], v[68:71]
	v_mfma_f32_16x16x32_bf16 v[68:71], v[148:151], v[180:183], v[68:71]
	v_mfma_f32_16x16x32_bf16 v[72:75], v[152:155], v[176:179], v[72:75]
	v_mfma_f32_16x16x32_bf16 v[72:75], v[156:159], v[180:183], v[72:75]
	v_mfma_f32_16x16x32_bf16 v[76:79], v[144:147], v[184:187], v[76:79]
	v_mfma_f32_16x16x32_bf16 v[76:79], v[148:151], v[188:191], v[76:79]
	v_mfma_f32_16x16x32_bf16 v[80:83], v[152:155], v[184:187], v[80:83]
	v_mfma_f32_16x16x32_bf16 v[80:83], v[156:159], v[188:191], v[80:83]
	v_mfma_f32_16x16x32_bf16 v[84:87], v[144:147], v[192:195], v[84:87]
	v_mfma_f32_16x16x32_bf16 v[84:87], v[148:151], v[196:199], v[84:87]
	v_mfma_f32_16x16x32_bf16 v[88:91], v[152:155], v[192:195], v[88:91]
	v_mfma_f32_16x16x32_bf16 v[88:91], v[156:159], v[196:199], v[88:91]
	v_mfma_f32_16x16x32_bf16 v[92:95], v[144:147], v[200:203], v[92:95]
	v_mfma_f32_16x16x32_bf16 v[92:95], v[148:151], v[204:207], v[92:95]
	v_mfma_f32_16x16x32_bf16 v[96:99], v[152:155], v[200:203], v[96:99]
	v_mfma_f32_16x16x32_bf16 v[96:99], v[156:159], v[204:207], v[96:99]
	s_setprio 0
	s_setprio 1
	v_mfma_f32_16x16x32_bf16 v[100:103], v[160:163], v[176:179], v[100:103]
	v_mfma_f32_16x16x32_bf16 v[100:103], v[164:167], v[180:183], v[100:103]
	v_mfma_f32_16x16x32_bf16 v[104:107], v[168:171], v[176:179], v[104:107]
	v_mfma_f32_16x16x32_bf16 v[104:107], v[172:175], v[180:183], v[104:107]
	v_mfma_f32_16x16x32_bf16 v[108:111], v[160:163], v[184:187], v[108:111]
	v_mfma_f32_16x16x32_bf16 v[108:111], v[164:167], v[188:191], v[108:111]
	v_mfma_f32_16x16x32_bf16 v[112:115], v[168:171], v[184:187], v[112:115]
	v_mfma_f32_16x16x32_bf16 v[112:115], v[172:175], v[188:191], v[112:115]
	v_mfma_f32_16x16x32_bf16 v[116:119], v[160:163], v[192:195], v[116:119]
	v_mfma_f32_16x16x32_bf16 v[116:119], v[164:167], v[196:199], v[116:119]
	v_mfma_f32_16x16x32_bf16 v[120:123], v[168:171], v[192:195], v[120:123]
	v_mfma_f32_16x16x32_bf16 v[120:123], v[172:175], v[196:199], v[120:123]
	v_mfma_f32_16x16x32_bf16 v[124:127], v[160:163], v[200:203], v[124:127]
	v_mfma_f32_16x16x32_bf16 v[124:127], v[164:167], v[204:207], v[124:127]
	v_mfma_f32_16x16x32_bf16 v[128:131], v[168:171], v[200:203], v[128:131]
	v_mfma_f32_16x16x32_bf16 v[128:131], v[172:175], v[204:207], v[128:131]
	s_setprio 0
	s_barrier
	s_add_i32 s8, s97, 2
	s_add_u32 s95, s95, 0x100
	s_addc_u32 s96, s96, 0
	s_add_u32 s72, s72, 0x100
	s_addc_u32 s73, s73, 0
	s_cmp_ge_i32 s97, s76
	s_mov_b32 s97, s8
	s_cbranch_scc0 .LBB0_1021
	v_readlane_b32 s96, v255, 41
	v_readlane_b32 s97, v255, 42

.LBB0_1040:
	s_add_u32 s18, s66, 0x100
	s_addc_u32 s19, s67, 0
	s_add_u32 s16, s64, 0x100
	s_addc_u32 s17, s65, 0
	s_and_b64 s[8:9], s[30:31], exec
	s_cselect_b32 s17, s43, s17
	s_cselect_b32 s16, s42, s16
	s_add_i32 s87, 0, 0x10000
	s_and_b64 s[8:9], s[30:31], exec
	s_cselect_b32 s69, s41, s19
	s_cselect_b32 s68, s40, s18
	s_add_i32 s89, 0, 0x14000
	v_add_u32_e32 v132, s87, v140
	v_add_u32_e32 v133, s89, v140
	ds_read_b128 v[4:7], v132
	ds_read_b128 v[8:11], v132 offset:1024
	ds_read_b128 v[12:15], v132 offset:2048
	ds_read_b128 v[16:19], v132 offset:3072
	ds_read_b128 v[20:23], v133
	ds_read_b128 v[24:27], v133 offset:1024
	ds_read_b128 v[28:31], v133 offset:2048
	ds_read_b128 v[32:35], v133 offset:3072
	s_add_u32 s8, s66, 0x80
	s_addc_u32 s9, s67, 0
	s_add_i32 s83, s76, 0x8000
	s_add_i32 s84, s76, 0xa000
	s_mov_b64 s[18:19], s[8:9]
	s_mov_b32 m0, s83
	s_add_u32 s8, s8, s20
	ds_read_b128 v[36:39], v141
	ds_read_b128 v[40:43], v141 offset:1024
	ds_read_b128 v[44:47], v141 offset:2048
	ds_read_b128 v[48:51], v141 offset:3072
	ds_read_b128 v[52:55], v141 offset:4096
	ds_read_b128 v[56:59], v141 offset:5120
	ds_read_b128 v[60:63], v141 offset:6144
	ds_read_b128 v[64:67], v141 offset:7168
	s_addc_u32 s9, s9, s21
	global_load_lds_dwordx4 v137, s[18:19]
	s_mov_b32 m0, s84
	s_add_i32 s85, s76, 0xc000
	global_load_lds_dwordx4 v136, s[18:19]
	s_mov_b32 m0, s85
	s_add_i32 s86, s76, 0xe000
	s_add_u32 s18, s16, 0x80
	global_load_lds_dwordx4 v137, s[8:9]
	s_mov_b32 m0, s86
	s_addc_u32 s19, s17, 0
	global_load_lds_dwordx4 v136, s[8:9]
	s_waitcnt vmcnt(8)
	s_waitcnt lgkmcnt(0)
	s_barrier
	s_setprio 1
	s_waitcnt lgkmcnt(0)
	v_mfma_f32_16x16x32_bf16 v[68:71], v[4:7], v[36:39], 0
	v_mfma_f32_16x16x32_bf16 v[72:75], v[12:15], v[36:39], 0
	v_mfma_f32_16x16x32_bf16 v[76:79], v[4:7], v[44:47], 0
	v_mfma_f32_16x16x32_bf16 v[80:83], v[12:15], v[44:47], 0
	v_mfma_f32_16x16x32_bf16 v[84:87], v[4:7], v[52:55], 0
	v_mfma_f32_16x16x32_bf16 v[88:91], v[12:15], v[52:55], 0
	v_mfma_f32_16x16x32_bf16 v[92:95], v[4:7], v[60:63], 0
	v_mfma_f32_16x16x32_bf16 v[96:99], v[12:15], v[60:63], 0
	v_mfma_f32_16x16x32_bf16 v[68:71], v[8:11], v[40:43], v[68:71]
	v_mfma_f32_16x16x32_bf16 v[72:75], v[16:19], v[40:43], v[72:75]
	v_mfma_f32_16x16x32_bf16 v[76:79], v[8:11], v[48:51], v[76:79]
	v_mfma_f32_16x16x32_bf16 v[80:83], v[16:19], v[48:51], v[80:83]
	v_mfma_f32_16x16x32_bf16 v[84:87], v[8:11], v[56:59], v[84:87]
	v_mfma_f32_16x16x32_bf16 v[88:91], v[16:19], v[56:59], v[88:91]
	v_mfma_f32_16x16x32_bf16 v[92:95], v[8:11], v[64:67], v[92:95]
	v_mfma_f32_16x16x32_bf16 v[96:99], v[16:19], v[64:67], v[96:99]
	s_setprio 0
	s_setprio 1
	v_mfma_f32_16x16x32_bf16 v[100:103], v[20:23], v[36:39], 0
	v_mfma_f32_16x16x32_bf16 v[36:39], v[28:31], v[36:39], 0
	v_mfma_f32_16x16x32_bf16 v[100:103], v[24:27], v[40:43], v[100:103]
	v_mfma_f32_16x16x32_bf16 v[40:43], v[32:35], v[40:43], v[36:39]
	v_mfma_f32_16x16x32_bf16 v[36:39], v[20:23], v[44:47], 0
	v_mfma_f32_16x16x32_bf16 v[104:107], v[24:27], v[48:51], v[36:39]
	v_mfma_f32_16x16x32_bf16 v[36:39], v[28:31], v[44:47], 0
	v_mfma_f32_16x16x32_bf16 v[48:51], v[32:35], v[48:51], v[36:39]
	v_mfma_f32_16x16x32_bf16 v[36:39], v[20:23], v[52:55], 0
	v_mfma_f32_16x16x32_bf16 v[108:111], v[24:27], v[56:59], v[36:39]
	v_mfma_f32_16x16x32_bf16 v[36:39], v[28:31], v[52:55], 0
	v_mfma_f32_16x16x32_bf16 v[56:59], v[32:35], v[56:59], v[36:39]
	v_mfma_f32_16x16x32_bf16 v[36:39], v[20:23], v[60:63], 0
	v_mfma_f32_16x16x32_bf16 v[112:115], v[24:27], v[64:67], v[36:39]
	v_mfma_f32_16x16x32_bf16 v[36:39], v[28:31], v[60:63], 0
	v_mfma_f32_16x16x32_bf16 v[64:67], v[32:35], v[64:67], v[36:39]
	s_setprio 0
	s_barrier
	s_add_i32 s87, s87, s73
	s_mov_b64 s[8:9], s[16:17]
	s_mov_b32 m0, s87
	s_add_i32 s88, s87, 0x2000
	s_nop 0
	ds_read_b128 v[36:39], v141 offset:16384
	ds_read_b128 v[44:47], v141 offset:17408
	ds_read_b128 v[52:55], v141 offset:18432
	ds_read_b128 v[60:63], v141 offset:19456
	ds_read_b128 v[116:119], v141 offset:20480
	ds_read_b128 v[120:123], v141 offset:21504
	ds_read_b128 v[124:127], v141 offset:22528
	ds_read_b128 v[128:131], v141 offset:23552
	s_nop 0
	global_load_lds_dwordx4 v143, s[8:9]
	s_mov_b32 m0, s88
	s_nop 0
	global_load_lds_dwordx4 v142, s[8:9]
	s_add_u32 s8, s16, s20
	s_addc_u32 s9, s17, s21
	s_add_i32 s89, s89, s73
	s_mov_b32 m0, s89
	s_add_i32 s90, s89, 0x2000
	s_nop 0
	global_load_lds_dwordx4 v143, s[8:9]
	s_mov_b32 m0, s90
	s_nop 0
	global_load_lds_dwordx4 v142, s[8:9]
	s_waitcnt vmcnt(6)
	s_waitcnt lgkmcnt(0)
	s_barrier
	s_setprio 1
	s_waitcnt lgkmcnt(0)
	v_mfma_f32_16x16x32_bf16 v[144:147], v[4:7], v[36:39], 0
	v_mfma_f32_16x16x32_bf16 v[152:155], v[4:7], v[52:55], 0
	v_mfma_f32_16x16x32_bf16 v[160:163], v[4:7], v[116:119], 0
	v_mfma_f32_16x16x32_bf16 v[4:7], v[4:7], v[124:127], 0
	v_mfma_f32_16x16x32_bf16 v[148:151], v[12:15], v[36:39], 0
	v_mfma_f32_16x16x32_bf16 v[156:159], v[12:15], v[52:55], 0
	v_mfma_f32_16x16x32_bf16 v[164:167], v[12:15], v[116:119], 0
	v_mfma_f32_16x16x32_bf16 v[168:171], v[8:11], v[128:131], v[4:7]
	v_mfma_f32_16x16x32_bf16 v[4:7], v[12:15], v[124:127], 0
	v_mfma_f32_16x16x32_bf16 v[144:147], v[8:11], v[44:47], v[144:147]
	v_mfma_f32_16x16x32_bf16 v[148:151], v[16:19], v[44:47], v[148:151]
	v_mfma_f32_16x16x32_bf16 v[152:155], v[8:11], v[60:63], v[152:155]
	v_mfma_f32_16x16x32_bf16 v[156:159], v[16:19], v[60:63], v[156:159]
	v_mfma_f32_16x16x32_bf16 v[160:163], v[8:11], v[120:123], v[160:163]
	v_mfma_f32_16x16x32_bf16 v[164:167], v[16:19], v[120:123], v[164:167]
	v_mfma_f32_16x16x32_bf16 v[172:175], v[16:19], v[128:131], v[4:7]
	s_setprio 0
	s_setprio 1
	v_mfma_f32_16x16x32_bf16 v[4:7], v[20:23], v[36:39], 0
	v_mfma_f32_16x16x32_bf16 v[176:179], v[24:27], v[44:47], v[4:7]
	v_mfma_f32_16x16x32_bf16 v[4:7], v[28:31], v[36:39], 0
	v_mfma_f32_16x16x32_bf16 v[180:183], v[32:35], v[44:47], v[4:7]
	v_mfma_f32_16x16x32_bf16 v[4:7], v[20:23], v[52:55], 0
	v_mfma_f32_16x16x32_bf16 v[184:187], v[24:27], v[60:63], v[4:7]
	v_mfma_f32_16x16x32_bf16 v[4:7], v[28:31], v[52:55], 0
	v_mfma_f32_16x16x32_bf16 v[188:191], v[32:35], v[60:63], v[4:7]
	v_mfma_f32_16x16x32_bf16 v[4:7], v[20:23], v[116:119], 0
	v_mfma_f32_16x16x32_bf16 v[192:195], v[24:27], v[120:123], v[4:7]
	v_mfma_f32_16x16x32_bf16 v[4:7], v[28:31], v[116:119], 0
	v_mfma_f32_16x16x32_bf16 v[120:123], v[32:35], v[120:123], v[4:7]
	v_mfma_f32_16x16x32_bf16 v[4:7], v[20:23], v[124:127], 0
	v_mfma_f32_16x16x32_bf16 v[196:199], v[24:27], v[128:131], v[4:7]
	v_mfma_f32_16x16x32_bf16 v[4:7], v[28:31], v[124:127], 0
	v_mfma_f32_16x16x32_bf16 v[128:131], v[32:35], v[128:131], v[4:7]
	s_setprio 0
	s_barrier
	s_add_i32 s16, 0, 0x18000
	s_add_i32 s91, 0, 0x1c000
	v_add_u32_e32 v134, s16, v140
	v_add_u32_e32 v135, s91, v140
	ds_read_b128 v[116:119], v134
	ds_read_b128 v[124:127], v134 offset:1024
	ds_read_b128 v[200:203], v134 offset:2048
	ds_read_b128 v[204:207], v134 offset:3072
	ds_read_b128 v[216:219], v135
	ds_read_b128 v[220:223], v135 offset:1024
	ds_read_b128 v[224:227], v135 offset:2048
	ds_read_b128 v[228:231], v135 offset:3072
	s_mov_b32 m0, s76
	s_mov_b64 s[8:9], s[68:69]
	ds_read_b128 v[44:47], v141 offset:32768
	ds_read_b128 v[52:55], v141 offset:33792
	ds_read_b128 v[60:63], v141 offset:34816
	ds_read_b128 v[232:235], v141 offset:35840
	ds_read_b128 v[236:239], v141 offset:36864
	ds_read_b128 v[242:245], v141 offset:37888
	ds_read_b128 v[246:249], v141 offset:38912
	ds_read_b128 v[250:253], v141 offset:39936
	s_nop 0
	global_load_lds_dwordx4 v137, s[8:9]
	s_mov_b32 m0, s77
	s_nop 0
	global_load_lds_dwordx4 v136, s[8:9]
	s_add_u32 s8, s68, s20
	s_addc_u32 s9, s69, s21
	s_mov_b32 m0, s78
	s_nop 0
	global_load_lds_dwordx4 v137, s[8:9]
	s_mov_b32 m0, s79
	s_nop 0
	global_load_lds_dwordx4 v136, s[8:9]
	s_waitcnt vmcnt(8)
	s_waitcnt lgkmcnt(0)
	s_barrier
	s_setprio 1
	s_waitcnt lgkmcnt(0)
	v_mfma_f32_16x16x32_bf16 v[4:7], v[116:119], v[44:47], v[68:71]
	v_mfma_f32_16x16x32_bf16 v[4:7], v[124:127], v[52:55], v[4:7]
	v_mfma_f32_16x16x32_bf16 v[8:11], v[200:203], v[44:47], v[72:75]
	v_mfma_f32_16x16x32_bf16 v[8:11], v[204:207], v[52:55], v[8:11]
	v_mfma_f32_16x16x32_bf16 v[12:15], v[116:119], v[60:63], v[76:79]
	v_mfma_f32_16x16x32_bf16 v[12:15], v[124:127], v[232:235], v[12:15]
	v_mfma_f32_16x16x32_bf16 v[16:19], v[200:203], v[60:63], v[80:83]
	v_mfma_f32_16x16x32_bf16 v[16:19], v[204:207], v[232:235], v[16:19]
	v_mfma_f32_16x16x32_bf16 v[20:23], v[116:119], v[236:239], v[84:87]
	v_mfma_f32_16x16x32_bf16 v[20:23], v[124:127], v[242:245], v[20:23]
	v_mfma_f32_16x16x32_bf16 v[24:27], v[200:203], v[236:239], v[88:91]
	v_mfma_f32_16x16x32_bf16 v[24:27], v[204:207], v[242:245], v[24:27]
	v_mfma_f32_16x16x32_bf16 v[28:31], v[116:119], v[246:249], v[92:95]
	v_mfma_f32_16x16x32_bf16 v[28:31], v[124:127], v[250:253], v[28:31]
	v_mfma_f32_16x16x32_bf16 v[32:35], v[200:203], v[246:249], v[96:99]
	v_mfma_f32_16x16x32_bf16 v[32:35], v[204:207], v[250:253], v[32:35]
	s_setprio 0
	s_setprio 1
	v_mfma_f32_16x16x32_bf16 v[36:39], v[216:219], v[44:47], v[100:103]
	v_mfma_f32_16x16x32_bf16 v[40:43], v[224:227], v[44:47], v[40:43]
	v_mfma_f32_16x16x32_bf16 v[36:39], v[220:223], v[52:55], v[36:39]
	v_mfma_f32_16x16x32_bf16 v[40:43], v[228:231], v[52:55], v[40:43]
	v_mfma_f32_16x16x32_bf16 v[44:47], v[216:219], v[60:63], v[104:107]
	v_mfma_f32_16x16x32_bf16 v[48:51], v[224:227], v[60:63], v[48:51]
	v_mfma_f32_16x16x32_bf16 v[52:55], v[216:219], v[236:239], v[108:111]
	v_mfma_f32_16x16x32_bf16 v[56:59], v[224:227], v[236:239], v[56:59]
	v_mfma_f32_16x16x32_bf16 v[60:63], v[216:219], v[246:249], v[112:115]
	v_mfma_f32_16x16x32_bf16 v[64:67], v[224:227], v[246:249], v[64:67]
	v_mfma_f32_16x16x32_bf16 v[44:47], v[220:223], v[232:235], v[44:47]
	v_mfma_f32_16x16x32_bf16 v[48:51], v[228:231], v[232:235], v[48:51]
	v_mfma_f32_16x16x32_bf16 v[52:55], v[220:223], v[242:245], v[52:55]
	v_mfma_f32_16x16x32_bf16 v[56:59], v[228:231], v[242:245], v[56:59]
	v_mfma_f32_16x16x32_bf16 v[60:63], v[220:223], v[250:253], v[60:63]
	v_mfma_f32_16x16x32_bf16 v[64:67], v[228:231], v[250:253], v[64:67]
	s_setprio 0
	s_barrier
	s_add_i32 s68, s16, s73
	s_mov_b64 s[8:9], s[18:19]
	s_mov_b32 m0, s68
	s_add_i32 s69, s68, 0x2000
	ds_read_b128 v[104:107], v141 offset:49152
	ds_read_b128 v[108:111], v141 offset:50176
	ds_read_b128 v[112:115], v141 offset:51200
	ds_read_b128 v[232:235], v141 offset:52224
	ds_read_b128 v[236:239], v141 offset:53248
	ds_read_b128 v[242:245], v141 offset:54272
	ds_read_b128 v[246:249], v141 offset:55296
	ds_read_b128 v[250:253], v141 offset:56320
	s_nop 0
	global_load_lds_dwordx4 v143, s[8:9]
	s_mov_b32 m0, s69
	s_nop 0
	global_load_lds_dwordx4 v142, s[8:9]
	s_add_u32 s8, s18, s20
	s_addc_u32 s9, s19, s21
	s_add_i32 s91, s91, s73
	s_mov_b32 m0, s91
	s_add_i32 s92, s91, 0x2000
	s_nop 0
	global_load_lds_dwordx4 v143, s[8:9]
	s_mov_b32 m0, s92
	s_nop 0
	global_load_lds_dwordx4 v142, s[8:9]
	s_waitcnt vmcnt(6)
	s_waitcnt lgkmcnt(0)
	s_barrier
	s_setprio 1
	s_waitcnt lgkmcnt(0)
	v_mfma_f32_16x16x32_bf16 v[68:71], v[116:119], v[104:107], v[144:147]
	v_mfma_f32_16x16x32_bf16 v[68:71], v[124:127], v[108:111], v[68:71]
	v_mfma_f32_16x16x32_bf16 v[72:75], v[200:203], v[104:107], v[148:151]
	v_mfma_f32_16x16x32_bf16 v[72:75], v[204:207], v[108:111], v[72:75]
	v_mfma_f32_16x16x32_bf16 v[76:79], v[116:119], v[112:115], v[152:155]
	v_mfma_f32_16x16x32_bf16 v[76:79], v[124:127], v[232:235], v[76:79]
	v_mfma_f32_16x16x32_bf16 v[80:83], v[200:203], v[112:115], v[156:159]
	v_mfma_f32_16x16x32_bf16 v[80:83], v[204:207], v[232:235], v[80:83]
	v_mfma_f32_16x16x32_bf16 v[84:87], v[116:119], v[236:239], v[160:163]
	v_mfma_f32_16x16x32_bf16 v[84:87], v[124:127], v[242:245], v[84:87]
	v_mfma_f32_16x16x32_bf16 v[88:91], v[200:203], v[236:239], v[164:167]
	v_mfma_f32_16x16x32_bf16 v[88:91], v[204:207], v[242:245], v[88:91]
	v_mfma_f32_16x16x32_bf16 v[92:95], v[116:119], v[246:249], v[168:171]
	v_mfma_f32_16x16x32_bf16 v[92:95], v[124:127], v[250:253], v[92:95]
	v_mfma_f32_16x16x32_bf16 v[96:99], v[200:203], v[246:249], v[172:175]
	v_mfma_f32_16x16x32_bf16 v[96:99], v[204:207], v[250:253], v[96:99]
	s_setprio 0
	s_setprio 1
	v_mfma_f32_16x16x32_bf16 v[100:103], v[216:219], v[104:107], v[176:179]
	v_mfma_f32_16x16x32_bf16 v[104:107], v[224:227], v[104:107], v[180:183]
	v_mfma_f32_16x16x32_bf16 v[100:103], v[220:223], v[108:111], v[100:103]
	v_mfma_f32_16x16x32_bf16 v[104:107], v[228:231], v[108:111], v[104:107]
	v_mfma_f32_16x16x32_bf16 v[108:111], v[216:219], v[112:115], v[184:187]
	v_mfma_f32_16x16x32_bf16 v[112:115], v[224:227], v[112:115], v[188:191]
	v_mfma_f32_16x16x32_bf16 v[116:119], v[216:219], v[236:239], v[192:195]
	v_mfma_f32_16x16x32_bf16 v[120:123], v[224:227], v[236:239], v[120:123]
	v_mfma_f32_16x16x32_bf16 v[124:127], v[216:219], v[246:249], v[196:199]
	v_mfma_f32_16x16x32_bf16 v[128:131], v[224:227], v[246:249], v[128:131]
	v_mfma_f32_16x16x32_bf16 v[108:111], v[220:223], v[232:235], v[108:111]
	v_mfma_f32_16x16x32_bf16 v[112:115], v[228:231], v[232:235], v[112:115]
	v_mfma_f32_16x16x32_bf16 v[116:119], v[220:223], v[242:245], v[116:119]
	v_mfma_f32_16x16x32_bf16 v[120:123], v[228:231], v[242:245], v[120:123]
	v_mfma_f32_16x16x32_bf16 v[124:127], v[220:223], v[250:253], v[124:127]
	v_mfma_f32_16x16x32_bf16 v[128:131], v[228:231], v[250:253], v[128:131]
	s_setprio 0
	s_barrier
	s_andn2_b64 vcc, exec, s[60:61]
	s_cbranch_vccnz .LBB0_1031
	s_add_u32 s93, s64, 0x200
	s_addc_u32 s94, s65, 0
	s_add_u32 s66, s66, 0x200
	s_addc_u32 s67, s67, 0
	s_mov_b32 s95, 4
.LBB0_1042:
	ds_read_b128 v[144:147], v132
	ds_read_b128 v[148:151], v132 offset:1024
	ds_read_b128 v[152:155], v132 offset:2048
	ds_read_b128 v[156:159], v132 offset:3072
	ds_read_b128 v[160:163], v133
	ds_read_b128 v[164:167], v133 offset:1024
	ds_read_b128 v[168:171], v133 offset:2048
	ds_read_b128 v[172:175], v133 offset:3072
	s_cmp_eq_u32 s72, s95
	s_cselect_b32 s17, s43, s94
	s_cselect_b32 s16, s42, s93
	s_cselect_b32 s65, s41, s67
	s_cselect_b32 s64, s40, s66
	s_add_u32 s8, s66, 0xffffff80
	s_addc_u32 s9, s67, -1
	s_mov_b32 m0, s83
	s_mov_b64 s[18:19], s[8:9]
	ds_read_b128 v[176:179], v141
	ds_read_b128 v[180:183], v141 offset:1024
	ds_read_b128 v[184:187], v141 offset:2048
	ds_read_b128 v[188:191], v141 offset:3072
	ds_read_b128 v[192:195], v141 offset:4096
	ds_read_b128 v[196:199], v141 offset:5120
	ds_read_b128 v[200:203], v141 offset:6144
	ds_read_b128 v[204:207], v141 offset:7168
	s_add_u32 s8, s8, s20
	global_load_lds_dwordx4 v137, s[18:19]
	s_mov_b32 m0, s84
	s_addc_u32 s9, s9, s21
	global_load_lds_dwordx4 v136, s[18:19]
	s_mov_b32 m0, s85
	s_add_u32 s18, s16, 0x80
	global_load_lds_dwordx4 v137, s[8:9]
	s_mov_b32 m0, s86
	s_addc_u32 s19, s17, 0
	global_load_lds_dwordx4 v136, s[8:9]
	s_waitcnt vmcnt(8)
	s_waitcnt lgkmcnt(0)
	s_barrier
	s_setprio 1
	s_waitcnt lgkmcnt(0)
	v_mfma_f32_16x16x32_bf16 v[4:7], v[144:147], v[176:179], v[4:7]
	v_mfma_f32_16x16x32_bf16 v[4:7], v[148:151], v[180:183], v[4:7]
	v_mfma_f32_16x16x32_bf16 v[8:11], v[152:155], v[176:179], v[8:11]
	v_mfma_f32_16x16x32_bf16 v[8:11], v[156:159], v[180:183], v[8:11]
	v_mfma_f32_16x16x32_bf16 v[12:15], v[144:147], v[184:187], v[12:15]
	v_mfma_f32_16x16x32_bf16 v[12:15], v[148:151], v[188:191], v[12:15]
	v_mfma_f32_16x16x32_bf16 v[16:19], v[152:155], v[184:187], v[16:19]
	v_mfma_f32_16x16x32_bf16 v[16:19], v[156:159], v[188:191], v[16:19]
	v_mfma_f32_16x16x32_bf16 v[20:23], v[144:147], v[192:195], v[20:23]
	v_mfma_f32_16x16x32_bf16 v[20:23], v[148:151], v[196:199], v[20:23]
	v_mfma_f32_16x16x32_bf16 v[24:27], v[152:155], v[192:195], v[24:27]
	v_mfma_f32_16x16x32_bf16 v[24:27], v[156:159], v[196:199], v[24:27]
	v_mfma_f32_16x16x32_bf16 v[28:31], v[144:147], v[200:203], v[28:31]
	v_mfma_f32_16x16x32_bf16 v[28:31], v[148:151], v[204:207], v[28:31]
	v_mfma_f32_16x16x32_bf16 v[32:35], v[152:155], v[200:203], v[32:35]
	v_mfma_f32_16x16x32_bf16 v[32:35], v[156:159], v[204:207], v[32:35]
	s_setprio 0
	s_setprio 1
	v_mfma_f32_16x16x32_bf16 v[36:39], v[160:163], v[176:179], v[36:39]
	v_mfma_f32_16x16x32_bf16 v[36:39], v[164:167], v[180:183], v[36:39]
	v_mfma_f32_16x16x32_bf16 v[40:43], v[168:171], v[176:179], v[40:43]
	v_mfma_f32_16x16x32_bf16 v[40:43], v[172:175], v[180:183], v[40:43]
	v_mfma_f32_16x16x32_bf16 v[44:47], v[160:163], v[184:187], v[44:47]
	v_mfma_f32_16x16x32_bf16 v[44:47], v[164:167], v[188:191], v[44:47]
	v_mfma_f32_16x16x32_bf16 v[48:51], v[168:171], v[184:187], v[48:51]
	v_mfma_f32_16x16x32_bf16 v[48:51], v[172:175], v[188:191], v[48:51]
	v_mfma_f32_16x16x32_bf16 v[52:55], v[160:163], v[192:195], v[52:55]
	v_mfma_f32_16x16x32_bf16 v[52:55], v[164:167], v[196:199], v[52:55]
	v_mfma_f32_16x16x32_bf16 v[56:59], v[168:171], v[192:195], v[56:59]
	v_mfma_f32_16x16x32_bf16 v[56:59], v[172:175], v[196:199], v[56:59]
	v_mfma_f32_16x16x32_bf16 v[60:63], v[160:163], v[200:203], v[60:63]
	v_mfma_f32_16x16x32_bf16 v[60:63], v[164:167], v[204:207], v[60:63]
	v_mfma_f32_16x16x32_bf16 v[64:67], v[168:171], v[200:203], v[64:67]
	v_mfma_f32_16x16x32_bf16 v[64:67], v[172:175], v[204:207], v[64:67]
	s_setprio 0
	s_barrier
	s_mov_b32 m0, s87
	s_mov_b64 s[8:9], s[16:17]
	ds_read_b128 v[176:179], v141 offset:16384
	ds_read_b128 v[180:183], v141 offset:17408
	ds_read_b128 v[184:187], v141 offset:18432
	ds_read_b128 v[188:191], v141 offset:19456
	ds_read_b128 v[192:195], v141 offset:20480
	ds_read_b128 v[196:199], v141 offset:21504
	ds_read_b128 v[200:203], v141 offset:22528
	ds_read_b128 v[204:207], v141 offset:23552
	s_nop 0
	global_load_lds_dwordx4 v143, s[8:9]
	s_mov_b32 m0, s88
	s_nop 0
	global_load_lds_dwordx4 v142, s[8:9]
	s_add_u32 s8, s16, s20
	s_addc_u32 s9, s17, s21
	s_mov_b32 m0, s89
	s_nop 0
	global_load_lds_dwordx4 v143, s[8:9]
	s_mov_b32 m0, s90
	s_nop 0
	global_load_lds_dwordx4 v142, s[8:9]
	s_waitcnt vmcnt(6)
	s_waitcnt lgkmcnt(0)
	s_barrier
	s_setprio 1
	s_waitcnt lgkmcnt(0)
	v_mfma_f32_16x16x32_bf16 v[68:71], v[144:147], v[176:179], v[68:71]
	v_mfma_f32_16x16x32_bf16 v[68:71], v[148:151], v[180:183], v[68:71]
	v_mfma_f32_16x16x32_bf16 v[72:75], v[152:155], v[176:179], v[72:75]
	v_mfma_f32_16x16x32_bf16 v[72:75], v[156:159], v[180:183], v[72:75]
	v_mfma_f32_16x16x32_bf16 v[76:79], v[144:147], v[184:187], v[76:79]
	v_mfma_f32_16x16x32_bf16 v[76:79], v[148:151], v[188:191], v[76:79]
	v_mfma_f32_16x16x32_bf16 v[80:83], v[152:155], v[184:187], v[80:83]
	v_mfma_f32_16x16x32_bf16 v[80:83], v[156:159], v[188:191], v[80:83]
	v_mfma_f32_16x16x32_bf16 v[84:87], v[144:147], v[192:195], v[84:87]
	v_mfma_f32_16x16x32_bf16 v[84:87], v[148:151], v[196:199], v[84:87]
	v_mfma_f32_16x16x32_bf16 v[88:91], v[152:155], v[192:195], v[88:91]
	v_mfma_f32_16x16x32_bf16 v[88:91], v[156:159], v[196:199], v[88:91]
	v_mfma_f32_16x16x32_bf16 v[92:95], v[144:147], v[200:203], v[92:95]
	v_mfma_f32_16x16x32_bf16 v[92:95], v[148:151], v[204:207], v[92:95]
	v_mfma_f32_16x16x32_bf16 v[96:99], v[152:155], v[200:203], v[96:99]
	v_mfma_f32_16x16x32_bf16 v[96:99], v[156:159], v[204:207], v[96:99]
	s_setprio 0
	s_setprio 1
	v_mfma_f32_16x16x32_bf16 v[100:103], v[160:163], v[176:179], v[100:103]
	v_mfma_f32_16x16x32_bf16 v[100:103], v[164:167], v[180:183], v[100:103]
	v_mfma_f32_16x16x32_bf16 v[104:107], v[168:171], v[176:179], v[104:107]
	v_mfma_f32_16x16x32_bf16 v[104:107], v[172:175], v[180:183], v[104:107]
	v_mfma_f32_16x16x32_bf16 v[108:111], v[160:163], v[184:187], v[108:111]
	v_mfma_f32_16x16x32_bf16 v[108:111], v[164:167], v[188:191], v[108:111]
	v_mfma_f32_16x16x32_bf16 v[112:115], v[168:171], v[184:187], v[112:115]
	v_mfma_f32_16x16x32_bf16 v[112:115], v[172:175], v[188:191], v[112:115]
	v_mfma_f32_16x16x32_bf16 v[116:119], v[160:163], v[192:195], v[116:119]
	v_mfma_f32_16x16x32_bf16 v[116:119], v[164:167], v[196:199], v[116:119]
	v_mfma_f32_16x16x32_bf16 v[120:123], v[168:171], v[192:195], v[120:123]
	v_mfma_f32_16x16x32_bf16 v[120:123], v[172:175], v[196:199], v[120:123]
	v_mfma_f32_16x16x32_bf16 v[124:127], v[160:163], v[200:203], v[124:127]
	v_mfma_f32_16x16x32_bf16 v[124:127], v[164:167], v[204:207], v[124:127]
	v_mfma_f32_16x16x32_bf16 v[128:131], v[168:171], v[200:203], v[128:131]
	v_mfma_f32_16x16x32_bf16 v[128:131], v[172:175], v[204:207], v[128:131]
	s_setprio 0
	s_barrier
	ds_read_b128 v[144:147], v134
	ds_read_b128 v[148:151], v134 offset:1024
	ds_read_b128 v[152:155], v134 offset:2048
	ds_read_b128 v[156:159], v134 offset:3072
	ds_read_b128 v[160:163], v135
	ds_read_b128 v[164:167], v135 offset:1024
	ds_read_b128 v[168:171], v135 offset:2048
	ds_read_b128 v[172:175], v135 offset:3072
	s_mov_b32 m0, s76
	s_mov_b64 s[8:9], s[64:65]
	ds_read_b128 v[176:179], v141 offset:32768
	ds_read_b128 v[180:183], v141 offset:33792
	ds_read_b128 v[184:187], v141 offset:34816
	ds_read_b128 v[188:191], v141 offset:35840
	ds_read_b128 v[192:195], v141 offset:36864
	ds_read_b128 v[196:199], v141 offset:37888
	ds_read_b128 v[200:203], v141 offset:38912
	ds_read_b128 v[204:207], v141 offset:39936
	s_nop 0
	global_load_lds_dwordx4 v137, s[8:9]
	s_mov_b32 m0, s77
	s_nop 0
	global_load_lds_dwordx4 v136, s[8:9]
	s_add_u32 s8, s64, s20
	s_addc_u32 s9, s65, s21
	s_mov_b32 m0, s78
	s_nop 0
	global_load_lds_dwordx4 v137, s[8:9]
	s_mov_b32 m0, s79
	s_nop 0
	global_load_lds_dwordx4 v136, s[8:9]
	s_waitcnt vmcnt(8)
	s_waitcnt lgkmcnt(0)
	s_barrier
	s_setprio 1
	s_waitcnt lgkmcnt(0)
	v_mfma_f32_16x16x32_bf16 v[4:7], v[144:147], v[176:179], v[4:7]
	v_mfma_f32_16x16x32_bf16 v[4:7], v[148:151], v[180:183], v[4:7]
	v_mfma_f32_16x16x32_bf16 v[8:11], v[152:155], v[176:179], v[8:11]
	v_mfma_f32_16x16x32_bf16 v[8:11], v[156:159], v[180:183], v[8:11]
	v_mfma_f32_16x16x32_bf16 v[12:15], v[144:147], v[184:187], v[12:15]
	v_mfma_f32_16x16x32_bf16 v[12:15], v[148:151], v[188:191], v[12:15]
	v_mfma_f32_16x16x32_bf16 v[16:19], v[152:155], v[184:187], v[16:19]
	v_mfma_f32_16x16x32_bf16 v[16:19], v[156:159], v[188:191], v[16:19]
	v_mfma_f32_16x16x32_bf16 v[20:23], v[144:147], v[192:195], v[20:23]
	v_mfma_f32_16x16x32_bf16 v[20:23], v[148:151], v[196:199], v[20:23]
	v_mfma_f32_16x16x32_bf16 v[24:27], v[152:155], v[192:195], v[24:27]
	v_mfma_f32_16x16x32_bf16 v[24:27], v[156:159], v[196:199], v[24:27]
	v_mfma_f32_16x16x32_bf16 v[28:31], v[144:147], v[200:203], v[28:31]
	v_mfma_f32_16x16x32_bf16 v[28:31], v[148:151], v[204:207], v[28:31]
	v_mfma_f32_16x16x32_bf16 v[32:35], v[152:155], v[200:203], v[32:35]
	v_mfma_f32_16x16x32_bf16 v[32:35], v[156:159], v[204:207], v[32:35]
	s_setprio 0
	s_setprio 1
	v_mfma_f32_16x16x32_bf16 v[36:39], v[160:163], v[176:179], v[36:39]
	v_mfma_f32_16x16x32_bf16 v[36:39], v[164:167], v[180:183], v[36:39]
	v_mfma_f32_16x16x32_bf16 v[40:43], v[168:171], v[176:179], v[40:43]
	v_mfma_f32_16x16x32_bf16 v[40:43], v[172:175], v[180:183], v[40:43]
	v_mfma_f32_16x16x32_bf16 v[44:47], v[160:163], v[184:187], v[44:47]
	v_mfma_f32_16x16x32_bf16 v[44:47], v[164:167], v[188:191], v[44:47]
	v_mfma_f32_16x16x32_bf16 v[48:51], v[168:171], v[184:187], v[48:51]
	v_mfma_f32_16x16x32_bf16 v[48:51], v[172:175], v[188:191], v[48:51]
	v_mfma_f32_16x16x32_bf16 v[52:55], v[160:163], v[192:195], v[52:55]
	v_mfma_f32_16x16x32_bf16 v[52:55], v[164:167], v[196:199], v[52:55]
	v_mfma_f32_16x16x32_bf16 v[56:59], v[168:171], v[192:195], v[56:59]
	v_mfma_f32_16x16x32_bf16 v[56:59], v[172:175], v[196:199], v[56:59]
	v_mfma_f32_16x16x32_bf16 v[60:63], v[160:163], v[200:203], v[60:63]
	v_mfma_f32_16x16x32_bf16 v[60:63], v[164:167], v[204:207], v[60:63]
	v_mfma_f32_16x16x32_bf16 v[64:67], v[168:171], v[200:203], v[64:67]
	v_mfma_f32_16x16x32_bf16 v[64:67], v[172:175], v[204:207], v[64:67]
	s_setprio 0
	s_barrier
	s_mov_b32 m0, s68
	s_mov_b64 s[8:9], s[18:19]
	ds_read_b128 v[176:179], v141 offset:49152
	ds_read_b128 v[180:183], v141 offset:50176
	ds_read_b128 v[184:187], v141 offset:51200
	ds_read_b128 v[188:191], v141 offset:52224
	ds_read_b128 v[192:195], v141 offset:53248
	ds_read_b128 v[196:199], v141 offset:54272
	ds_read_b128 v[200:203], v141 offset:55296
	ds_read_b128 v[204:207], v141 offset:56320
	s_nop 0
	global_load_lds_dwordx4 v143, s[8:9]
	s_mov_b32 m0, s69
	s_nop 0
	global_load_lds_dwordx4 v142, s[8:9]
	s_add_u32 s8, s18, s20
	s_addc_u32 s9, s19, s21
	s_mov_b32 m0, s91
	s_nop 0
	global_load_lds_dwordx4 v143, s[8:9]
	s_mov_b32 m0, s92
	s_nop 0
	global_load_lds_dwordx4 v142, s[8:9]
	s_waitcnt vmcnt(6)
	s_waitcnt lgkmcnt(0)
	s_barrier
	s_setprio 1
	s_waitcnt lgkmcnt(0)
	v_mfma_f32_16x16x32_bf16 v[68:71], v[144:147], v[176:179], v[68:71]
	v_mfma_f32_16x16x32_bf16 v[68:71], v[148:151], v[180:183], v[68:71]
	v_mfma_f32_16x16x32_bf16 v[72:75], v[152:155], v[176:179], v[72:75]
	v_mfma_f32_16x16x32_bf16 v[72:75], v[156:159], v[180:183], v[72:75]
	v_mfma_f32_16x16x32_bf16 v[76:79], v[144:147], v[184:187], v[76:79]
	v_mfma_f32_16x16x32_bf16 v[76:79], v[148:151], v[188:191], v[76:79]
	v_mfma_f32_16x16x32_bf16 v[80:83], v[152:155], v[184:187], v[80:83]
	v_mfma_f32_16x16x32_bf16 v[80:83], v[156:159], v[188:191], v[80:83]
	v_mfma_f32_16x16x32_bf16 v[84:87], v[144:147], v[192:195], v[84:87]
	v_mfma_f32_16x16x32_bf16 v[84:87], v[148:151], v[196:199], v[84:87]
	v_mfma_f32_16x16x32_bf16 v[88:91], v[152:155], v[192:195], v[88:91]
	v_mfma_f32_16x16x32_bf16 v[88:91], v[156:159], v[196:199], v[88:91]
	v_mfma_f32_16x16x32_bf16 v[92:95], v[144:147], v[200:203], v[92:95]
	v_mfma_f32_16x16x32_bf16 v[92:95], v[148:151], v[204:207], v[92:95]
	v_mfma_f32_16x16x32_bf16 v[96:99], v[152:155], v[200:203], v[96:99]
	v_mfma_f32_16x16x32_bf16 v[96:99], v[156:159], v[204:207], v[96:99]
	s_setprio 0
	s_setprio 1
	v_mfma_f32_16x16x32_bf16 v[100:103], v[160:163], v[176:179], v[100:103]
	v_mfma_f32_16x16x32_bf16 v[100:103], v[164:167], v[180:183], v[100:103]
	v_mfma_f32_16x16x32_bf16 v[104:107], v[168:171], v[176:179], v[104:107]
	v_mfma_f32_16x16x32_bf16 v[104:107], v[172:175], v[180:183], v[104:107]
	v_mfma_f32_16x16x32_bf16 v[108:111], v[160:163], v[184:187], v[108:111]
	v_mfma_f32_16x16x32_bf16 v[108:111], v[164:167], v[188:191], v[108:111]
	v_mfma_f32_16x16x32_bf16 v[112:115], v[168:171], v[184:187], v[112:115]
	v_mfma_f32_16x16x32_bf16 v[112:115], v[172:175], v[188:191], v[112:115]
	v_mfma_f32_16x16x32_bf16 v[116:119], v[160:163], v[192:195], v[116:119]
	v_mfma_f32_16x16x32_bf16 v[116:119], v[164:167], v[196:199], v[116:119]
	v_mfma_f32_16x16x32_bf16 v[120:123], v[168:171], v[192:195], v[120:123]
	v_mfma_f32_16x16x32_bf16 v[120:123], v[172:175], v[196:199], v[120:123]
	v_mfma_f32_16x16x32_bf16 v[124:127], v[160:163], v[200:203], v[124:127]
	v_mfma_f32_16x16x32_bf16 v[124:127], v[164:167], v[204:207], v[124:127]
	v_mfma_f32_16x16x32_bf16 v[128:131], v[168:171], v[200:203], v[128:131]
	v_mfma_f32_16x16x32_bf16 v[128:131], v[172:175], v[204:207], v[128:131]
	s_setprio 0
	s_barrier
	s_add_i32 s8, s95, 2
	s_add_u32 s93, s93, 0x100
	s_addc_u32 s94, s94, 0
	s_add_u32 s66, s66, 0x100
	s_addc_u32 s67, s67, 0
	s_cmp_ge_i32 s95, s72
	s_mov_b32 s95, s8
	s_cbranch_scc0 .LBB0_1042
	v_readlane_b32 s94, v255, 39
	v_readlane_b32 s95, v255, 40
	s_branch .LBB0_1031

.LBB0_1154:
	s_add_u32 s18, s52, 0x100
	s_addc_u32 s19, s53, 0
	s_add_u32 s16, s20, 0x100
	s_addc_u32 s17, s21, 0
	s_and_b64 s[8:9], s[46:47], exec
	s_cselect_b32 s17, s27, s17
	s_cselect_b32 s16, s26, s16
	s_add_i32 s72, 0, 0x10000
	s_and_b64 s[8:9], s[46:47], exec
	s_cselect_b32 s43, s51, s19
	s_cselect_b32 s42, s50, s18
	s_add_i32 s76, 0, 0x14000
	v_add_u32_e32 v132, s72, v243
	v_add_u32_e32 v133, s76, v243
	ds_read_b128 v[4:7], v132
	ds_read_b128 v[8:11], v132 offset:1024
	ds_read_b128 v[12:15], v132 offset:2048
	ds_read_b128 v[16:19], v132 offset:3072
	ds_read_b128 v[20:23], v133
	ds_read_b128 v[24:27], v133 offset:1024
	ds_read_b128 v[28:31], v133 offset:2048
	ds_read_b128 v[32:35], v133 offset:3072
	s_add_u32 s8, s52, 0x80
	s_addc_u32 s9, s53, 0
	s_add_i32 s66, s58, 0x8000
	s_add_i32 s67, s58, 0xa000
	s_mov_b64 s[18:19], s[8:9]
	s_mov_b32 m0, s66
	s_add_u32 s8, s8, s28
	ds_read_b128 v[36:39], v244 offset:8192
	ds_read_b128 v[40:43], v244 offset:9216
	ds_read_b128 v[44:47], v244 offset:10240
	ds_read_b128 v[48:51], v244 offset:11264
	ds_read_b128 v[52:55], v244 offset:12288
	ds_read_b128 v[56:59], v244 offset:13312
	ds_read_b128 v[60:63], v244 offset:14336
	ds_read_b128 v[64:67], v244 offset:15360
	s_addc_u32 s9, s9, s29
	global_load_lds_dwordx4 v238, s[18:19]
	s_mov_b32 m0, s67
	s_add_i32 s68, s58, 0xc000
	global_load_lds_dwordx4 v2, s[18:19]
	s_mov_b32 m0, s68
	s_add_i32 s69, s58, 0xe000
	s_add_u32 s18, s16, 0x80
	global_load_lds_dwordx4 v238, s[8:9]
	s_mov_b32 m0, s69
	s_addc_u32 s19, s17, 0
	global_load_lds_dwordx4 v2, s[8:9]
	s_waitcnt vmcnt(8)
	s_waitcnt lgkmcnt(0)
	s_barrier
	s_setprio 1
	s_waitcnt lgkmcnt(0)
	v_mfma_f32_16x16x32_bf16 v[68:71], v[4:7], v[36:39], 0
	v_mfma_f32_16x16x32_bf16 v[72:75], v[12:15], v[36:39], 0
	v_mfma_f32_16x16x32_bf16 v[76:79], v[4:7], v[44:47], 0
	v_mfma_f32_16x16x32_bf16 v[80:83], v[12:15], v[44:47], 0
	v_mfma_f32_16x16x32_bf16 v[84:87], v[4:7], v[52:55], 0
	v_mfma_f32_16x16x32_bf16 v[88:91], v[12:15], v[52:55], 0
	v_mfma_f32_16x16x32_bf16 v[92:95], v[4:7], v[60:63], 0
	v_mfma_f32_16x16x32_bf16 v[96:99], v[12:15], v[60:63], 0
	v_mfma_f32_16x16x32_bf16 v[68:71], v[8:11], v[40:43], v[68:71]
	v_mfma_f32_16x16x32_bf16 v[72:75], v[16:19], v[40:43], v[72:75]
	v_mfma_f32_16x16x32_bf16 v[76:79], v[8:11], v[48:51], v[76:79]
	v_mfma_f32_16x16x32_bf16 v[80:83], v[16:19], v[48:51], v[80:83]
	v_mfma_f32_16x16x32_bf16 v[84:87], v[8:11], v[56:59], v[84:87]
	v_mfma_f32_16x16x32_bf16 v[88:91], v[16:19], v[56:59], v[88:91]
	v_mfma_f32_16x16x32_bf16 v[92:95], v[8:11], v[64:67], v[92:95]
	v_mfma_f32_16x16x32_bf16 v[96:99], v[16:19], v[64:67], v[96:99]
	s_setprio 0
	s_setprio 1
	v_mfma_f32_16x16x32_bf16 v[100:103], v[20:23], v[36:39], 0
	v_mfma_f32_16x16x32_bf16 v[36:39], v[28:31], v[36:39], 0
	v_mfma_f32_16x16x32_bf16 v[100:103], v[24:27], v[40:43], v[100:103]
	v_mfma_f32_16x16x32_bf16 v[40:43], v[32:35], v[40:43], v[36:39]
	v_mfma_f32_16x16x32_bf16 v[36:39], v[20:23], v[44:47], 0
	v_mfma_f32_16x16x32_bf16 v[104:107], v[24:27], v[48:51], v[36:39]
	v_mfma_f32_16x16x32_bf16 v[36:39], v[28:31], v[44:47], 0
	v_mfma_f32_16x16x32_bf16 v[48:51], v[32:35], v[48:51], v[36:39]
	v_mfma_f32_16x16x32_bf16 v[36:39], v[20:23], v[52:55], 0
	v_mfma_f32_16x16x32_bf16 v[108:111], v[24:27], v[56:59], v[36:39]
	v_mfma_f32_16x16x32_bf16 v[36:39], v[28:31], v[52:55], 0
	v_mfma_f32_16x16x32_bf16 v[56:59], v[32:35], v[56:59], v[36:39]
	v_mfma_f32_16x16x32_bf16 v[36:39], v[20:23], v[60:63], 0
	v_mfma_f32_16x16x32_bf16 v[112:115], v[24:27], v[64:67], v[36:39]
	v_mfma_f32_16x16x32_bf16 v[36:39], v[28:31], v[60:63], 0
	v_mfma_f32_16x16x32_bf16 v[64:67], v[32:35], v[64:67], v[36:39]
	s_setprio 0
	s_barrier
	s_add_i32 s72, s72, s57
	s_mov_b64 s[8:9], s[16:17]
	s_mov_b32 m0, s72
	s_add_i32 s73, s72, 0x2000
	s_nop 0
	ds_read_b128 v[36:39], v244 offset:24576
	ds_read_b128 v[44:47], v244 offset:25600
	ds_read_b128 v[52:55], v244 offset:26624
	ds_read_b128 v[60:63], v244 offset:27648
	ds_read_b128 v[116:119], v244 offset:28672
	ds_read_b128 v[120:123], v244 offset:29696
	ds_read_b128 v[124:127], v244 offset:30720
	ds_read_b128 v[128:131], v244 offset:31744
	s_nop 0
	global_load_lds_dwordx4 v246, s[8:9]
	s_mov_b32 m0, s73
	s_nop 0
	global_load_lds_dwordx4 v245, s[8:9]
	s_add_u32 s8, s16, s28
	s_addc_u32 s9, s17, s29
	s_add_i32 s76, s76, s57
	s_mov_b32 m0, s76
	s_add_i32 s77, s76, 0x2000
	s_nop 0
	global_load_lds_dwordx4 v246, s[8:9]
	s_mov_b32 m0, s77
	s_nop 0
	global_load_lds_dwordx4 v245, s[8:9]
	s_waitcnt vmcnt(6)
	s_waitcnt lgkmcnt(0)
	s_barrier
	s_setprio 1
	s_waitcnt lgkmcnt(0)
	v_mfma_f32_16x16x32_bf16 v[134:137], v[4:7], v[36:39], 0
	v_mfma_f32_16x16x32_bf16 v[144:147], v[4:7], v[52:55], 0
	v_mfma_f32_16x16x32_bf16 v[152:155], v[4:7], v[116:119], 0
	v_mfma_f32_16x16x32_bf16 v[4:7], v[4:7], v[124:127], 0
	v_mfma_f32_16x16x32_bf16 v[140:143], v[12:15], v[36:39], 0
	v_mfma_f32_16x16x32_bf16 v[148:151], v[12:15], v[52:55], 0
	v_mfma_f32_16x16x32_bf16 v[156:159], v[12:15], v[116:119], 0
	v_mfma_f32_16x16x32_bf16 v[160:163], v[8:11], v[128:131], v[4:7]
	v_mfma_f32_16x16x32_bf16 v[4:7], v[12:15], v[124:127], 0
	v_mfma_f32_16x16x32_bf16 v[136:139], v[8:11], v[44:47], v[134:137]
	v_mfma_f32_16x16x32_bf16 v[140:143], v[16:19], v[44:47], v[140:143]
	v_mfma_f32_16x16x32_bf16 v[144:147], v[8:11], v[60:63], v[144:147]
	v_mfma_f32_16x16x32_bf16 v[148:151], v[16:19], v[60:63], v[148:151]
	v_mfma_f32_16x16x32_bf16 v[152:155], v[8:11], v[120:123], v[152:155]
	v_mfma_f32_16x16x32_bf16 v[156:159], v[16:19], v[120:123], v[156:159]
	v_mfma_f32_16x16x32_bf16 v[164:167], v[16:19], v[128:131], v[4:7]
	s_setprio 0
	s_setprio 1
	v_mfma_f32_16x16x32_bf16 v[4:7], v[20:23], v[36:39], 0
	v_mfma_f32_16x16x32_bf16 v[168:171], v[24:27], v[44:47], v[4:7]
	v_mfma_f32_16x16x32_bf16 v[4:7], v[28:31], v[36:39], 0
	v_mfma_f32_16x16x32_bf16 v[172:175], v[32:35], v[44:47], v[4:7]
	v_mfma_f32_16x16x32_bf16 v[4:7], v[20:23], v[52:55], 0
	v_mfma_f32_16x16x32_bf16 v[176:179], v[24:27], v[60:63], v[4:7]
	v_mfma_f32_16x16x32_bf16 v[4:7], v[28:31], v[52:55], 0
	v_mfma_f32_16x16x32_bf16 v[180:183], v[32:35], v[60:63], v[4:7]
	v_mfma_f32_16x16x32_bf16 v[4:7], v[20:23], v[116:119], 0
	v_mfma_f32_16x16x32_bf16 v[184:187], v[24:27], v[120:123], v[4:7]
	v_mfma_f32_16x16x32_bf16 v[4:7], v[28:31], v[116:119], 0
	v_mfma_f32_16x16x32_bf16 v[120:123], v[32:35], v[120:123], v[4:7]
	v_mfma_f32_16x16x32_bf16 v[4:7], v[20:23], v[124:127], 0
	v_mfma_f32_16x16x32_bf16 v[188:191], v[24:27], v[128:131], v[4:7]
	v_mfma_f32_16x16x32_bf16 v[4:7], v[28:31], v[124:127], 0
	v_mfma_f32_16x16x32_bf16 v[128:131], v[32:35], v[128:131], v[4:7]
	s_setprio 0
	s_barrier
	s_add_i32 s16, 0, 0x18000
	s_add_i32 s78, 0, 0x1c000
	v_add_u32_e32 v134, s16, v243
	v_add_u32_e32 v135, s78, v243
	ds_read_b128 v[116:119], v134
	ds_read_b128 v[124:127], v134 offset:1024
	ds_read_b128 v[192:195], v134 offset:2048
	ds_read_b128 v[196:199], v134 offset:3072
	ds_read_b128 v[200:203], v135
	ds_read_b128 v[204:207], v135 offset:1024
	ds_read_b128 v[208:211], v135 offset:2048
	ds_read_b128 v[216:219], v135 offset:3072
	s_mov_b32 m0, s58
	s_mov_b64 s[8:9], s[42:43]
	ds_read_b128 v[44:47], v244 offset:40960
	ds_read_b128 v[52:55], v244 offset:41984
	ds_read_b128 v[60:63], v244 offset:43008
	ds_read_b128 v[220:223], v244 offset:44032
	ds_read_b128 v[224:227], v244 offset:45056
	ds_read_b128 v[228:231], v244 offset:46080
	ds_read_b128 v[232:235], v244 offset:47104
	ds_read_b128 v[248:251], v244 offset:48128
	s_nop 0
	global_load_lds_dwordx4 v238, s[8:9]
	s_mov_b32 m0, s59
	s_nop 0
	global_load_lds_dwordx4 v2, s[8:9]
	s_add_u32 s8, s42, s28
	s_addc_u32 s9, s43, s29
	s_mov_b32 m0, s60
	s_nop 0
	global_load_lds_dwordx4 v238, s[8:9]
	s_mov_b32 m0, s61
	s_nop 0
	global_load_lds_dwordx4 v2, s[8:9]
	s_waitcnt vmcnt(8)
	s_waitcnt lgkmcnt(0)
	s_barrier
	s_setprio 1
	s_waitcnt lgkmcnt(0)
	v_mfma_f32_16x16x32_bf16 v[4:7], v[116:119], v[44:47], v[68:71]
	v_mfma_f32_16x16x32_bf16 v[4:7], v[124:127], v[52:55], v[4:7]
	v_mfma_f32_16x16x32_bf16 v[8:11], v[192:195], v[44:47], v[72:75]
	v_mfma_f32_16x16x32_bf16 v[8:11], v[196:199], v[52:55], v[8:11]
	v_mfma_f32_16x16x32_bf16 v[12:15], v[116:119], v[60:63], v[76:79]
	v_mfma_f32_16x16x32_bf16 v[12:15], v[124:127], v[220:223], v[12:15]
	v_mfma_f32_16x16x32_bf16 v[16:19], v[192:195], v[60:63], v[80:83]
	v_mfma_f32_16x16x32_bf16 v[16:19], v[196:199], v[220:223], v[16:19]
	v_mfma_f32_16x16x32_bf16 v[20:23], v[116:119], v[224:227], v[84:87]
	v_mfma_f32_16x16x32_bf16 v[20:23], v[124:127], v[228:231], v[20:23]
	v_mfma_f32_16x16x32_bf16 v[24:27], v[192:195], v[224:227], v[88:91]
	v_mfma_f32_16x16x32_bf16 v[24:27], v[196:199], v[228:231], v[24:27]
	v_mfma_f32_16x16x32_bf16 v[28:31], v[116:119], v[232:235], v[92:95]
	v_mfma_f32_16x16x32_bf16 v[28:31], v[124:127], v[248:251], v[28:31]
	v_mfma_f32_16x16x32_bf16 v[32:35], v[192:195], v[232:235], v[96:99]
	v_mfma_f32_16x16x32_bf16 v[32:35], v[196:199], v[248:251], v[32:35]
	s_setprio 0
	s_setprio 1
	v_mfma_f32_16x16x32_bf16 v[36:39], v[200:203], v[44:47], v[100:103]
	v_mfma_f32_16x16x32_bf16 v[40:43], v[208:211], v[44:47], v[40:43]
	v_mfma_f32_16x16x32_bf16 v[36:39], v[204:207], v[52:55], v[36:39]
	v_mfma_f32_16x16x32_bf16 v[40:43], v[216:219], v[52:55], v[40:43]
	v_mfma_f32_16x16x32_bf16 v[44:47], v[200:203], v[60:63], v[104:107]
	v_mfma_f32_16x16x32_bf16 v[48:51], v[208:211], v[60:63], v[48:51]
	v_mfma_f32_16x16x32_bf16 v[52:55], v[200:203], v[224:227], v[108:111]
	v_mfma_f32_16x16x32_bf16 v[56:59], v[208:211], v[224:227], v[56:59]
	v_mfma_f32_16x16x32_bf16 v[60:63], v[200:203], v[232:235], v[112:115]
	v_mfma_f32_16x16x32_bf16 v[64:67], v[208:211], v[232:235], v[64:67]
	v_mfma_f32_16x16x32_bf16 v[44:47], v[204:207], v[220:223], v[44:47]
	v_mfma_f32_16x16x32_bf16 v[48:51], v[216:219], v[220:223], v[48:51]
	v_mfma_f32_16x16x32_bf16 v[52:55], v[204:207], v[228:231], v[52:55]
	v_mfma_f32_16x16x32_bf16 v[56:59], v[216:219], v[228:231], v[56:59]
	v_mfma_f32_16x16x32_bf16 v[60:63], v[204:207], v[248:251], v[60:63]
	v_mfma_f32_16x16x32_bf16 v[64:67], v[216:219], v[248:251], v[64:67]
	s_setprio 0
	s_barrier
	s_add_i32 s42, s16, s57
	s_mov_b64 s[8:9], s[18:19]
	s_mov_b32 m0, s42
	s_add_i32 s43, s42, 0x2000
	ds_read_b128 v[104:107], v244 offset:57344
	ds_read_b128 v[108:111], v244 offset:58368
	ds_read_b128 v[112:115], v244 offset:59392
	ds_read_b128 v[220:223], v244 offset:60416
	ds_read_b128 v[224:227], v244 offset:61440
	ds_read_b128 v[228:231], v244 offset:62464
	ds_read_b128 v[232:235], v244 offset:63488
	ds_read_b128 v[248:251], v244 offset:64512
	s_nop 0
	global_load_lds_dwordx4 v246, s[8:9]
	s_mov_b32 m0, s43
	s_nop 0
	global_load_lds_dwordx4 v245, s[8:9]
	s_add_u32 s8, s18, s28
	s_addc_u32 s9, s19, s29
	s_add_i32 s78, s78, s57
	s_mov_b32 m0, s78
	s_add_i32 s79, s78, 0x2000
	s_nop 0
	global_load_lds_dwordx4 v246, s[8:9]
	s_mov_b32 m0, s79
	s_nop 0
	global_load_lds_dwordx4 v245, s[8:9]
	s_waitcnt vmcnt(6)
	s_waitcnt lgkmcnt(0)
	s_barrier
	s_setprio 1
	s_waitcnt lgkmcnt(0)
	v_mfma_f32_16x16x32_bf16 v[68:71], v[116:119], v[104:107], v[136:139]
	v_mfma_f32_16x16x32_bf16 v[68:71], v[124:127], v[108:111], v[68:71]
	v_mfma_f32_16x16x32_bf16 v[72:75], v[192:195], v[104:107], v[140:143]
	v_mfma_f32_16x16x32_bf16 v[72:75], v[196:199], v[108:111], v[72:75]
	v_mfma_f32_16x16x32_bf16 v[76:79], v[116:119], v[112:115], v[144:147]
	v_mfma_f32_16x16x32_bf16 v[76:79], v[124:127], v[220:223], v[76:79]
	v_mfma_f32_16x16x32_bf16 v[80:83], v[192:195], v[112:115], v[148:151]
	v_mfma_f32_16x16x32_bf16 v[80:83], v[196:199], v[220:223], v[80:83]
	v_mfma_f32_16x16x32_bf16 v[84:87], v[116:119], v[224:227], v[152:155]
	v_mfma_f32_16x16x32_bf16 v[84:87], v[124:127], v[228:231], v[84:87]
	v_mfma_f32_16x16x32_bf16 v[88:91], v[192:195], v[224:227], v[156:159]
	v_mfma_f32_16x16x32_bf16 v[88:91], v[196:199], v[228:231], v[88:91]
	v_mfma_f32_16x16x32_bf16 v[92:95], v[116:119], v[232:235], v[160:163]
	v_mfma_f32_16x16x32_bf16 v[92:95], v[124:127], v[248:251], v[92:95]
	v_mfma_f32_16x16x32_bf16 v[96:99], v[192:195], v[232:235], v[164:167]
	v_mfma_f32_16x16x32_bf16 v[96:99], v[196:199], v[248:251], v[96:99]
	s_setprio 0
	s_setprio 1
	v_mfma_f32_16x16x32_bf16 v[100:103], v[200:203], v[104:107], v[168:171]
	v_mfma_f32_16x16x32_bf16 v[104:107], v[208:211], v[104:107], v[172:175]
	v_mfma_f32_16x16x32_bf16 v[100:103], v[204:207], v[108:111], v[100:103]
	v_mfma_f32_16x16x32_bf16 v[104:107], v[216:219], v[108:111], v[104:107]
	v_mfma_f32_16x16x32_bf16 v[108:111], v[200:203], v[112:115], v[176:179]
	v_mfma_f32_16x16x32_bf16 v[112:115], v[208:211], v[112:115], v[180:183]
	v_mfma_f32_16x16x32_bf16 v[116:119], v[200:203], v[224:227], v[184:187]
	v_mfma_f32_16x16x32_bf16 v[120:123], v[208:211], v[224:227], v[120:123]
	v_mfma_f32_16x16x32_bf16 v[124:127], v[200:203], v[232:235], v[188:191]
	v_mfma_f32_16x16x32_bf16 v[128:131], v[208:211], v[232:235], v[128:131]
	v_mfma_f32_16x16x32_bf16 v[108:111], v[204:207], v[220:223], v[108:111]
	v_mfma_f32_16x16x32_bf16 v[112:115], v[216:219], v[220:223], v[112:115]
	v_mfma_f32_16x16x32_bf16 v[116:119], v[204:207], v[228:231], v[116:119]
	v_mfma_f32_16x16x32_bf16 v[120:123], v[216:219], v[228:231], v[120:123]
	v_mfma_f32_16x16x32_bf16 v[124:127], v[204:207], v[248:251], v[124:127]
	v_mfma_f32_16x16x32_bf16 v[128:131], v[216:219], v[248:251], v[128:131]
	s_setprio 0
	s_barrier
	s_andn2_b64 vcc, exec, s[48:49]
	s_cbranch_vccnz .LBB0_1157
	s_add_u32 s80, s20, 0x200
	s_addc_u32 s81, s21, 0
	s_add_u32 s52, s52, 0x200
	s_addc_u32 s53, s53, 0
	s_mov_b32 s82, 4
.LBB0_1156:
	ds_read_b128 v[136:139], v132
	ds_read_b128 v[140:143], v132 offset:1024
	ds_read_b128 v[144:147], v132 offset:2048
	ds_read_b128 v[148:151], v132 offset:3072
	ds_read_b128 v[152:155], v133
	ds_read_b128 v[156:159], v133 offset:1024
	ds_read_b128 v[160:163], v133 offset:2048
	ds_read_b128 v[164:167], v133 offset:3072
	s_cmp_eq_u32 s6, s82
	s_cselect_b32 s17, s27, s81
	s_cselect_b32 s16, s26, s80
	s_cselect_b32 s21, s51, s53
	s_cselect_b32 s20, s50, s52
	s_add_u32 s8, s52, 0xffffff80
	s_addc_u32 s9, s53, -1
	s_mov_b32 m0, s66
	s_mov_b64 s[18:19], s[8:9]
	ds_read_b128 v[168:171], v244 offset:8192
	ds_read_b128 v[172:175], v244 offset:9216
	ds_read_b128 v[176:179], v244 offset:10240
	ds_read_b128 v[180:183], v244 offset:11264
	ds_read_b128 v[184:187], v244 offset:12288
	ds_read_b128 v[188:191], v244 offset:13312
	ds_read_b128 v[192:195], v244 offset:14336
	ds_read_b128 v[196:199], v244 offset:15360
	s_add_u32 s8, s8, s28
	global_load_lds_dwordx4 v238, s[18:19]
	s_mov_b32 m0, s67
	s_addc_u32 s9, s9, s29
	global_load_lds_dwordx4 v2, s[18:19]
	s_mov_b32 m0, s68
	s_add_u32 s18, s16, 0x80
	global_load_lds_dwordx4 v238, s[8:9]
	s_mov_b32 m0, s69
	s_addc_u32 s19, s17, 0
	global_load_lds_dwordx4 v2, s[8:9]
	s_waitcnt vmcnt(8)
	s_waitcnt lgkmcnt(0)
	s_barrier
	s_setprio 1
	s_waitcnt lgkmcnt(0)
	v_mfma_f32_16x16x32_bf16 v[4:7], v[136:139], v[168:171], v[4:7]
	v_mfma_f32_16x16x32_bf16 v[4:7], v[140:143], v[172:175], v[4:7]
	v_mfma_f32_16x16x32_bf16 v[8:11], v[144:147], v[168:171], v[8:11]
	v_mfma_f32_16x16x32_bf16 v[8:11], v[148:151], v[172:175], v[8:11]
	v_mfma_f32_16x16x32_bf16 v[12:15], v[136:139], v[176:179], v[12:15]
	v_mfma_f32_16x16x32_bf16 v[12:15], v[140:143], v[180:183], v[12:15]
	v_mfma_f32_16x16x32_bf16 v[16:19], v[144:147], v[176:179], v[16:19]
	v_mfma_f32_16x16x32_bf16 v[16:19], v[148:151], v[180:183], v[16:19]
	v_mfma_f32_16x16x32_bf16 v[20:23], v[136:139], v[184:187], v[20:23]
	v_mfma_f32_16x16x32_bf16 v[20:23], v[140:143], v[188:191], v[20:23]
	v_mfma_f32_16x16x32_bf16 v[24:27], v[144:147], v[184:187], v[24:27]
	v_mfma_f32_16x16x32_bf16 v[24:27], v[148:151], v[188:191], v[24:27]
	v_mfma_f32_16x16x32_bf16 v[28:31], v[136:139], v[192:195], v[28:31]
	v_mfma_f32_16x16x32_bf16 v[28:31], v[140:143], v[196:199], v[28:31]
	v_mfma_f32_16x16x32_bf16 v[32:35], v[144:147], v[192:195], v[32:35]
	v_mfma_f32_16x16x32_bf16 v[32:35], v[148:151], v[196:199], v[32:35]
	s_setprio 0
	s_setprio 1
	v_mfma_f32_16x16x32_bf16 v[36:39], v[152:155], v[168:171], v[36:39]
	v_mfma_f32_16x16x32_bf16 v[36:39], v[156:159], v[172:175], v[36:39]
	v_mfma_f32_16x16x32_bf16 v[40:43], v[160:163], v[168:171], v[40:43]
	v_mfma_f32_16x16x32_bf16 v[40:43], v[164:167], v[172:175], v[40:43]
	v_mfma_f32_16x16x32_bf16 v[44:47], v[152:155], v[176:179], v[44:47]
	v_mfma_f32_16x16x32_bf16 v[44:47], v[156:159], v[180:183], v[44:47]
	v_mfma_f32_16x16x32_bf16 v[48:51], v[160:163], v[176:179], v[48:51]
	v_mfma_f32_16x16x32_bf16 v[48:51], v[164:167], v[180:183], v[48:51]
	v_mfma_f32_16x16x32_bf16 v[52:55], v[152:155], v[184:187], v[52:55]
	v_mfma_f32_16x16x32_bf16 v[52:55], v[156:159], v[188:191], v[52:55]
	v_mfma_f32_16x16x32_bf16 v[56:59], v[160:163], v[184:187], v[56:59]
	v_mfma_f32_16x16x32_bf16 v[56:59], v[164:167], v[188:191], v[56:59]
	v_mfma_f32_16x16x32_bf16 v[60:63], v[152:155], v[192:195], v[60:63]
	v_mfma_f32_16x16x32_bf16 v[60:63], v[156:159], v[196:199], v[60:63]
	v_mfma_f32_16x16x32_bf16 v[64:67], v[160:163], v[192:195], v[64:67]
	v_mfma_f32_16x16x32_bf16 v[64:67], v[164:167], v[196:199], v[64:67]
	s_setprio 0
	s_barrier
	s_mov_b32 m0, s72
	s_mov_b64 s[8:9], s[16:17]
	ds_read_b128 v[168:171], v244 offset:24576
	ds_read_b128 v[172:175], v244 offset:25600
	ds_read_b128 v[176:179], v244 offset:26624
	ds_read_b128 v[180:183], v244 offset:27648
	ds_read_b128 v[184:187], v244 offset:28672
	ds_read_b128 v[188:191], v244 offset:29696
	ds_read_b128 v[192:195], v244 offset:30720
	ds_read_b128 v[196:199], v244 offset:31744
	s_nop 0
	global_load_lds_dwordx4 v246, s[8:9]
	s_mov_b32 m0, s73
	s_nop 0
	global_load_lds_dwordx4 v245, s[8:9]
	s_add_u32 s8, s16, s28
	s_addc_u32 s9, s17, s29
	s_mov_b32 m0, s76
	s_nop 0
	global_load_lds_dwordx4 v246, s[8:9]
	s_mov_b32 m0, s77
	s_nop 0
	global_load_lds_dwordx4 v245, s[8:9]
	s_waitcnt vmcnt(6)
	s_waitcnt lgkmcnt(0)
	s_barrier
	s_setprio 1
	s_waitcnt lgkmcnt(0)
	v_mfma_f32_16x16x32_bf16 v[68:71], v[136:139], v[168:171], v[68:71]
	v_mfma_f32_16x16x32_bf16 v[68:71], v[140:143], v[172:175], v[68:71]
	v_mfma_f32_16x16x32_bf16 v[72:75], v[144:147], v[168:171], v[72:75]
	v_mfma_f32_16x16x32_bf16 v[72:75], v[148:151], v[172:175], v[72:75]
	v_mfma_f32_16x16x32_bf16 v[76:79], v[136:139], v[176:179], v[76:79]
	v_mfma_f32_16x16x32_bf16 v[76:79], v[140:143], v[180:183], v[76:79]
	v_mfma_f32_16x16x32_bf16 v[80:83], v[144:147], v[176:179], v[80:83]
	v_mfma_f32_16x16x32_bf16 v[80:83], v[148:151], v[180:183], v[80:83]
	v_mfma_f32_16x16x32_bf16 v[84:87], v[136:139], v[184:187], v[84:87]
	v_mfma_f32_16x16x32_bf16 v[84:87], v[140:143], v[188:191], v[84:87]
	v_mfma_f32_16x16x32_bf16 v[88:91], v[144:147], v[184:187], v[88:91]
	v_mfma_f32_16x16x32_bf16 v[88:91], v[148:151], v[188:191], v[88:91]
	v_mfma_f32_16x16x32_bf16 v[92:95], v[136:139], v[192:195], v[92:95]
	v_mfma_f32_16x16x32_bf16 v[92:95], v[140:143], v[196:199], v[92:95]
	v_mfma_f32_16x16x32_bf16 v[96:99], v[144:147], v[192:195], v[96:99]
	v_mfma_f32_16x16x32_bf16 v[96:99], v[148:151], v[196:199], v[96:99]
	s_setprio 0
	s_setprio 1
	v_mfma_f32_16x16x32_bf16 v[100:103], v[152:155], v[168:171], v[100:103]
	v_mfma_f32_16x16x32_bf16 v[100:103], v[156:159], v[172:175], v[100:103]
	v_mfma_f32_16x16x32_bf16 v[104:107], v[160:163], v[168:171], v[104:107]
	v_mfma_f32_16x16x32_bf16 v[104:107], v[164:167], v[172:175], v[104:107]
	v_mfma_f32_16x16x32_bf16 v[108:111], v[152:155], v[176:179], v[108:111]
	v_mfma_f32_16x16x32_bf16 v[108:111], v[156:159], v[180:183], v[108:111]
	v_mfma_f32_16x16x32_bf16 v[112:115], v[160:163], v[176:179], v[112:115]
	v_mfma_f32_16x16x32_bf16 v[112:115], v[164:167], v[180:183], v[112:115]
	v_mfma_f32_16x16x32_bf16 v[116:119], v[152:155], v[184:187], v[116:119]
	v_mfma_f32_16x16x32_bf16 v[116:119], v[156:159], v[188:191], v[116:119]
	v_mfma_f32_16x16x32_bf16 v[120:123], v[160:163], v[184:187], v[120:123]
	v_mfma_f32_16x16x32_bf16 v[120:123], v[164:167], v[188:191], v[120:123]
	v_mfma_f32_16x16x32_bf16 v[124:127], v[152:155], v[192:195], v[124:127]
	v_mfma_f32_16x16x32_bf16 v[124:127], v[156:159], v[196:199], v[124:127]
	v_mfma_f32_16x16x32_bf16 v[128:131], v[160:163], v[192:195], v[128:131]
	v_mfma_f32_16x16x32_bf16 v[128:131], v[164:167], v[196:199], v[128:131]
	s_setprio 0
	s_barrier
	ds_read_b128 v[136:139], v134
	ds_read_b128 v[140:143], v134 offset:1024
	ds_read_b128 v[144:147], v134 offset:2048
	ds_read_b128 v[148:151], v134 offset:3072
	ds_read_b128 v[152:155], v135
	ds_read_b128 v[156:159], v135 offset:1024
	ds_read_b128 v[160:163], v135 offset:2048
	ds_read_b128 v[164:167], v135 offset:3072
	s_mov_b32 m0, s58
	s_mov_b64 s[8:9], s[20:21]
	ds_read_b128 v[168:171], v244 offset:40960
	ds_read_b128 v[172:175], v244 offset:41984
	ds_read_b128 v[176:179], v244 offset:43008
	ds_read_b128 v[180:183], v244 offset:44032
	ds_read_b128 v[184:187], v244 offset:45056
	ds_read_b128 v[188:191], v244 offset:46080
	ds_read_b128 v[192:195], v244 offset:47104
	ds_read_b128 v[196:199], v244 offset:48128
	s_nop 0
	global_load_lds_dwordx4 v238, s[8:9]
	s_mov_b32 m0, s59
	s_nop 0
	global_load_lds_dwordx4 v2, s[8:9]
	s_add_u32 s8, s20, s28
	s_addc_u32 s9, s21, s29
	s_mov_b32 m0, s60
	s_nop 0
	global_load_lds_dwordx4 v238, s[8:9]
	s_mov_b32 m0, s61
	s_nop 0
	global_load_lds_dwordx4 v2, s[8:9]
	s_waitcnt vmcnt(8)
	s_waitcnt lgkmcnt(0)
	s_barrier
	s_setprio 1
	s_waitcnt lgkmcnt(0)
	v_mfma_f32_16x16x32_bf16 v[4:7], v[136:139], v[168:171], v[4:7]
	v_mfma_f32_16x16x32_bf16 v[4:7], v[140:143], v[172:175], v[4:7]
	v_mfma_f32_16x16x32_bf16 v[8:11], v[144:147], v[168:171], v[8:11]
	v_mfma_f32_16x16x32_bf16 v[8:11], v[148:151], v[172:175], v[8:11]
	v_mfma_f32_16x16x32_bf16 v[12:15], v[136:139], v[176:179], v[12:15]
	v_mfma_f32_16x16x32_bf16 v[12:15], v[140:143], v[180:183], v[12:15]
	v_mfma_f32_16x16x32_bf16 v[16:19], v[144:147], v[176:179], v[16:19]
	v_mfma_f32_16x16x32_bf16 v[16:19], v[148:151], v[180:183], v[16:19]
	v_mfma_f32_16x16x32_bf16 v[20:23], v[136:139], v[184:187], v[20:23]
	v_mfma_f32_16x16x32_bf16 v[20:23], v[140:143], v[188:191], v[20:23]
	v_mfma_f32_16x16x32_bf16 v[24:27], v[144:147], v[184:187], v[24:27]
	v_mfma_f32_16x16x32_bf16 v[24:27], v[148:151], v[188:191], v[24:27]
	v_mfma_f32_16x16x32_bf16 v[28:31], v[136:139], v[192:195], v[28:31]
	v_mfma_f32_16x16x32_bf16 v[28:31], v[140:143], v[196:199], v[28:31]
	v_mfma_f32_16x16x32_bf16 v[32:35], v[144:147], v[192:195], v[32:35]
	v_mfma_f32_16x16x32_bf16 v[32:35], v[148:151], v[196:199], v[32:35]
	s_setprio 0
	s_setprio 1
	v_mfma_f32_16x16x32_bf16 v[36:39], v[152:155], v[168:171], v[36:39]
	v_mfma_f32_16x16x32_bf16 v[36:39], v[156:159], v[172:175], v[36:39]
	v_mfma_f32_16x16x32_bf16 v[40:43], v[160:163], v[168:171], v[40:43]
	v_mfma_f32_16x16x32_bf16 v[40:43], v[164:167], v[172:175], v[40:43]
	v_mfma_f32_16x16x32_bf16 v[44:47], v[152:155], v[176:179], v[44:47]
	v_mfma_f32_16x16x32_bf16 v[44:47], v[156:159], v[180:183], v[44:47]
	v_mfma_f32_16x16x32_bf16 v[48:51], v[160:163], v[176:179], v[48:51]
	v_mfma_f32_16x16x32_bf16 v[48:51], v[164:167], v[180:183], v[48:51]
	v_mfma_f32_16x16x32_bf16 v[52:55], v[152:155], v[184:187], v[52:55]
	v_mfma_f32_16x16x32_bf16 v[52:55], v[156:159], v[188:191], v[52:55]
	v_mfma_f32_16x16x32_bf16 v[56:59], v[160:163], v[184:187], v[56:59]
	v_mfma_f32_16x16x32_bf16 v[56:59], v[164:167], v[188:191], v[56:59]
	v_mfma_f32_16x16x32_bf16 v[60:63], v[152:155], v[192:195], v[60:63]
	v_mfma_f32_16x16x32_bf16 v[60:63], v[156:159], v[196:199], v[60:63]
	v_mfma_f32_16x16x32_bf16 v[64:67], v[160:163], v[192:195], v[64:67]
	v_mfma_f32_16x16x32_bf16 v[64:67], v[164:167], v[196:199], v[64:67]
	s_setprio 0
	s_barrier
	s_mov_b32 m0, s42
	s_mov_b64 s[8:9], s[18:19]
	ds_read_b128 v[168:171], v244 offset:57344
	ds_read_b128 v[172:175], v244 offset:58368
	ds_read_b128 v[176:179], v244 offset:59392
	ds_read_b128 v[180:183], v244 offset:60416
	ds_read_b128 v[184:187], v244 offset:61440
	ds_read_b128 v[188:191], v244 offset:62464
	ds_read_b128 v[192:195], v244 offset:63488
	ds_read_b128 v[196:199], v244 offset:64512
	s_nop 0
	global_load_lds_dwordx4 v246, s[8:9]
	s_mov_b32 m0, s43
	s_nop 0
	global_load_lds_dwordx4 v245, s[8:9]
	s_add_u32 s8, s18, s28
	s_addc_u32 s9, s19, s29
	s_mov_b32 m0, s78
	s_nop 0
	global_load_lds_dwordx4 v246, s[8:9]
	s_mov_b32 m0, s79
	s_nop 0
	global_load_lds_dwordx4 v245, s[8:9]
	s_waitcnt vmcnt(6)
	s_waitcnt lgkmcnt(0)
	s_barrier
	s_setprio 1
	s_waitcnt lgkmcnt(0)
	v_mfma_f32_16x16x32_bf16 v[68:71], v[136:139], v[168:171], v[68:71]
	v_mfma_f32_16x16x32_bf16 v[68:71], v[140:143], v[172:175], v[68:71]
	v_mfma_f32_16x16x32_bf16 v[72:75], v[144:147], v[168:171], v[72:75]
	v_mfma_f32_16x16x32_bf16 v[72:75], v[148:151], v[172:175], v[72:75]
	v_mfma_f32_16x16x32_bf16 v[76:79], v[136:139], v[176:179], v[76:79]
	v_mfma_f32_16x16x32_bf16 v[76:79], v[140:143], v[180:183], v[76:79]
	v_mfma_f32_16x16x32_bf16 v[80:83], v[144:147], v[176:179], v[80:83]
	v_mfma_f32_16x16x32_bf16 v[80:83], v[148:151], v[180:183], v[80:83]
	v_mfma_f32_16x16x32_bf16 v[84:87], v[136:139], v[184:187], v[84:87]
	v_mfma_f32_16x16x32_bf16 v[84:87], v[140:143], v[188:191], v[84:87]
	v_mfma_f32_16x16x32_bf16 v[88:91], v[144:147], v[184:187], v[88:91]
	v_mfma_f32_16x16x32_bf16 v[88:91], v[148:151], v[188:191], v[88:91]
	v_mfma_f32_16x16x32_bf16 v[92:95], v[136:139], v[192:195], v[92:95]
	v_mfma_f32_16x16x32_bf16 v[92:95], v[140:143], v[196:199], v[92:95]
	v_mfma_f32_16x16x32_bf16 v[96:99], v[144:147], v[192:195], v[96:99]
	v_mfma_f32_16x16x32_bf16 v[96:99], v[148:151], v[196:199], v[96:99]
	s_setprio 0
	s_setprio 1
	v_mfma_f32_16x16x32_bf16 v[100:103], v[152:155], v[168:171], v[100:103]
	v_mfma_f32_16x16x32_bf16 v[100:103], v[156:159], v[172:175], v[100:103]
	v_mfma_f32_16x16x32_bf16 v[104:107], v[160:163], v[168:171], v[104:107]
	v_mfma_f32_16x16x32_bf16 v[104:107], v[164:167], v[172:175], v[104:107]
	v_mfma_f32_16x16x32_bf16 v[108:111], v[152:155], v[176:179], v[108:111]
	v_mfma_f32_16x16x32_bf16 v[108:111], v[156:159], v[180:183], v[108:111]
	v_mfma_f32_16x16x32_bf16 v[112:115], v[160:163], v[176:179], v[112:115]
	v_mfma_f32_16x16x32_bf16 v[112:115], v[164:167], v[180:183], v[112:115]
	v_mfma_f32_16x16x32_bf16 v[116:119], v[152:155], v[184:187], v[116:119]
	v_mfma_f32_16x16x32_bf16 v[116:119], v[156:159], v[188:191], v[116:119]
	v_mfma_f32_16x16x32_bf16 v[120:123], v[160:163], v[184:187], v[120:123]
	v_mfma_f32_16x16x32_bf16 v[120:123], v[164:167], v[188:191], v[120:123]
	v_mfma_f32_16x16x32_bf16 v[124:127], v[152:155], v[192:195], v[124:127]
	v_mfma_f32_16x16x32_bf16 v[124:127], v[156:159], v[196:199], v[124:127]
	v_mfma_f32_16x16x32_bf16 v[128:131], v[160:163], v[192:195], v[128:131]
	v_mfma_f32_16x16x32_bf16 v[128:131], v[164:167], v[196:199], v[128:131]
	s_setprio 0
	s_barrier
	s_add_i32 s8, s82, 2
	s_add_u32 s80, s80, 0x100
	s_addc_u32 s81, s81, 0
	s_add_u32 s52, s52, 0x100
	s_addc_u32 s53, s53, 0
	s_cmp_ge_i32 s82, s6
	s_mov_b32 s82, s8
	s_cbranch_scc0 .LBB0_1156

.LBB0_1174:
	s_add_u32 s18, s50, 0x100
	s_addc_u32 s19, s51, 0
	s_add_u32 s16, s26, 0x100
	s_addc_u32 s17, s27, 0
	s_and_b64 s[8:9], s[46:47], exec
	s_cselect_b32 s17, s21, s17
	s_cselect_b32 s16, s20, s16
	s_add_i32 s68, 0, 0x10000
	s_and_b64 s[8:9], s[46:47], exec
	s_cselect_b32 s43, s41, s19
	s_cselect_b32 s42, s40, s18
	s_add_i32 s72, 0, 0x14000
	v_add_u32_e32 v132, s68, v243
	v_add_u32_e32 v133, s72, v243
	ds_read_b128 v[4:7], v132
	ds_read_b128 v[8:11], v132 offset:1024
	ds_read_b128 v[12:15], v132 offset:2048
	ds_read_b128 v[16:19], v132 offset:3072
	ds_read_b128 v[20:23], v133
	ds_read_b128 v[24:27], v133 offset:1024
	ds_read_b128 v[28:31], v133 offset:2048
	ds_read_b128 v[32:35], v133 offset:3072
	s_add_u32 s8, s50, 0x80
	s_addc_u32 s9, s51, 0
	s_add_i32 s64, s53, 0x8000
	s_add_i32 s65, s53, 0xa000
	s_mov_b64 s[18:19], s[8:9]
	s_mov_b32 m0, s64
	s_add_u32 s8, s8, s28
	ds_read_b128 v[36:39], v244
	ds_read_b128 v[40:43], v244 offset:1024
	ds_read_b128 v[44:47], v244 offset:2048
	ds_read_b128 v[48:51], v244 offset:3072
	ds_read_b128 v[52:55], v244 offset:4096
	ds_read_b128 v[56:59], v244 offset:5120
	ds_read_b128 v[60:63], v244 offset:6144
	ds_read_b128 v[64:67], v244 offset:7168
	s_addc_u32 s9, s9, s29
	global_load_lds_dwordx4 v238, s[18:19]
	s_mov_b32 m0, s65
	s_add_i32 s66, s53, 0xc000
	global_load_lds_dwordx4 v2, s[18:19]
	s_mov_b32 m0, s66
	s_add_i32 s67, s53, 0xe000
	s_add_u32 s18, s16, 0x80
	global_load_lds_dwordx4 v238, s[8:9]
	s_mov_b32 m0, s67
	s_addc_u32 s19, s17, 0
	global_load_lds_dwordx4 v2, s[8:9]
	s_waitcnt vmcnt(8)
	s_waitcnt lgkmcnt(0)
	s_barrier
	s_setprio 1
	s_waitcnt lgkmcnt(0)
	v_mfma_f32_16x16x32_bf16 v[68:71], v[4:7], v[36:39], 0
	v_mfma_f32_16x16x32_bf16 v[72:75], v[12:15], v[36:39], 0
	v_mfma_f32_16x16x32_bf16 v[76:79], v[4:7], v[44:47], 0
	v_mfma_f32_16x16x32_bf16 v[80:83], v[12:15], v[44:47], 0
	v_mfma_f32_16x16x32_bf16 v[84:87], v[4:7], v[52:55], 0
	v_mfma_f32_16x16x32_bf16 v[88:91], v[12:15], v[52:55], 0
	v_mfma_f32_16x16x32_bf16 v[92:95], v[4:7], v[60:63], 0
	v_mfma_f32_16x16x32_bf16 v[96:99], v[12:15], v[60:63], 0
	v_mfma_f32_16x16x32_bf16 v[68:71], v[8:11], v[40:43], v[68:71]
	v_mfma_f32_16x16x32_bf16 v[72:75], v[16:19], v[40:43], v[72:75]
	v_mfma_f32_16x16x32_bf16 v[76:79], v[8:11], v[48:51], v[76:79]
	v_mfma_f32_16x16x32_bf16 v[80:83], v[16:19], v[48:51], v[80:83]
	v_mfma_f32_16x16x32_bf16 v[84:87], v[8:11], v[56:59], v[84:87]
	v_mfma_f32_16x16x32_bf16 v[88:91], v[16:19], v[56:59], v[88:91]
	v_mfma_f32_16x16x32_bf16 v[92:95], v[8:11], v[64:67], v[92:95]
	v_mfma_f32_16x16x32_bf16 v[96:99], v[16:19], v[64:67], v[96:99]
	s_setprio 0
	s_setprio 1
	v_mfma_f32_16x16x32_bf16 v[100:103], v[20:23], v[36:39], 0
	v_mfma_f32_16x16x32_bf16 v[36:39], v[28:31], v[36:39], 0
	v_mfma_f32_16x16x32_bf16 v[100:103], v[24:27], v[40:43], v[100:103]
	v_mfma_f32_16x16x32_bf16 v[40:43], v[32:35], v[40:43], v[36:39]
	v_mfma_f32_16x16x32_bf16 v[36:39], v[20:23], v[44:47], 0
	v_mfma_f32_16x16x32_bf16 v[104:107], v[24:27], v[48:51], v[36:39]
	v_mfma_f32_16x16x32_bf16 v[36:39], v[28:31], v[44:47], 0
	v_mfma_f32_16x16x32_bf16 v[48:51], v[32:35], v[48:51], v[36:39]
	v_mfma_f32_16x16x32_bf16 v[36:39], v[20:23], v[52:55], 0
	v_mfma_f32_16x16x32_bf16 v[108:111], v[24:27], v[56:59], v[36:39]
	v_mfma_f32_16x16x32_bf16 v[36:39], v[28:31], v[52:55], 0
	v_mfma_f32_16x16x32_bf16 v[56:59], v[32:35], v[56:59], v[36:39]
	v_mfma_f32_16x16x32_bf16 v[36:39], v[20:23], v[60:63], 0
	v_mfma_f32_16x16x32_bf16 v[112:115], v[24:27], v[64:67], v[36:39]
	v_mfma_f32_16x16x32_bf16 v[36:39], v[28:31], v[60:63], 0
	v_mfma_f32_16x16x32_bf16 v[64:67], v[32:35], v[64:67], v[36:39]
	s_setprio 0
	s_barrier
	s_add_i32 s68, s68, s52
	s_mov_b64 s[8:9], s[16:17]
	s_mov_b32 m0, s68
	s_add_i32 s69, s68, 0x2000
	s_nop 0
	ds_read_b128 v[36:39], v244 offset:16384
	ds_read_b128 v[44:47], v244 offset:17408
	ds_read_b128 v[52:55], v244 offset:18432
	ds_read_b128 v[60:63], v244 offset:19456
	ds_read_b128 v[116:119], v244 offset:20480
	ds_read_b128 v[120:123], v244 offset:21504
	ds_read_b128 v[124:127], v244 offset:22528
	ds_read_b128 v[128:131], v244 offset:23552
	s_nop 0
	global_load_lds_dwordx4 v246, s[8:9]
	s_mov_b32 m0, s69
	s_nop 0
	global_load_lds_dwordx4 v245, s[8:9]
	s_add_u32 s8, s16, s28
	s_addc_u32 s9, s17, s29
	s_add_i32 s72, s72, s52
	s_mov_b32 m0, s72
	s_add_i32 s73, s72, 0x2000
	s_nop 0
	global_load_lds_dwordx4 v246, s[8:9]
	s_mov_b32 m0, s73
	s_nop 0
	global_load_lds_dwordx4 v245, s[8:9]
	s_waitcnt vmcnt(6)
	s_waitcnt lgkmcnt(0)
	s_barrier
	s_setprio 1
	s_waitcnt lgkmcnt(0)
	v_mfma_f32_16x16x32_bf16 v[134:137], v[4:7], v[36:39], 0
	v_mfma_f32_16x16x32_bf16 v[144:147], v[4:7], v[52:55], 0
	v_mfma_f32_16x16x32_bf16 v[152:155], v[4:7], v[116:119], 0
	v_mfma_f32_16x16x32_bf16 v[4:7], v[4:7], v[124:127], 0
	v_mfma_f32_16x16x32_bf16 v[140:143], v[12:15], v[36:39], 0
	v_mfma_f32_16x16x32_bf16 v[148:151], v[12:15], v[52:55], 0
	v_mfma_f32_16x16x32_bf16 v[156:159], v[12:15], v[116:119], 0
	v_mfma_f32_16x16x32_bf16 v[160:163], v[8:11], v[128:131], v[4:7]
	v_mfma_f32_16x16x32_bf16 v[4:7], v[12:15], v[124:127], 0
	v_mfma_f32_16x16x32_bf16 v[136:139], v[8:11], v[44:47], v[134:137]
	v_mfma_f32_16x16x32_bf16 v[140:143], v[16:19], v[44:47], v[140:143]
	v_mfma_f32_16x16x32_bf16 v[144:147], v[8:11], v[60:63], v[144:147]
	v_mfma_f32_16x16x32_bf16 v[148:151], v[16:19], v[60:63], v[148:151]
	v_mfma_f32_16x16x32_bf16 v[152:155], v[8:11], v[120:123], v[152:155]
	v_mfma_f32_16x16x32_bf16 v[156:159], v[16:19], v[120:123], v[156:159]
	v_mfma_f32_16x16x32_bf16 v[164:167], v[16:19], v[128:131], v[4:7]
	s_setprio 0
	s_setprio 1
	v_mfma_f32_16x16x32_bf16 v[4:7], v[20:23], v[36:39], 0
	v_mfma_f32_16x16x32_bf16 v[168:171], v[24:27], v[44:47], v[4:7]
	v_mfma_f32_16x16x32_bf16 v[4:7], v[28:31], v[36:39], 0
	v_mfma_f32_16x16x32_bf16 v[172:175], v[32:35], v[44:47], v[4:7]
	v_mfma_f32_16x16x32_bf16 v[4:7], v[20:23], v[52:55], 0
	v_mfma_f32_16x16x32_bf16 v[176:179], v[24:27], v[60:63], v[4:7]
	v_mfma_f32_16x16x32_bf16 v[4:7], v[28:31], v[52:55], 0
	v_mfma_f32_16x16x32_bf16 v[180:183], v[32:35], v[60:63], v[4:7]
	v_mfma_f32_16x16x32_bf16 v[4:7], v[20:23], v[116:119], 0
	v_mfma_f32_16x16x32_bf16 v[184:187], v[24:27], v[120:123], v[4:7]
	v_mfma_f32_16x16x32_bf16 v[4:7], v[28:31], v[116:119], 0
	v_mfma_f32_16x16x32_bf16 v[120:123], v[32:35], v[120:123], v[4:7]
	v_mfma_f32_16x16x32_bf16 v[4:7], v[20:23], v[124:127], 0
	v_mfma_f32_16x16x32_bf16 v[188:191], v[24:27], v[128:131], v[4:7]
	v_mfma_f32_16x16x32_bf16 v[4:7], v[28:31], v[124:127], 0
	v_mfma_f32_16x16x32_bf16 v[128:131], v[32:35], v[128:131], v[4:7]
	s_setprio 0
	s_barrier
	s_add_i32 s16, 0, 0x18000
	s_add_i32 s76, 0, 0x1c000
	v_add_u32_e32 v134, s16, v243
	v_add_u32_e32 v135, s76, v243
	ds_read_b128 v[116:119], v134
	ds_read_b128 v[124:127], v134 offset:1024
	ds_read_b128 v[192:195], v134 offset:2048
	ds_read_b128 v[196:199], v134 offset:3072
	ds_read_b128 v[200:203], v135
	ds_read_b128 v[204:207], v135 offset:1024
	ds_read_b128 v[216:219], v135 offset:2048
	ds_read_b128 v[220:223], v135 offset:3072
	s_mov_b32 m0, s53
	s_mov_b64 s[8:9], s[42:43]
	ds_read_b128 v[44:47], v244 offset:32768
	ds_read_b128 v[52:55], v244 offset:33792
	ds_read_b128 v[60:63], v244 offset:34816
	ds_read_b128 v[224:227], v244 offset:35840
	ds_read_b128 v[228:231], v244 offset:36864
	ds_read_b128 v[232:235], v244 offset:37888
	ds_read_b128 v[248:251], v244 offset:38912
	ds_read_b128 v[208:211], v244 offset:39936
	s_nop 0
	global_load_lds_dwordx4 v238, s[8:9]
	s_mov_b32 m0, s57
	s_nop 0
	global_load_lds_dwordx4 v2, s[8:9]
	s_add_u32 s8, s42, s28
	s_addc_u32 s9, s43, s29
	s_mov_b32 m0, s58
	s_nop 0
	global_load_lds_dwordx4 v238, s[8:9]
	s_mov_b32 m0, s59
	s_nop 0
	global_load_lds_dwordx4 v2, s[8:9]
	s_waitcnt vmcnt(8)
	s_waitcnt lgkmcnt(0)
	s_barrier
	s_setprio 1
	s_waitcnt lgkmcnt(0)
	v_mfma_f32_16x16x32_bf16 v[4:7], v[116:119], v[44:47], v[68:71]
	v_mfma_f32_16x16x32_bf16 v[4:7], v[124:127], v[52:55], v[4:7]
	v_mfma_f32_16x16x32_bf16 v[8:11], v[192:195], v[44:47], v[72:75]
	v_mfma_f32_16x16x32_bf16 v[8:11], v[196:199], v[52:55], v[8:11]
	v_mfma_f32_16x16x32_bf16 v[12:15], v[116:119], v[60:63], v[76:79]
	v_mfma_f32_16x16x32_bf16 v[12:15], v[124:127], v[224:227], v[12:15]
	v_mfma_f32_16x16x32_bf16 v[16:19], v[192:195], v[60:63], v[80:83]
	v_mfma_f32_16x16x32_bf16 v[16:19], v[196:199], v[224:227], v[16:19]
	v_mfma_f32_16x16x32_bf16 v[20:23], v[116:119], v[228:231], v[84:87]
	v_mfma_f32_16x16x32_bf16 v[20:23], v[124:127], v[232:235], v[20:23]
	v_mfma_f32_16x16x32_bf16 v[24:27], v[192:195], v[228:231], v[88:91]
	v_mfma_f32_16x16x32_bf16 v[24:27], v[196:199], v[232:235], v[24:27]
	v_mfma_f32_16x16x32_bf16 v[28:31], v[116:119], v[248:251], v[92:95]
	v_mfma_f32_16x16x32_bf16 v[28:31], v[124:127], v[208:211], v[28:31]
	v_mfma_f32_16x16x32_bf16 v[32:35], v[192:195], v[248:251], v[96:99]
	v_mfma_f32_16x16x32_bf16 v[32:35], v[196:199], v[208:211], v[32:35]
	s_setprio 0
	s_setprio 1
	v_mfma_f32_16x16x32_bf16 v[36:39], v[200:203], v[44:47], v[100:103]
	v_mfma_f32_16x16x32_bf16 v[40:43], v[216:219], v[44:47], v[40:43]
	v_mfma_f32_16x16x32_bf16 v[36:39], v[204:207], v[52:55], v[36:39]
	v_mfma_f32_16x16x32_bf16 v[40:43], v[220:223], v[52:55], v[40:43]
	v_mfma_f32_16x16x32_bf16 v[44:47], v[200:203], v[60:63], v[104:107]
	v_mfma_f32_16x16x32_bf16 v[48:51], v[216:219], v[60:63], v[48:51]
	v_mfma_f32_16x16x32_bf16 v[52:55], v[200:203], v[228:231], v[108:111]
	v_mfma_f32_16x16x32_bf16 v[56:59], v[216:219], v[228:231], v[56:59]
	v_mfma_f32_16x16x32_bf16 v[60:63], v[200:203], v[248:251], v[112:115]
	v_mfma_f32_16x16x32_bf16 v[64:67], v[216:219], v[248:251], v[64:67]
	v_mfma_f32_16x16x32_bf16 v[44:47], v[204:207], v[224:227], v[44:47]
	v_mfma_f32_16x16x32_bf16 v[48:51], v[220:223], v[224:227], v[48:51]
	v_mfma_f32_16x16x32_bf16 v[52:55], v[204:207], v[232:235], v[52:55]
	v_mfma_f32_16x16x32_bf16 v[56:59], v[220:223], v[232:235], v[56:59]
	v_mfma_f32_16x16x32_bf16 v[60:63], v[204:207], v[208:211], v[60:63]
	v_mfma_f32_16x16x32_bf16 v[64:67], v[220:223], v[208:211], v[64:67]
	s_setprio 0
	s_barrier
	s_add_i32 s42, s16, s52
	s_mov_b64 s[8:9], s[18:19]
	s_mov_b32 m0, s42
	s_add_i32 s43, s42, 0x2000
	ds_read_b128 v[104:107], v244 offset:49152
	ds_read_b128 v[108:111], v244 offset:50176
	ds_read_b128 v[112:115], v244 offset:51200
	ds_read_b128 v[208:211], v244 offset:52224
	ds_read_b128 v[224:227], v244 offset:53248
	ds_read_b128 v[228:231], v244 offset:54272
	ds_read_b128 v[232:235], v244 offset:55296
	ds_read_b128 v[248:251], v244 offset:56320
	s_nop 0
	global_load_lds_dwordx4 v246, s[8:9]
	s_mov_b32 m0, s43
	s_nop 0
	global_load_lds_dwordx4 v245, s[8:9]
	s_add_u32 s8, s18, s28
	s_addc_u32 s9, s19, s29
	s_add_i32 s76, s76, s52
	s_mov_b32 m0, s76
	s_add_i32 s77, s76, 0x2000
	s_nop 0
	global_load_lds_dwordx4 v246, s[8:9]
	s_mov_b32 m0, s77
	s_nop 0
	global_load_lds_dwordx4 v245, s[8:9]
	s_waitcnt vmcnt(6)
	s_waitcnt lgkmcnt(0)
	s_barrier
	s_setprio 1
	s_waitcnt lgkmcnt(0)
	v_mfma_f32_16x16x32_bf16 v[68:71], v[116:119], v[104:107], v[136:139]
	v_mfma_f32_16x16x32_bf16 v[68:71], v[124:127], v[108:111], v[68:71]
	v_mfma_f32_16x16x32_bf16 v[72:75], v[192:195], v[104:107], v[140:143]
	v_mfma_f32_16x16x32_bf16 v[72:75], v[196:199], v[108:111], v[72:75]
	v_mfma_f32_16x16x32_bf16 v[76:79], v[116:119], v[112:115], v[144:147]
	v_mfma_f32_16x16x32_bf16 v[76:79], v[124:127], v[208:211], v[76:79]
	v_mfma_f32_16x16x32_bf16 v[80:83], v[192:195], v[112:115], v[148:151]
	v_mfma_f32_16x16x32_bf16 v[80:83], v[196:199], v[208:211], v[80:83]
	v_mfma_f32_16x16x32_bf16 v[84:87], v[116:119], v[224:227], v[152:155]
	v_mfma_f32_16x16x32_bf16 v[84:87], v[124:127], v[228:231], v[84:87]
	v_mfma_f32_16x16x32_bf16 v[88:91], v[192:195], v[224:227], v[156:159]
	v_mfma_f32_16x16x32_bf16 v[88:91], v[196:199], v[228:231], v[88:91]
	v_mfma_f32_16x16x32_bf16 v[92:95], v[116:119], v[232:235], v[160:163]
	v_mfma_f32_16x16x32_bf16 v[92:95], v[124:127], v[248:251], v[92:95]
	v_mfma_f32_16x16x32_bf16 v[96:99], v[192:195], v[232:235], v[164:167]
	v_mfma_f32_16x16x32_bf16 v[96:99], v[196:199], v[248:251], v[96:99]
	s_setprio 0
	s_setprio 1
	v_mfma_f32_16x16x32_bf16 v[100:103], v[200:203], v[104:107], v[168:171]
	v_mfma_f32_16x16x32_bf16 v[104:107], v[216:219], v[104:107], v[172:175]
	v_mfma_f32_16x16x32_bf16 v[100:103], v[204:207], v[108:111], v[100:103]
	v_mfma_f32_16x16x32_bf16 v[104:107], v[220:223], v[108:111], v[104:107]
	v_mfma_f32_16x16x32_bf16 v[108:111], v[200:203], v[112:115], v[176:179]
	v_mfma_f32_16x16x32_bf16 v[112:115], v[216:219], v[112:115], v[180:183]
	v_mfma_f32_16x16x32_bf16 v[116:119], v[200:203], v[224:227], v[184:187]
	v_mfma_f32_16x16x32_bf16 v[120:123], v[216:219], v[224:227], v[120:123]
	v_mfma_f32_16x16x32_bf16 v[124:127], v[200:203], v[232:235], v[188:191]
	v_mfma_f32_16x16x32_bf16 v[128:131], v[216:219], v[232:235], v[128:131]
	v_mfma_f32_16x16x32_bf16 v[108:111], v[204:207], v[208:211], v[108:111]
	v_mfma_f32_16x16x32_bf16 v[112:115], v[220:223], v[208:211], v[112:115]
	v_mfma_f32_16x16x32_bf16 v[116:119], v[204:207], v[228:231], v[116:119]
	v_mfma_f32_16x16x32_bf16 v[120:123], v[220:223], v[228:231], v[120:123]
	v_mfma_f32_16x16x32_bf16 v[124:127], v[204:207], v[248:251], v[124:127]
	v_mfma_f32_16x16x32_bf16 v[128:131], v[220:223], v[248:251], v[128:131]
	s_setprio 0
	s_barrier
	s_andn2_b64 vcc, exec, s[48:49]
	s_cbranch_vccnz .LBB0_1177
	s_add_u32 s78, s26, 0x200
	s_addc_u32 s79, s27, 0
	s_add_u32 s50, s50, 0x200
	s_addc_u32 s51, s51, 0
	s_mov_b32 s80, 4
.LBB0_1176:
	ds_read_b128 v[136:139], v132
	ds_read_b128 v[140:143], v132 offset:1024
	ds_read_b128 v[144:147], v132 offset:2048
	ds_read_b128 v[148:151], v132 offset:3072
	ds_read_b128 v[152:155], v133
	ds_read_b128 v[156:159], v133 offset:1024
	ds_read_b128 v[160:163], v133 offset:2048
	ds_read_b128 v[164:167], v133 offset:3072
	s_cmp_eq_u32 s6, s80
	s_cselect_b32 s17, s21, s79
	s_cselect_b32 s16, s20, s78
	s_cselect_b32 s27, s41, s51
	s_cselect_b32 s26, s40, s50
	s_add_u32 s8, s50, 0xffffff80
	s_addc_u32 s9, s51, -1
	s_mov_b32 m0, s64
	s_mov_b64 s[18:19], s[8:9]
	ds_read_b128 v[168:171], v244
	ds_read_b128 v[172:175], v244 offset:1024
	ds_read_b128 v[176:179], v244 offset:2048
	ds_read_b128 v[180:183], v244 offset:3072
	ds_read_b128 v[184:187], v244 offset:4096
	ds_read_b128 v[188:191], v244 offset:5120
	ds_read_b128 v[192:195], v244 offset:6144
	ds_read_b128 v[196:199], v244 offset:7168
	s_add_u32 s8, s8, s28
	global_load_lds_dwordx4 v238, s[18:19]
	s_mov_b32 m0, s65
	s_addc_u32 s9, s9, s29
	global_load_lds_dwordx4 v2, s[18:19]
	s_mov_b32 m0, s66
	s_add_u32 s18, s16, 0x80
	global_load_lds_dwordx4 v238, s[8:9]
	s_mov_b32 m0, s67
	s_addc_u32 s19, s17, 0
	global_load_lds_dwordx4 v2, s[8:9]
	s_waitcnt vmcnt(8)
	s_waitcnt lgkmcnt(0)
	s_barrier
	s_setprio 1
	s_waitcnt lgkmcnt(0)
	v_mfma_f32_16x16x32_bf16 v[4:7], v[136:139], v[168:171], v[4:7]
	v_mfma_f32_16x16x32_bf16 v[4:7], v[140:143], v[172:175], v[4:7]
	v_mfma_f32_16x16x32_bf16 v[8:11], v[144:147], v[168:171], v[8:11]
	v_mfma_f32_16x16x32_bf16 v[8:11], v[148:151], v[172:175], v[8:11]
	v_mfma_f32_16x16x32_bf16 v[12:15], v[136:139], v[176:179], v[12:15]
	v_mfma_f32_16x16x32_bf16 v[12:15], v[140:143], v[180:183], v[12:15]
	v_mfma_f32_16x16x32_bf16 v[16:19], v[144:147], v[176:179], v[16:19]
	v_mfma_f32_16x16x32_bf16 v[16:19], v[148:151], v[180:183], v[16:19]
	v_mfma_f32_16x16x32_bf16 v[20:23], v[136:139], v[184:187], v[20:23]
	v_mfma_f32_16x16x32_bf16 v[20:23], v[140:143], v[188:191], v[20:23]
	v_mfma_f32_16x16x32_bf16 v[24:27], v[144:147], v[184:187], v[24:27]
	v_mfma_f32_16x16x32_bf16 v[24:27], v[148:151], v[188:191], v[24:27]
	v_mfma_f32_16x16x32_bf16 v[28:31], v[136:139], v[192:195], v[28:31]
	v_mfma_f32_16x16x32_bf16 v[28:31], v[140:143], v[196:199], v[28:31]
	v_mfma_f32_16x16x32_bf16 v[32:35], v[144:147], v[192:195], v[32:35]
	v_mfma_f32_16x16x32_bf16 v[32:35], v[148:151], v[196:199], v[32:35]
	s_setprio 0
	s_setprio 1
	v_mfma_f32_16x16x32_bf16 v[36:39], v[152:155], v[168:171], v[36:39]
	v_mfma_f32_16x16x32_bf16 v[36:39], v[156:159], v[172:175], v[36:39]
	v_mfma_f32_16x16x32_bf16 v[40:43], v[160:163], v[168:171], v[40:43]
	v_mfma_f32_16x16x32_bf16 v[40:43], v[164:167], v[172:175], v[40:43]
	v_mfma_f32_16x16x32_bf16 v[44:47], v[152:155], v[176:179], v[44:47]
	v_mfma_f32_16x16x32_bf16 v[44:47], v[156:159], v[180:183], v[44:47]
	v_mfma_f32_16x16x32_bf16 v[48:51], v[160:163], v[176:179], v[48:51]
	v_mfma_f32_16x16x32_bf16 v[48:51], v[164:167], v[180:183], v[48:51]
	v_mfma_f32_16x16x32_bf16 v[52:55], v[152:155], v[184:187], v[52:55]
	v_mfma_f32_16x16x32_bf16 v[52:55], v[156:159], v[188:191], v[52:55]
	v_mfma_f32_16x16x32_bf16 v[56:59], v[160:163], v[184:187], v[56:59]
	v_mfma_f32_16x16x32_bf16 v[56:59], v[164:167], v[188:191], v[56:59]
	v_mfma_f32_16x16x32_bf16 v[60:63], v[152:155], v[192:195], v[60:63]
	v_mfma_f32_16x16x32_bf16 v[60:63], v[156:159], v[196:199], v[60:63]
	v_mfma_f32_16x16x32_bf16 v[64:67], v[160:163], v[192:195], v[64:67]
	v_mfma_f32_16x16x32_bf16 v[64:67], v[164:167], v[196:199], v[64:67]
	s_setprio 0
	s_barrier
	s_mov_b32 m0, s68
	s_mov_b64 s[8:9], s[16:17]
	ds_read_b128 v[168:171], v244 offset:16384
	ds_read_b128 v[172:175], v244 offset:17408
	ds_read_b128 v[176:179], v244 offset:18432
	ds_read_b128 v[180:183], v244 offset:19456
	ds_read_b128 v[184:187], v244 offset:20480
	ds_read_b128 v[188:191], v244 offset:21504
	ds_read_b128 v[192:195], v244 offset:22528
	ds_read_b128 v[196:199], v244 offset:23552
	s_nop 0
	global_load_lds_dwordx4 v246, s[8:9]
	s_mov_b32 m0, s69
	s_nop 0
	global_load_lds_dwordx4 v245, s[8:9]
	s_add_u32 s8, s16, s28
	s_addc_u32 s9, s17, s29
	s_mov_b32 m0, s72
	s_nop 0
	global_load_lds_dwordx4 v246, s[8:9]
	s_mov_b32 m0, s73
	s_nop 0
	global_load_lds_dwordx4 v245, s[8:9]
	s_waitcnt vmcnt(6)
	s_waitcnt lgkmcnt(0)
	s_barrier
	s_setprio 1
	s_waitcnt lgkmcnt(0)
	v_mfma_f32_16x16x32_bf16 v[68:71], v[136:139], v[168:171], v[68:71]
	v_mfma_f32_16x16x32_bf16 v[68:71], v[140:143], v[172:175], v[68:71]
	v_mfma_f32_16x16x32_bf16 v[72:75], v[144:147], v[168:171], v[72:75]
	v_mfma_f32_16x16x32_bf16 v[72:75], v[148:151], v[172:175], v[72:75]
	v_mfma_f32_16x16x32_bf16 v[76:79], v[136:139], v[176:179], v[76:79]
	v_mfma_f32_16x16x32_bf16 v[76:79], v[140:143], v[180:183], v[76:79]
	v_mfma_f32_16x16x32_bf16 v[80:83], v[144:147], v[176:179], v[80:83]
	v_mfma_f32_16x16x32_bf16 v[80:83], v[148:151], v[180:183], v[80:83]
	v_mfma_f32_16x16x32_bf16 v[84:87], v[136:139], v[184:187], v[84:87]
	v_mfma_f32_16x16x32_bf16 v[84:87], v[140:143], v[188:191], v[84:87]
	v_mfma_f32_16x16x32_bf16 v[88:91], v[144:147], v[184:187], v[88:91]
	v_mfma_f32_16x16x32_bf16 v[88:91], v[148:151], v[188:191], v[88:91]
	v_mfma_f32_16x16x32_bf16 v[92:95], v[136:139], v[192:195], v[92:95]
	v_mfma_f32_16x16x32_bf16 v[92:95], v[140:143], v[196:199], v[92:95]
	v_mfma_f32_16x16x32_bf16 v[96:99], v[144:147], v[192:195], v[96:99]
	v_mfma_f32_16x16x32_bf16 v[96:99], v[148:151], v[196:199], v[96:99]
	s_setprio 0
	s_setprio 1
	v_mfma_f32_16x16x32_bf16 v[100:103], v[152:155], v[168:171], v[100:103]
	v_mfma_f32_16x16x32_bf16 v[100:103], v[156:159], v[172:175], v[100:103]
	v_mfma_f32_16x16x32_bf16 v[104:107], v[160:163], v[168:171], v[104:107]
	v_mfma_f32_16x16x32_bf16 v[104:107], v[164:167], v[172:175], v[104:107]
	v_mfma_f32_16x16x32_bf16 v[108:111], v[152:155], v[176:179], v[108:111]
	v_mfma_f32_16x16x32_bf16 v[108:111], v[156:159], v[180:183], v[108:111]
	v_mfma_f32_16x16x32_bf16 v[112:115], v[160:163], v[176:179], v[112:115]
	v_mfma_f32_16x16x32_bf16 v[112:115], v[164:167], v[180:183], v[112:115]
	v_mfma_f32_16x16x32_bf16 v[116:119], v[152:155], v[184:187], v[116:119]
	v_mfma_f32_16x16x32_bf16 v[116:119], v[156:159], v[188:191], v[116:119]
	v_mfma_f32_16x16x32_bf16 v[120:123], v[160:163], v[184:187], v[120:123]
	v_mfma_f32_16x16x32_bf16 v[120:123], v[164:167], v[188:191], v[120:123]
	v_mfma_f32_16x16x32_bf16 v[124:127], v[152:155], v[192:195], v[124:127]
	v_mfma_f32_16x16x32_bf16 v[124:127], v[156:159], v[196:199], v[124:127]
	v_mfma_f32_16x16x32_bf16 v[128:131], v[160:163], v[192:195], v[128:131]
	v_mfma_f32_16x16x32_bf16 v[128:131], v[164:167], v[196:199], v[128:131]
	s_setprio 0
	s_barrier
	ds_read_b128 v[136:139], v134
	ds_read_b128 v[140:143], v134 offset:1024
	ds_read_b128 v[144:147], v134 offset:2048
	ds_read_b128 v[148:151], v134 offset:3072
	ds_read_b128 v[152:155], v135
	ds_read_b128 v[156:159], v135 offset:1024
	ds_read_b128 v[160:163], v135 offset:2048
	ds_read_b128 v[164:167], v135 offset:3072
	s_mov_b32 m0, s53
	s_mov_b64 s[8:9], s[26:27]
	ds_read_b128 v[168:171], v244 offset:32768
	ds_read_b128 v[172:175], v244 offset:33792
	ds_read_b128 v[176:179], v244 offset:34816
	ds_read_b128 v[180:183], v244 offset:35840
	ds_read_b128 v[184:187], v244 offset:36864
	ds_read_b128 v[188:191], v244 offset:37888
	ds_read_b128 v[192:195], v244 offset:38912
	ds_read_b128 v[196:199], v244 offset:39936
	s_nop 0
	global_load_lds_dwordx4 v238, s[8:9]
	s_mov_b32 m0, s57
	s_nop 0
	global_load_lds_dwordx4 v2, s[8:9]
	s_add_u32 s8, s26, s28
	s_addc_u32 s9, s27, s29
	s_mov_b32 m0, s58
	s_nop 0
	global_load_lds_dwordx4 v238, s[8:9]
	s_mov_b32 m0, s59
	s_nop 0
	global_load_lds_dwordx4 v2, s[8:9]
	s_waitcnt vmcnt(8)
	s_waitcnt lgkmcnt(0)
	s_barrier
	s_setprio 1
	s_waitcnt lgkmcnt(0)
	v_mfma_f32_16x16x32_bf16 v[4:7], v[136:139], v[168:171], v[4:7]
	v_mfma_f32_16x16x32_bf16 v[4:7], v[140:143], v[172:175], v[4:7]
	v_mfma_f32_16x16x32_bf16 v[8:11], v[144:147], v[168:171], v[8:11]
	v_mfma_f32_16x16x32_bf16 v[8:11], v[148:151], v[172:175], v[8:11]
	v_mfma_f32_16x16x32_bf16 v[12:15], v[136:139], v[176:179], v[12:15]
	v_mfma_f32_16x16x32_bf16 v[12:15], v[140:143], v[180:183], v[12:15]
	v_mfma_f32_16x16x32_bf16 v[16:19], v[144:147], v[176:179], v[16:19]
	v_mfma_f32_16x16x32_bf16 v[16:19], v[148:151], v[180:183], v[16:19]
	v_mfma_f32_16x16x32_bf16 v[20:23], v[136:139], v[184:187], v[20:23]
	v_mfma_f32_16x16x32_bf16 v[20:23], v[140:143], v[188:191], v[20:23]
	v_mfma_f32_16x16x32_bf16 v[24:27], v[144:147], v[184:187], v[24:27]
	v_mfma_f32_16x16x32_bf16 v[24:27], v[148:151], v[188:191], v[24:27]
	v_mfma_f32_16x16x32_bf16 v[28:31], v[136:139], v[192:195], v[28:31]
	v_mfma_f32_16x16x32_bf16 v[28:31], v[140:143], v[196:199], v[28:31]
	v_mfma_f32_16x16x32_bf16 v[32:35], v[144:147], v[192:195], v[32:35]
	v_mfma_f32_16x16x32_bf16 v[32:35], v[148:151], v[196:199], v[32:35]
	s_setprio 0
	s_setprio 1
	v_mfma_f32_16x16x32_bf16 v[36:39], v[152:155], v[168:171], v[36:39]
	v_mfma_f32_16x16x32_bf16 v[36:39], v[156:159], v[172:175], v[36:39]
	v_mfma_f32_16x16x32_bf16 v[40:43], v[160:163], v[168:171], v[40:43]
	v_mfma_f32_16x16x32_bf16 v[40:43], v[164:167], v[172:175], v[40:43]
	v_mfma_f32_16x16x32_bf16 v[44:47], v[152:155], v[176:179], v[44:47]
	v_mfma_f32_16x16x32_bf16 v[44:47], v[156:159], v[180:183], v[44:47]
	v_mfma_f32_16x16x32_bf16 v[48:51], v[160:163], v[176:179], v[48:51]
	v_mfma_f32_16x16x32_bf16 v[48:51], v[164:167], v[180:183], v[48:51]
	v_mfma_f32_16x16x32_bf16 v[52:55], v[152:155], v[184:187], v[52:55]
	v_mfma_f32_16x16x32_bf16 v[52:55], v[156:159], v[188:191], v[52:55]
	v_mfma_f32_16x16x32_bf16 v[56:59], v[160:163], v[184:187], v[56:59]
	v_mfma_f32_16x16x32_bf16 v[56:59], v[164:167], v[188:191], v[56:59]
	v_mfma_f32_16x16x32_bf16 v[60:63], v[152:155], v[192:195], v[60:63]
	v_mfma_f32_16x16x32_bf16 v[60:63], v[156:159], v[196:199], v[60:63]
	v_mfma_f32_16x16x32_bf16 v[64:67], v[160:163], v[192:195], v[64:67]
	v_mfma_f32_16x16x32_bf16 v[64:67], v[164:167], v[196:199], v[64:67]
	s_setprio 0
	s_barrier
	s_mov_b32 m0, s42
	s_mov_b64 s[8:9], s[18:19]
	ds_read_b128 v[168:171], v244 offset:49152
	ds_read_b128 v[172:175], v244 offset:50176
	ds_read_b128 v[176:179], v244 offset:51200
	ds_read_b128 v[180:183], v244 offset:52224
	ds_read_b128 v[184:187], v244 offset:53248
	ds_read_b128 v[188:191], v244 offset:54272
	ds_read_b128 v[192:195], v244 offset:55296
	ds_read_b128 v[196:199], v244 offset:56320
	s_nop 0
	global_load_lds_dwordx4 v246, s[8:9]
	s_mov_b32 m0, s43
	s_nop 0
	global_load_lds_dwordx4 v245, s[8:9]
	s_add_u32 s8, s18, s28
	s_addc_u32 s9, s19, s29
	s_mov_b32 m0, s76
	s_nop 0
	global_load_lds_dwordx4 v246, s[8:9]
	s_mov_b32 m0, s77
	s_nop 0
	global_load_lds_dwordx4 v245, s[8:9]
	s_waitcnt vmcnt(6)
	s_waitcnt lgkmcnt(0)
	s_barrier
	s_setprio 1
	s_waitcnt lgkmcnt(0)
	v_mfma_f32_16x16x32_bf16 v[68:71], v[136:139], v[168:171], v[68:71]
	v_mfma_f32_16x16x32_bf16 v[68:71], v[140:143], v[172:175], v[68:71]
	v_mfma_f32_16x16x32_bf16 v[72:75], v[144:147], v[168:171], v[72:75]
	v_mfma_f32_16x16x32_bf16 v[72:75], v[148:151], v[172:175], v[72:75]
	v_mfma_f32_16x16x32_bf16 v[76:79], v[136:139], v[176:179], v[76:79]
	v_mfma_f32_16x16x32_bf16 v[76:79], v[140:143], v[180:183], v[76:79]
	v_mfma_f32_16x16x32_bf16 v[80:83], v[144:147], v[176:179], v[80:83]
	v_mfma_f32_16x16x32_bf16 v[80:83], v[148:151], v[180:183], v[80:83]
	v_mfma_f32_16x16x32_bf16 v[84:87], v[136:139], v[184:187], v[84:87]
	v_mfma_f32_16x16x32_bf16 v[84:87], v[140:143], v[188:191], v[84:87]
	v_mfma_f32_16x16x32_bf16 v[88:91], v[144:147], v[184:187], v[88:91]
	v_mfma_f32_16x16x32_bf16 v[88:91], v[148:151], v[188:191], v[88:91]
	v_mfma_f32_16x16x32_bf16 v[92:95], v[136:139], v[192:195], v[92:95]
	v_mfma_f32_16x16x32_bf16 v[92:95], v[140:143], v[196:199], v[92:95]
	v_mfma_f32_16x16x32_bf16 v[96:99], v[144:147], v[192:195], v[96:99]
	v_mfma_f32_16x16x32_bf16 v[96:99], v[148:151], v[196:199], v[96:99]
	s_setprio 0
	s_setprio 1
	v_mfma_f32_16x16x32_bf16 v[100:103], v[152:155], v[168:171], v[100:103]
	v_mfma_f32_16x16x32_bf16 v[100:103], v[156:159], v[172:175], v[100:103]
	v_mfma_f32_16x16x32_bf16 v[104:107], v[160:163], v[168:171], v[104:107]
	v_mfma_f32_16x16x32_bf16 v[104:107], v[164:167], v[172:175], v[104:107]
	v_mfma_f32_16x16x32_bf16 v[108:111], v[152:155], v[176:179], v[108:111]
	v_mfma_f32_16x16x32_bf16 v[108:111], v[156:159], v[180:183], v[108:111]
	v_mfma_f32_16x16x32_bf16 v[112:115], v[160:163], v[176:179], v[112:115]
	v_mfma_f32_16x16x32_bf16 v[112:115], v[164:167], v[180:183], v[112:115]
	v_mfma_f32_16x16x32_bf16 v[116:119], v[152:155], v[184:187], v[116:119]
	v_mfma_f32_16x16x32_bf16 v[116:119], v[156:159], v[188:191], v[116:119]
	v_mfma_f32_16x16x32_bf16 v[120:123], v[160:163], v[184:187], v[120:123]
	v_mfma_f32_16x16x32_bf16 v[120:123], v[164:167], v[188:191], v[120:123]
	v_mfma_f32_16x16x32_bf16 v[124:127], v[152:155], v[192:195], v[124:127]
	v_mfma_f32_16x16x32_bf16 v[124:127], v[156:159], v[196:199], v[124:127]
	v_mfma_f32_16x16x32_bf16 v[128:131], v[160:163], v[192:195], v[128:131]
	v_mfma_f32_16x16x32_bf16 v[128:131], v[164:167], v[196:199], v[128:131]
	s_setprio 0
	s_barrier
	s_add_i32 s8, s80, 2
	s_add_u32 s78, s78, 0x100
	s_addc_u32 s79, s79, 0
	s_add_u32 s50, s50, 0x100
	s_addc_u32 s51, s51, 0
	s_cmp_ge_i32 s80, s6
	s_mov_b32 s80, s8
	s_cbranch_scc0 .LBB0_1176
